# sparse v3: K rows gathered with full-line loads (8 lanes per 128B row) and transposed to MFMA layout through a per-wave LDS stage; dilated block loads de-serialised; indexer LDS-staged
# speedup vs baseline: 1.4115x; 1.0783x over previous
; #define LAS __attribute__((address_space(3)))
; __device__ __forceinline__ void s8_issue_k(long (&kf)[16], const unsigned char* K8h, LAS const int* wsel, int j0, int n16, int slab) {
; #pragma unroll
;     for (int g = 0; g < 4; ++g) { const unsigned char* kp = K8h + (size_t)wsel[j0 + 16 * g + n16] * 1024 + 16 * slab;
;         const u32x4 lo = *(const u32x4*)kp, hi = *(const u32x4*)(kp + 64);
;         kf[g * 4 + 0] = (long)(((unsigned long long)lo.y << 32) | lo.x); kf[g * 4 + 1] = (long)(((unsigned long long)lo.w << 32) | lo.z);
;         kf[g * 4 + 2] = (long)(((unsigned long long)hi.y << 32) | hi.x); kf[g * 4 + 3] = (long)(((unsigned long long)hi.w << 32) | hi.z); }
; }
; __device__ __forceinline__ void sparse_unit7(const bf16_t* QKV, const unsigned char* K8, const unsigned char* V8, const int (&selv)[4], bf16_t* OB, LAS unsigned char* wl, int t, int h, int lane) {
;     LAS int* wsel = (LAS int*)wl; LAS unsigned* otw = (LAS unsigned*)(wl + 1024); LAS float* ptw = (LAS float*)(wl + 2048);
;     const int n16 = lane & 15, slab = lane >> 4, half = lane >> 5, l4 = (lane & 31) * 4;
;     const bf16_t* qrow = QKV + (size_t)t * QKVW + COL_BQ + h * 128 + 16 * slab;
;     long qa[4];
; #pragma unroll
;     for (int ks = 0; ks < 4; ++ks) { const u32x4 raw = *(const u32x4*)(qrow + 8 * (ks & 1) + 64 * (ks >> 1)); const unsigned w[4] = {raw.x, raw.y, raw.z, raw.w}; float x[8];
; #pragma unroll
;         for (int i = 0; i < 4; ++i) { x[2 * i] = bf2f(w[i] & 0xffffu); x[2 * i + 1] = __builtin_bit_cast(float, w[i] & 0xffff0000u); }
;         const u32x2 f = to_fp8x8(x); qa[ks] = (long)(((unsigned long long)f.y << 32) | f.x); }
;     const unsigned char* K8h = K8 + h * 128; const unsigned char* V8h = V8 + h * 128;
;     const int n = min(256, t + 1), ns = (n + 63) >> 6;
; #pragma unroll
;     for (int s = 0; s < 4; ++s) { const int j = 64 * s + lane; const int id = (j < n) ? selv[s] : 0; wsel[j] = id; otw[j] = (unsigned)id * 1024u; }
;     asm volatile("" ::: "memory");
;     long kf[16]; unsigned va[8], vb[8];
;     s8_issue_k(kf, K8h, wsel, 0, n16, slab);
.LBB0_160:
.LBB0_161:
	v_readlane_b32 s0, v251, 0
	v_readlane_b32 s1, v250, 18
	s_nop 3
	s_and_b32 s4, s0, 7
	s_and_b32 s5, s0, -8
	s_add_i32 s34, s5, s1
	s_add_i32 s48, s94, 7
	s_and_b32 s48, s48, -8
	s_add_u32 s38, s90, 0x28600000
	s_addc_u32 s39, s91, 0
	s_lshl_b32 s5, s4, 8
	s_add_u32 s5, s5, 0x12302400
	s_add_u32 s40, s90, s5
	s_addc_u32 s41, s91, 0
	s_lshl_b32 s5, s4, 21
	s_add_u32 s0, s5, 0x3cf00000
	s_add_u32 s42, s90, s0
	s_addc_u32 s43, s91, 0
	s_add_u32 s0, s5, 0x3df00000
	s_add_u32 s44, s90, s0
	s_addc_u32 s45, s91, 0
	s_lshl_b32 s5, s4, 8
	s_add_u32 s0, s5, 0x29e00000
	s_add_u32 s46, s90, s0
	s_addc_u32 s47, s91, 0
	s_lshl_b32 s0, s1, 13
	v_and_b32_e32 v218, 15, v182
	v_lshrrev_b32_e32 v219, 4, v182
	v_and_b32_e32 v246, 7, v182
	v_lshrrev_b32_e32 v247, 3, v182
	v_lshlrev_b32_e32 v200, 6, v247
	v_lshlrev_b32_e32 v201, 5, v219
	v_xor_b32_e32 v248, v246, v247
	v_lshlrev_b32_e32 v202, 4, v248
	v_lshlrev_b32_e32 v203, 4, v246
	v_lshl_add_u32 v224, v182, 4, s0
	v_and_b32_e32 v248, 7, v218
	v_lshrrev_b32_e32 v249, 3, v218
	v_lshlrev_b32_e32 v227, 4, v249
	v_lshlrev_b32_e32 v225, 10, v249
	v_lshl_add_u32 v225, v248, 7, v225
	v_add_u32_e32 v225, s0, v225
	v_xor_b32_e32 v217, v219, v248
	v_xor_b32_e32 v226, 4, v217
	v_lshl_add_u32 v226, v226, 4, v225
	v_lshl_add_u32 v225, v217, 4, v225
	v_lshlrev_b32_e32 v217, 5, v248
	v_lshl_add_u32 v217, v219, 3, v217
	v_sub_u32_e32 v216, v217, v161
	v_lshlrev_b32_e32 v216, 1, v216
	v_add_u32_e32 v217, v217, v249
	v_lshlrev_b32_e32 v248, 4, v218
	v_lshl_add_u32 v248, v219, 2, v248
	v_lshrrev_b32_e32 v249, 1, v218
	v_lshl_add_u32 v248, v249, 2, v248
	v_lshlrev_b32_e32 v213, 2, v248
	s_add_i32 s1, s0, 0x1000
	v_add_u32_e32 v213, s1, v213
	v_mul_u32_u24_e32 v214, 0x90, v247
	v_add_u32_e32 v214, s1, v214
	v_lshlrev_b32_e32 v215, 5, v246
	v_lshl_add_u32 v215, v219, 3, v215
	v_cmp_eq_u32_e64 s[8:9], 0, v219
	v_cmp_eq_u32_e64 s[10:11], 1, v219
	v_cmp_eq_u32_e64 s[16:17], 2, v219
	v_cmp_eq_u32_e64 s[22:23], 3, v219
	s_lshl_b32 s0, s34, 9
	s_add_u32 s0, s38, s0
	s_addc_u32 s1, s39, 0
	s_mul_i32 s4, s34, 0x3c00
	s_add_u32 s4, s40, s4
	s_addc_u32 s5, s41, 0
	global_load_dwordx4 v[96:99], v200, s[0:1]
	global_load_dwordx4 v[100:103], v200, s[0:1] offset:16
	global_load_dwordx4 v[104:107], v200, s[0:1] offset:32
	global_load_dwordx4 v[108:111], v200, s[0:1] offset:48
	global_load_dwordx4 v[220:223], v216, s[0:1]
	global_load_dwordx4 v[230:233], v201, s[4:5]
	global_load_dwordx4 v[234:237], v201, s[4:5] offset:16
	global_load_dwordx4 v[238:241], v201, s[4:5] offset:128
	global_load_dwordx4 v[242:245], v201, s[4:5] offset:144
.Lsp_unit:
	s_waitcnt vmcnt(0)
	s_add_i32 s98, s34, 1
	s_min_i32 s98, s98, 0x100
	v_and_b32_e32 v218, 0x3fff, v96
	v_lshl_add_u32 v218, v218, 7, v202
	global_load_dwordx4 v[0:3], v218, s[42:43]
	v_bfe_u32 v218, v96, 16, 14
	v_lshl_add_u32 v218, v218, 7, v202
	global_load_dwordx4 v[4:7], v218, s[42:43]
	v_and_b32_e32 v218, 0x3fff, v97
	v_lshl_add_u32 v218, v218, 7, v202
	global_load_dwordx4 v[8:11], v218, s[42:43]
	v_bfe_u32 v218, v97, 16, 14
	v_lshl_add_u32 v218, v218, 7, v202
	global_load_dwordx4 v[12:15], v218, s[42:43]
	v_and_b32_e32 v218, 0x3fff, v98
	v_lshl_add_u32 v218, v218, 7, v202
	global_load_dwordx4 v[16:19], v218, s[42:43]
	v_bfe_u32 v218, v98, 16, 14
	v_lshl_add_u32 v218, v218, 7, v202
	global_load_dwordx4 v[20:23], v218, s[42:43]
	v_and_b32_e32 v218, 0x3fff, v99
	v_lshl_add_u32 v218, v218, 7, v202
	global_load_dwordx4 v[24:27], v218, s[42:43]
	v_bfe_u32 v218, v99, 16, 14
	v_lshl_add_u32 v218, v218, 7, v202
	global_load_dwordx4 v[28:31], v218, s[42:43]
	v_and_b32_e32 v218, 0x3fff, v100
	v_lshl_add_u32 v218, v218, 7, v202
	global_load_dwordx4 v[32:35], v218, s[42:43]
	v_bfe_u32 v218, v100, 16, 14
	v_lshl_add_u32 v218, v218, 7, v202
	global_load_dwordx4 v[36:39], v218, s[42:43]
	v_and_b32_e32 v218, 0x3fff, v101
	v_lshl_add_u32 v218, v218, 7, v202
	global_load_dwordx4 v[40:43], v218, s[42:43]
	v_bfe_u32 v218, v101, 16, 14
	v_lshl_add_u32 v218, v218, 7, v202
	global_load_dwordx4 v[44:47], v218, s[42:43]
	v_and_b32_e32 v218, 0x3fff, v102
	v_lshl_add_u32 v218, v218, 7, v202
	global_load_dwordx4 v[48:51], v218, s[42:43]
	v_bfe_u32 v218, v102, 16, 14
	v_lshl_add_u32 v218, v218, 7, v202
	global_load_dwordx4 v[52:55], v218, s[42:43]
	v_and_b32_e32 v218, 0x3fff, v103
	v_lshl_add_u32 v218, v218, 7, v202
	global_load_dwordx4 v[56:59], v218, s[42:43]
	v_bfe_u32 v218, v103, 16, 14
	v_lshl_add_u32 v218, v218, 7, v202
	global_load_dwordx4 v[60:63], v218, s[42:43]
	v_and_b32_e32 v218, 0x3fff, v104
	v_lshl_add_u32 v218, v218, 7, v202
	global_load_dwordx4 v[64:67], v218, s[42:43]
	v_bfe_u32 v218, v104, 16, 14
	v_lshl_add_u32 v218, v218, 7, v202
	global_load_dwordx4 v[68:71], v218, s[42:43]
	v_and_b32_e32 v218, 0x3fff, v105
	v_lshl_add_u32 v218, v218, 7, v202
	global_load_dwordx4 v[72:75], v218, s[42:43]
	v_bfe_u32 v218, v105, 16, 14
	v_lshl_add_u32 v218, v218, 7, v202
	global_load_dwordx4 v[76:79], v218, s[42:43]
	v_and_b32_e32 v218, 0x3fff, v106
	v_lshl_add_u32 v218, v218, 7, v202
	global_load_dwordx4 v[80:83], v218, s[42:43]
	v_bfe_u32 v218, v106, 16, 14
	v_lshl_add_u32 v218, v218, 7, v202
	global_load_dwordx4 v[84:87], v218, s[42:43]
	v_and_b32_e32 v218, 0x3fff, v107
	v_lshl_add_u32 v218, v218, 7, v202
	global_load_dwordx4 v[88:91], v218, s[42:43]
	v_bfe_u32 v218, v107, 16, 14
	v_lshl_add_u32 v218, v218, 7, v202
	global_load_dwordx4 v[92:95], v218, s[42:43]
	v_and_b32_e32 v112, 0x3fff, v108
	v_lshl_add_u32 v112, v112, 7, v202
	v_bfe_u32 v113, v108, 16, 14
	v_lshl_add_u32 v113, v113, 7, v202
	v_and_b32_e32 v114, 0x3fff, v109
	v_lshl_add_u32 v114, v114, 7, v202
	v_bfe_u32 v115, v109, 16, 14
; #define LAS __attribute__((address_space(3)))
; __device__ __forceinline__ void sparse_unit7(const bf16_t* QKV, const unsigned char* K8, const unsigned char* V8, const int (&selv)[4], bf16_t* OB, LAS unsigned char* wl, int t, int h, int lane) {
;     ...
;     for (int ks = 0; ks < 4; ++ks) { const u32x4 raw = *(const u32x4*)(qrow + 8 * (ks & 1) + 64 * (ks >> 1)); const unsigned w[4] = {raw.x, raw.y, raw.z, raw.w}; float x[8];
; #pragma unroll
;         for (int i = 0; i < 4; ++i) { x[2 * i] = bf2f(w[i] & 0xffffu); x[2 * i + 1] = __builtin_bit_cast(float, w[i] & 0xffff0000u); }
;         const u32x2 f = to_fp8x8(x); qa[ks] = (long)(((unsigned long long)f.y << 32) | f.x); }
;     const unsigned char* K8h = K8 + h * 128; const unsigned char* V8h = V8 + h * 128;
;     const int n = min(256, t + 1), ns = (n + 63) >> 6;
; #pragma unroll
;     for (int s = 0; s < 4; ++s) { const int j = 64 * s + lane; const int id = (j < n) ? selv[s] : 0; wsel[j] = id; otw[j] = (unsigned)id * 1024u; }
;     asm volatile("" ::: "memory");
;     long kf[16]; unsigned va[8], vb[8];
;     s8_issue_k(kf, K8h, wsel, 0, n16, slab);
;     s9_issue_v<0>(va, V8h, otw, half, l4);
;     float m = -INFINITY, l = 0.f; f32x2_t oa = {0.f, 0.f}, ob = {0.f, 0.f};
; #pragma unroll
;     for (int s = 0; s < 4; ++s) {
;         if (s < ns) {
;             const bool valid = (64 * s + lane) < n;
;             LAS const unsigned* ot = otw + 64 * s; LAS float* pt = ptw + 64 * s;
;             s9_issue_v<1>(vb, V8h, ot, half, l4);
;             f32x4 acc[4];
; #pragma unroll
;             for (int g = 0; g < 4; ++g) { acc[g] = (f32x4){0.f, 0.f, 0.f, 0.f};
; #pragma unroll
;                 for (int ks = 0; ks < 4; ++ks) acc[g] = __builtin_amdgcn_mfma_f32_16x16x32_fp8_fp8(qa[ks], kf[g * 4 + ks], acc[g], 0, 0, 0); }
;             float sc = (slab == 0) ? acc[0][0] : (slab == 1) ? acc[1][0] : (slab == 2) ? acc[2][0] : acc[3][0];
; __global__ void __launch_bounds__(NTHREADS, 2) mega(Args a) {
;     ...
;                         const int tn = min(t + nqg, SEQ - 1);
; #pragma unroll
;                         for (int s = 0; s < 4; ++s) seln[s] = (int)SEL[(size_t)tn * 256 + 64 * s + lane];
;                         sparse_unit7(QKV, K8, V8, selc, OB, lds + wave * 4096, t, h, lane); } }
	v_lshl_add_u32 v115, v115, 7, v202
	v_and_b32_e32 v116, 0x3fff, v110
	v_lshl_add_u32 v116, v116, 7, v202
	v_bfe_u32 v117, v110, 16, 14
	v_lshl_add_u32 v117, v117, 7, v202
	v_and_b32_e32 v118, 0x3fff, v111
	v_lshl_add_u32 v118, v118, 7, v202
	v_bfe_u32 v119, v111, 16, 14
	v_lshl_add_u32 v119, v119, 7, v202
	v_lshrrev_b32_e32 v136, v227, v220
	v_lshrrev_b32_e32 v137, v227, v221
	v_lshrrev_b32_e32 v138, v227, v222
	v_lshrrev_b32_e32 v139, v227, v223
	v_and_b32_e32 v136, 0x3fff, v136
	v_and_b32_e32 v137, 0x3fff, v137
	v_and_b32_e32 v138, 0x3fff, v138
	v_and_b32_e32 v139, 0x3fff, v139
	v_lshlrev_b32_e32 v136, 7, v136
	v_lshlrev_b32_e32 v137, 7, v137
	v_lshlrev_b32_e32 v138, 7, v138
	v_lshlrev_b32_e32 v139, 7, v139
	v_lshlrev_b32_e32 v218, 16, v230
	v_and_b32_e32 v219, 0xffff0000, v230
	v_lshlrev_b32_e32 v246, 16, v231
	v_and_b32_e32 v247, 0xffff0000, v231
	v_cvt_pk_fp8_f32 v128, v218, v219
	s_nop 0
	v_cvt_pk_fp8_f32 v128, v246, v247 op_sel:[0,0,1]
	v_lshlrev_b32_e32 v218, 16, v232
	v_and_b32_e32 v219, 0xffff0000, v232
	v_lshlrev_b32_e32 v246, 16, v233
	v_and_b32_e32 v247, 0xffff0000, v233
	v_cvt_pk_fp8_f32 v129, v218, v219
	s_nop 0
	v_cvt_pk_fp8_f32 v129, v246, v247 op_sel:[0,0,1]
	v_lshlrev_b32_e32 v218, 16, v234
	v_and_b32_e32 v219, 0xffff0000, v234
	v_lshlrev_b32_e32 v246, 16, v235
	v_and_b32_e32 v247, 0xffff0000, v235
	v_cvt_pk_fp8_f32 v130, v218, v219
	s_nop 0
	v_cvt_pk_fp8_f32 v130, v246, v247 op_sel:[0,0,1]
	v_lshlrev_b32_e32 v218, 16, v236
	v_and_b32_e32 v219, 0xffff0000, v236
	v_lshlrev_b32_e32 v246, 16, v237
	v_and_b32_e32 v247, 0xffff0000, v237
	v_cvt_pk_fp8_f32 v131, v218, v219
	s_nop 0
	v_cvt_pk_fp8_f32 v131, v246, v247 op_sel:[0,0,1]
	v_lshlrev_b32_e32 v218, 16, v238
	v_and_b32_e32 v219, 0xffff0000, v238
	v_lshlrev_b32_e32 v246, 16, v239
	v_and_b32_e32 v247, 0xffff0000, v239
	v_cvt_pk_fp8_f32 v132, v218, v219
	s_nop 0
	v_cvt_pk_fp8_f32 v132, v246, v247 op_sel:[0,0,1]
	v_lshlrev_b32_e32 v218, 16, v240
	v_and_b32_e32 v219, 0xffff0000, v240
	v_lshlrev_b32_e32 v246, 16, v241
	v_and_b32_e32 v247, 0xffff0000, v241
	v_cvt_pk_fp8_f32 v133, v218, v219
	s_nop 0
	v_cvt_pk_fp8_f32 v133, v246, v247 op_sel:[0,0,1]
	v_lshlrev_b32_e32 v218, 16, v242
	v_and_b32_e32 v219, 0xffff0000, v242
	v_lshlrev_b32_e32 v246, 16, v243
	v_and_b32_e32 v247, 0xffff0000, v243
	v_cvt_pk_fp8_f32 v134, v218, v219
	s_nop 0
	v_cvt_pk_fp8_f32 v134, v246, v247 op_sel:[0,0,1]
	v_lshlrev_b32_e32 v218, 16, v244
	v_and_b32_e32 v219, 0xffff0000, v244
	v_lshlrev_b32_e32 v246, 16, v245
	v_and_b32_e32 v247, 0xffff0000, v245
	v_cvt_pk_fp8_f32 v135, v218, v219
	s_nop 0
	v_cvt_pk_fp8_f32 v135, v246, v247 op_sel:[0,0,1]
	s_add_i32 s49, s34, s48
	s_min_i32 s49, s49, 0x3fff
	s_lshl_b32 s0, s49, 9
	s_add_u32 s0, s38, s0
	s_addc_u32 s1, s39, 0
	s_mul_i32 s4, s49, 0x3c00
	s_add_u32 s4, s40, s4
	s_addc_u32 s5, s41, 0
	global_load_dwordx4 v[96:99], v200, s[0:1]
	global_load_dwordx4 v[100:103], v200, s[0:1] offset:16
	global_load_dwordx4 v[104:107], v200, s[0:1] offset:32
	global_load_dwordx4 v[108:111], v200, s[0:1] offset:48
	global_load_dwordx4 v[220:223], v216, s[0:1]
	global_load_dwordx4 v[230:233], v201, s[4:5]
	global_load_dwordx4 v[234:237], v201, s[4:5] offset:16
	global_load_dwordx4 v[238:241], v201, s[4:5] offset:128
	global_load_dwordx4 v[242:245], v201, s[4:5] offset:144
	s_waitcnt vmcnt(31)
	ds_write_b128 v224, v[0:3] offset:0
	ds_write_b128 v224, v[4:7] offset:1024
	ds_read_b128 v[144:147], v225 offset:0
	ds_read_b128 v[148:151], v226 offset:0
	global_load_dwordx4 v[0:3], v112, s[42:43]
	global_load_dwordx4 v[4:7], v113, s[42:43]
	s_waitcnt vmcnt(31)
	ds_write_b128 v224, v[8:11] offset:2048
	ds_write_b128 v224, v[12:15] offset:3072
	ds_read_b128 v[152:155], v225 offset:2048
	ds_read_b128 v[156:159], v226 offset:2048
	global_load_dwordx4 v[8:11], v114, s[42:43]
	global_load_dwordx4 v[12:15], v115, s[42:43]
	s_waitcnt lgkmcnt(4)
	v_mfma_f32_16x16x32_fp8_fp8 v[184:187], v[128:129], v[144:145], 0
	v_mfma_f32_16x16x32_fp8_fp8 v[184:187], v[130:131], v[146:147], v[184:187]
	v_mfma_f32_16x16x32_fp8_fp8 v[184:187], v[132:133], v[148:149], v[184:187]
	v_mfma_f32_16x16x32_fp8_fp8 v[184:187], v[134:135], v[150:151], v[184:187]
	s_waitcnt vmcnt(31)
	ds_write_b128 v224, v[16:19] offset:0
	ds_write_b128 v224, v[20:23] offset:1024
	ds_read_b128 v[144:147], v225 offset:0
	ds_read_b128 v[148:151], v226 offset:0
	global_load_dwordx4 v[16:19], v116, s[42:43]
	global_load_dwordx4 v[20:23], v117, s[42:43]
	s_waitcnt lgkmcnt(4)
	v_mfma_f32_16x16x32_fp8_fp8 v[188:191], v[128:129], v[152:153], 0
	v_mfma_f32_16x16x32_fp8_fp8 v[188:191], v[130:131], v[154:155], v[188:191]
	v_mfma_f32_16x16x32_fp8_fp8 v[188:191], v[132:133], v[156:157], v[188:191]
	v_mfma_f32_16x16x32_fp8_fp8 v[188:191], v[134:135], v[158:159], v[188:191]
	s_waitcnt vmcnt(31)
	ds_write_b128 v224, v[24:27] offset:2048
	ds_write_b128 v224, v[28:31] offset:3072
	ds_read_b128 v[152:155], v225 offset:2048
	ds_read_b128 v[156:159], v226 offset:2048
	global_load_dwordx4 v[24:27], v118, s[42:43]
	global_load_dwordx4 v[28:31], v119, s[42:43]
	s_waitcnt lgkmcnt(4)
	v_mfma_f32_16x16x32_fp8_fp8 v[192:195], v[128:129], v[144:145], 0
	v_mfma_f32_16x16x32_fp8_fp8 v[192:195], v[130:131], v[146:147], v[192:195]
	v_mfma_f32_16x16x32_fp8_fp8 v[192:195], v[132:133], v[148:149], v[192:195]
	v_mfma_f32_16x16x32_fp8_fp8 v[192:195], v[134:135], v[150:151], v[192:195]
	v_cndmask_b32_e64 v140, v140, v184, s[8:9]
	s_waitcnt vmcnt(31)
	ds_write_b128 v224, v[32:35] offset:0
	ds_write_b128 v224, v[36:39] offset:1024
	ds_read_b128 v[144:147], v225 offset:0
	ds_read_b128 v[148:151], v226 offset:0
	s_waitcnt lgkmcnt(4)
; #define LAS __attribute__((address_space(3)))
; __device__ __forceinline__ void s8_issue_k(long (&kf)[16], const unsigned char* K8h, LAS const int* wsel, int j0, int n16, int slab) {
; #pragma unroll
;     for (int g = 0; g < 4; ++g) { const unsigned char* kp = K8h + (size_t)wsel[j0 + 16 * g + n16] * 1024 + 16 * slab;
;         const u32x4 lo = *(const u32x4*)kp, hi = *(const u32x4*)(kp + 64);
;         kf[g * 4 + 0] = (long)(((unsigned long long)lo.y << 32) | lo.x); kf[g * 4 + 1] = (long)(((unsigned long long)lo.w << 32) | lo.z);
;         kf[g * 4 + 2] = (long)(((unsigned long long)hi.y << 32) | hi.x); kf[g * 4 + 3] = (long)(((unsigned long long)hi.w << 32) | hi.z); }
; }
; __device__ __forceinline__ void sparse_unit7(const bf16_t* QKV, const unsigned char* K8, const unsigned char* V8, const int (&selv)[4], bf16_t* OB, LAS unsigned char* wl, int t, int h, int lane) {
;     ...
;             f32x4 acc[4];
; #pragma unroll
;             for (int g = 0; g < 4; ++g) { acc[g] = (f32x4){0.f, 0.f, 0.f, 0.f};
; #pragma unroll
;                 for (int ks = 0; ks < 4; ++ks) acc[g] = __builtin_amdgcn_mfma_f32_16x16x32_fp8_fp8(qa[ks], kf[g * 4 + ks], acc[g], 0, 0, 0); }
;             float sc = (slab == 0) ? acc[0][0] : (slab == 1) ? acc[1][0] : (slab == 2) ? acc[2][0] : acc[3][0];
	v_mfma_f32_16x16x32_fp8_fp8 v[196:199], v[128:129], v[152:153], 0
	v_mfma_f32_16x16x32_fp8_fp8 v[196:199], v[130:131], v[154:155], v[196:199]
	v_mfma_f32_16x16x32_fp8_fp8 v[196:199], v[132:133], v[156:157], v[196:199]
	v_mfma_f32_16x16x32_fp8_fp8 v[196:199], v[134:135], v[158:159], v[196:199]
	v_cndmask_b32_e64 v141, v141, v188, s[8:9]
	s_waitcnt vmcnt(29)
	ds_write_b128 v224, v[40:43] offset:2048
	ds_write_b128 v224, v[44:47] offset:3072
	ds_read_b128 v[152:155], v225 offset:2048
	ds_read_b128 v[156:159], v226 offset:2048
	s_waitcnt lgkmcnt(4)
	v_mfma_f32_16x16x32_fp8_fp8 v[184:187], v[128:129], v[144:145], 0
	v_mfma_f32_16x16x32_fp8_fp8 v[184:187], v[130:131], v[146:147], v[184:187]
	v_mfma_f32_16x16x32_fp8_fp8 v[184:187], v[132:133], v[148:149], v[184:187]
	v_mfma_f32_16x16x32_fp8_fp8 v[184:187], v[134:135], v[150:151], v[184:187]
	v_cndmask_b32_e64 v142, v142, v192, s[8:9]
	s_waitcnt vmcnt(27)
	ds_write_b128 v224, v[48:51] offset:0
	ds_write_b128 v224, v[52:55] offset:1024
	ds_read_b128 v[144:147], v225 offset:0
	ds_read_b128 v[148:151], v226 offset:0
	s_waitcnt lgkmcnt(4)
	v_mfma_f32_16x16x32_fp8_fp8 v[188:191], v[128:129], v[152:153], 0
	v_mfma_f32_16x16x32_fp8_fp8 v[188:191], v[130:131], v[154:155], v[188:191]
	v_mfma_f32_16x16x32_fp8_fp8 v[188:191], v[132:133], v[156:157], v[188:191]
	v_mfma_f32_16x16x32_fp8_fp8 v[188:191], v[134:135], v[158:159], v[188:191]
	v_cndmask_b32_e64 v143, v143, v196, s[8:9]
	s_waitcnt vmcnt(25)
	ds_write_b128 v224, v[56:59] offset:2048
	ds_write_b128 v224, v[60:63] offset:3072
	ds_read_b128 v[152:155], v225 offset:2048
	ds_read_b128 v[156:159], v226 offset:2048
	s_waitcnt lgkmcnt(4)
	v_mfma_f32_16x16x32_fp8_fp8 v[192:195], v[128:129], v[144:145], 0
	v_mfma_f32_16x16x32_fp8_fp8 v[192:195], v[130:131], v[146:147], v[192:195]
	v_mfma_f32_16x16x32_fp8_fp8 v[192:195], v[132:133], v[148:149], v[192:195]
	v_mfma_f32_16x16x32_fp8_fp8 v[192:195], v[134:135], v[150:151], v[192:195]
	v_cndmask_b32_e64 v140, v140, v184, s[10:11]
	s_waitcnt vmcnt(23)
	ds_write_b128 v224, v[64:67] offset:0
	ds_write_b128 v224, v[68:71] offset:1024
	ds_read_b128 v[144:147], v225 offset:0
	ds_read_b128 v[148:151], v226 offset:0
	s_waitcnt lgkmcnt(4)
	v_mfma_f32_16x16x32_fp8_fp8 v[196:199], v[128:129], v[152:153], 0
	v_mfma_f32_16x16x32_fp8_fp8 v[196:199], v[130:131], v[154:155], v[196:199]
	v_mfma_f32_16x16x32_fp8_fp8 v[196:199], v[132:133], v[156:157], v[196:199]
	v_mfma_f32_16x16x32_fp8_fp8 v[196:199], v[134:135], v[158:159], v[196:199]
	v_cndmask_b32_e64 v141, v141, v188, s[10:11]
	s_waitcnt vmcnt(21)
	ds_write_b128 v224, v[72:75] offset:2048
	ds_write_b128 v224, v[76:79] offset:3072
	ds_read_b128 v[152:155], v225 offset:2048
	ds_read_b128 v[156:159], v226 offset:2048
	s_waitcnt lgkmcnt(4)
	v_mfma_f32_16x16x32_fp8_fp8 v[184:187], v[128:129], v[144:145], 0
	v_mfma_f32_16x16x32_fp8_fp8 v[184:187], v[130:131], v[146:147], v[184:187]
	v_mfma_f32_16x16x32_fp8_fp8 v[184:187], v[132:133], v[148:149], v[184:187]
	v_mfma_f32_16x16x32_fp8_fp8 v[184:187], v[134:135], v[150:151], v[184:187]
	v_cndmask_b32_e64 v142, v142, v192, s[10:11]
	s_waitcnt vmcnt(19)
	ds_write_b128 v224, v[80:83] offset:0
	ds_write_b128 v224, v[84:87] offset:1024
	ds_read_b128 v[144:147], v225 offset:0
	ds_read_b128 v[148:151], v226 offset:0
	s_waitcnt lgkmcnt(4)
	v_mfma_f32_16x16x32_fp8_fp8 v[188:191], v[128:129], v[152:153], 0
	v_mfma_f32_16x16x32_fp8_fp8 v[188:191], v[130:131], v[154:155], v[188:191]
	v_mfma_f32_16x16x32_fp8_fp8 v[188:191], v[132:133], v[156:157], v[188:191]
	v_mfma_f32_16x16x32_fp8_fp8 v[188:191], v[134:135], v[158:159], v[188:191]
	v_cndmask_b32_e64 v143, v143, v196, s[10:11]
	s_waitcnt vmcnt(17)
	ds_write_b128 v224, v[88:91] offset:2048
	ds_write_b128 v224, v[92:95] offset:3072
	ds_read_b128 v[152:155], v225 offset:2048
	ds_read_b128 v[156:159], v226 offset:2048
	s_waitcnt lgkmcnt(4)
	v_mfma_f32_16x16x32_fp8_fp8 v[192:195], v[128:129], v[144:145], 0
	v_mfma_f32_16x16x32_fp8_fp8 v[192:195], v[130:131], v[146:147], v[192:195]
	v_mfma_f32_16x16x32_fp8_fp8 v[192:195], v[132:133], v[148:149], v[192:195]
	v_mfma_f32_16x16x32_fp8_fp8 v[192:195], v[134:135], v[150:151], v[192:195]
	v_cndmask_b32_e64 v140, v140, v184, s[16:17]
	s_waitcnt vmcnt(6)
	ds_write_b128 v224, v[0:3] offset:0
	ds_write_b128 v224, v[4:7] offset:1024
	ds_read_b128 v[144:147], v225 offset:0
	ds_read_b128 v[148:151], v226 offset:0
	s_waitcnt lgkmcnt(4)
	v_mfma_f32_16x16x32_fp8_fp8 v[196:199], v[128:129], v[152:153], 0
	v_mfma_f32_16x16x32_fp8_fp8 v[196:199], v[130:131], v[154:155], v[196:199]
	v_mfma_f32_16x16x32_fp8_fp8 v[196:199], v[132:133], v[156:157], v[196:199]
	v_mfma_f32_16x16x32_fp8_fp8 v[196:199], v[134:135], v[158:159], v[196:199]
	v_cndmask_b32_e64 v141, v141, v188, s[16:17]
	s_waitcnt vmcnt(4)
	ds_write_b128 v224, v[8:11] offset:2048
	ds_write_b128 v224, v[12:15] offset:3072
	ds_read_b128 v[152:155], v225 offset:2048
	ds_read_b128 v[156:159], v226 offset:2048
	s_waitcnt lgkmcnt(4)
	v_mfma_f32_16x16x32_fp8_fp8 v[184:187], v[128:129], v[144:145], 0
	v_mfma_f32_16x16x32_fp8_fp8 v[184:187], v[130:131], v[146:147], v[184:187]
	v_mfma_f32_16x16x32_fp8_fp8 v[184:187], v[132:133], v[148:149], v[184:187]
	v_mfma_f32_16x16x32_fp8_fp8 v[184:187], v[134:135], v[150:151], v[184:187]
	v_cndmask_b32_e64 v142, v142, v192, s[16:17]
	s_waitcnt vmcnt(2)
	ds_write_b128 v224, v[16:19] offset:0
	ds_write_b128 v224, v[20:23] offset:1024
	ds_read_b128 v[144:147], v225 offset:0
	ds_read_b128 v[148:151], v226 offset:0
	s_waitcnt lgkmcnt(4)
; #define LAS __attribute__((address_space(3)))
; __device__ __forceinline__ void sparse_unit7(const bf16_t* QKV, const unsigned char* K8, const unsigned char* V8, const int (&selv)[4], bf16_t* OB, LAS unsigned char* wl, int t, int h, int lane) {
;     ...
;             const bool valid = (64 * s + lane) < n;
;             LAS const unsigned* ot = otw + 64 * s; LAS float* pt = ptw + 64 * s;
;             s9_issue_v<1>(vb, V8h, ot, half, l4);
;             f32x4 acc[4];
; #pragma unroll
;             for (int g = 0; g < 4; ++g) { acc[g] = (f32x4){0.f, 0.f, 0.f, 0.f};
; #pragma unroll
;                 for (int ks = 0; ks < 4; ++ks) acc[g] = __builtin_amdgcn_mfma_f32_16x16x32_fp8_fp8(qa[ks], kf[g * 4 + ks], acc[g], 0, 0, 0); }
;             float sc = (slab == 0) ? acc[0][0] : (slab == 1) ? acc[1][0] : (slab == 2) ? acc[2][0] : acc[3][0];
;             sc = valid ? sc * 0.08838834764831845f : -INFINITY;
;             const float mn = fmaxf(m, wave_max(sc));
;             const float alpha = __expf(m - mn), p = __expf(sc - mn);
;             oa = oa * alpha; ob = ob * alpha; m = mn; l = l * alpha + p;
;             pt[lane] = p;
;             asm volatile("" ::: "memory");
;             const int sn_ = (s < 3) ? (s + 1) : 3;
;             s8_issue_k(kf, K8h, wsel, 64 * sn_, n16, slab);
	v_mfma_f32_16x16x32_fp8_fp8 v[188:191], v[128:129], v[152:153], 0
	v_mfma_f32_16x16x32_fp8_fp8 v[188:191], v[130:131], v[154:155], v[188:191]
	v_mfma_f32_16x16x32_fp8_fp8 v[188:191], v[132:133], v[156:157], v[188:191]
	v_mfma_f32_16x16x32_fp8_fp8 v[188:191], v[134:135], v[158:159], v[188:191]
	v_cndmask_b32_e64 v143, v143, v196, s[16:17]
	s_waitcnt vmcnt(0)
	ds_write_b128 v224, v[24:27] offset:2048
	ds_write_b128 v224, v[28:31] offset:3072
	ds_read_b128 v[152:155], v225 offset:2048
	ds_read_b128 v[156:159], v226 offset:2048
	s_waitcnt lgkmcnt(4)
	v_mfma_f32_16x16x32_fp8_fp8 v[192:195], v[128:129], v[144:145], 0
	v_mfma_f32_16x16x32_fp8_fp8 v[192:195], v[130:131], v[146:147], v[192:195]
	v_mfma_f32_16x16x32_fp8_fp8 v[192:195], v[132:133], v[148:149], v[192:195]
	v_mfma_f32_16x16x32_fp8_fp8 v[192:195], v[134:135], v[150:151], v[192:195]
	v_cndmask_b32_e64 v140, v140, v184, s[22:23]
	s_waitcnt lgkmcnt(0)
	v_mfma_f32_16x16x32_fp8_fp8 v[196:199], v[128:129], v[152:153], 0
	v_mfma_f32_16x16x32_fp8_fp8 v[196:199], v[130:131], v[154:155], v[196:199]
	v_mfma_f32_16x16x32_fp8_fp8 v[196:199], v[132:133], v[156:157], v[196:199]
	v_mfma_f32_16x16x32_fp8_fp8 v[196:199], v[134:135], v[158:159], v[196:199]
	v_cndmask_b32_e64 v141, v141, v188, s[22:23]
	s_nop 7
	v_cndmask_b32_e64 v142, v142, v192, s[22:23]
	s_nop 7
	v_cndmask_b32_e64 v143, v143, v196, s[22:23]
	s_sub_i32 s99, s98, 0
	v_mul_f32_e32 v140, 0x3db504f3, v140
	v_cmp_gt_i32_e32 vcc, s99, v217
	s_nop 1
	v_cndmask_b32_e32 v140, v208, v140, vcc
	s_sub_i32 s99, s98, 2
	v_mul_f32_e32 v141, 0x3db504f3, v141
	v_cmp_gt_i32_e32 vcc, s99, v217
	s_nop 1
	v_cndmask_b32_e32 v141, v208, v141, vcc
	s_sub_i32 s99, s98, 4
	v_mul_f32_e32 v142, 0x3db504f3, v142
	v_cmp_gt_i32_e32 vcc, s99, v217
	s_nop 1
	v_cndmask_b32_e32 v142, v208, v142, vcc
	s_sub_i32 s99, s98, 6
	v_mul_f32_e32 v143, 0x3db504f3, v143
	v_cmp_gt_i32_e32 vcc, s99, v217
	s_nop 1
	v_cndmask_b32_e32 v143, v208, v143, vcc
	v_max_f32_e32 v218, v140, v141
	v_max3_f32 v218, v218, v142, v143
	s_nop 1
	v_max_f32_dpp v218, v218, v218 row_ror:8 row_mask:0xf bank_mask:0xf bound_ctrl:1
	s_nop 1
	v_max_f32_dpp v218, v218, v218 row_ror:4 row_mask:0xf bank_mask:0xf bound_ctrl:1
	s_nop 1
	v_max_f32_dpp v218, v218, v218 quad_perm:[2,3,0,1] row_mask:0xf bank_mask:0xf bound_ctrl:1
	s_nop 1
	v_max_f32_dpp v218, v218, v218 quad_perm:[1,0,3,2] row_mask:0xf bank_mask:0xf bound_ctrl:1
	v_mov_b32_e32 v219, v218
	s_nop 1
	v_permlane16_swap_b32_e32 v218, v219
	s_nop 1
	v_max_f32_e32 v218, v218, v219
	v_mov_b32_e32 v219, v218
	s_nop 1
	v_permlane32_swap_b32_e32 v218, v219
	s_nop 1
	v_max_f32_e32 v218, v218, v219
	v_sub_f32_e32 v140, v140, v218
	v_sub_f32_e32 v141, v141, v218
	v_sub_f32_e32 v142, v142, v218
	v_sub_f32_e32 v143, v143, v218
	v_mul_f32_e32 v140, 0x3fb8aa3b, v140
	v_mul_f32_e32 v141, 0x3fb8aa3b, v141
	v_mul_f32_e32 v142, 0x3fb8aa3b, v142
	v_mul_f32_e32 v143, 0x3fb8aa3b, v143
	v_exp_f32_e32 v140, v140
	v_exp_f32_e32 v141, v141
	v_exp_f32_e32 v142, v142
	v_exp_f32_e32 v143, v143
	s_nop 1
	ds_write_b128 v213, v[140:143]
	ds_write_b128 v213, v[136:139] offset:1152
	v_add_f32_e32 v246, v140, v141
	v_add_f32_e32 v247, v142, v143
	v_add_f32_e32 v246, v246, v247
	ds_read_b128 v[64:67], v214 offset:1152
	ds_read_b128 v[68:71], v214 offset:1168
	ds_read_b128 v[72:75], v214 offset:1184
	ds_read_b128 v[76:79], v214 offset:1200
	ds_read_b128 v[80:83], v214 offset:1216
	ds_read_b128 v[84:87], v214 offset:1232
	ds_read_b128 v[88:91], v214 offset:1248
	ds_read_b128 v[92:95], v214 offset:1264
	ds_read_b128 v[112:115], v214 offset:0
	ds_read_b128 v[116:119], v214 offset:16
	ds_read_b128 v[120:123], v214 offset:32
	ds_read_b128 v[124:127], v214 offset:48
	v_mov_b32_e32 v144, 0
	v_mov_b32_e32 v145, 0
	v_mov_b32_e32 v146, 0
	v_mov_b32_e32 v147, 0
	v_mov_b32_e32 v148, 0
	v_mov_b32_e32 v149, 0
	v_mov_b32_e32 v150, 0
	v_mov_b32_e32 v151, 0
	v_mov_b32_e32 v152, 0
	v_mov_b32_e32 v153, 0
	v_mov_b32_e32 v154, 0
	v_mov_b32_e32 v155, 0
	v_mov_b32_e32 v156, 0
	v_mov_b32_e32 v157, 0
	v_mov_b32_e32 v158, 0
	v_mov_b32_e32 v159, 0
	s_waitcnt lgkmcnt(4)
	v_or_b32_e32 v218, v64, v203
	global_load_dwordx4 v[0:3], v218, s[44:45]
	v_or_b32_e32 v218, v65, v203
	global_load_dwordx4 v[4:7], v218, s[44:45]
	v_or_b32_e32 v218, v66, v203
	global_load_dwordx4 v[8:11], v218, s[44:45]
	v_or_b32_e32 v218, v67, v203
	global_load_dwordx4 v[12:15], v218, s[44:45]
	v_or_b32_e32 v218, v68, v203
	global_load_dwordx4 v[16:19], v218, s[44:45]
	v_or_b32_e32 v218, v69, v203
	global_load_dwordx4 v[20:23], v218, s[44:45]
	v_or_b32_e32 v218, v70, v203
	global_load_dwordx4 v[24:27], v218, s[44:45]
	v_or_b32_e32 v218, v71, v203
	global_load_dwordx4 v[28:31], v218, s[44:45]
	v_or_b32_e32 v218, v72, v203
	global_load_dwordx4 v[32:35], v218, s[44:45]
	v_or_b32_e32 v218, v73, v203
	global_load_dwordx4 v[36:39], v218, s[44:45]
	v_or_b32_e32 v218, v74, v203
	global_load_dwordx4 v[40:43], v218, s[44:45]
	v_or_b32_e32 v218, v75, v203
	global_load_dwordx4 v[44:47], v218, s[44:45]
	v_or_b32_e32 v218, v76, v203
	global_load_dwordx4 v[48:51], v218, s[44:45]
	v_or_b32_e32 v218, v77, v203
	global_load_dwordx4 v[52:55], v218, s[44:45]
	v_or_b32_e32 v218, v78, v203
	global_load_dwordx4 v[56:59], v218, s[44:45]
	v_or_b32_e32 v218, v79, v203
	global_load_dwordx4 v[60:63], v218, s[44:45]
	s_nop 1
	v_add_f32_dpp v246, v246, v246 row_ror:8 row_mask:0xf bank_mask:0xf bound_ctrl:1
	s_nop 1
	v_add_f32_dpp v246, v246, v246 row_ror:4 row_mask:0xf bank_mask:0xf bound_ctrl:1
	s_nop 1
	v_add_f32_dpp v246, v246, v246 quad_perm:[2,3,0,1] row_mask:0xf bank_mask:0xf bound_ctrl:1
	s_nop 1
	v_add_f32_dpp v246, v246, v246 quad_perm:[1,0,3,2] row_mask:0xf bank_mask:0xf bound_ctrl:1
	v_mov_b32_e32 v247, v246
	s_nop 1
	v_permlane16_swap_b32_e32 v246, v247
	s_nop 1
	v_add_f32_e32 v246, v246, v247
	v_mov_b32_e32 v247, v246
	s_nop 1
	v_permlane32_swap_b32_e32 v246, v247
	s_nop 1
	v_add_f32_e32 v246, v246, v247
	s_waitcnt lgkmcnt(0)
; #define LAS __attribute__((address_space(3)))
; template <int Q> __device__ __forceinline__ void s9_issue_v(unsigned (&vv)[8], const unsigned char* V8h, LAS const unsigned* otw, int half, int l4) {
; #pragma unroll
;     for (int u2 = 0; u2 < 8; ++u2) vv[u2] = *(const unsigned*)(V8h + (otw[2 * (Q * 8 + u2) + half] | (unsigned)l4));
; }
; template <int Q> __device__ __forceinline__ void s9_pv(const unsigned (&vv)[8], LAS const float* ptw, int half, f32x2_t& oa, f32x2_t& ob) {
; #pragma unroll
;     for (int u2 = 0; u2 < 8; ++u2) { const float p = ptw[2 * (Q * 8 + u2) + half];
;         oa = __builtin_amdgcn_cvt_pk_f32_fp8((int)vv[u2], false) * p + oa; ob = __builtin_amdgcn_cvt_pk_f32_fp8((int)vv[u2], true) * p + ob; }
; }
; __device__ __forceinline__ void sparse_unit7(const bf16_t* QKV, const unsigned char* K8, const unsigned char* V8, const int (&selv)[4], bf16_t* OB, LAS unsigned char* wl, int t, int h, int lane) {
;     ...
;             s9_pv<0>(va, pt, half, oa, ob);
;             s9_issue_v<2>(va, V8h, ot, half, l4);
;             s9_pv<1>(vb, pt, half, oa, ob);
;             s9_issue_v<3>(vb, V8h, ot, half, l4);
;             s9_pv<2>(va, pt, half, oa, ob);
;             s9_issue_v<0>(va, V8h, otw + 64 * sn_, half, l4);
;             s9_pv<3>(vb, pt, half, oa, ob);
	s_waitcnt vmcnt(15)
	v_cvt_pk_f32_fp8_e32 v[184:185], v0
	v_cvt_pk_f32_fp8_sdwa v[186:187], v0 src0_sel:WORD_1
	v_cvt_pk_f32_fp8_e32 v[188:189], v1
	v_cvt_pk_f32_fp8_sdwa v[190:191], v1 src0_sel:WORD_1
	v_cvt_pk_f32_fp8_e32 v[192:193], v2
	v_cvt_pk_f32_fp8_sdwa v[194:195], v2 src0_sel:WORD_1
	v_cvt_pk_f32_fp8_e32 v[196:197], v3
	v_cvt_pk_f32_fp8_sdwa v[198:199], v3 src0_sel:WORD_1
	v_or_b32_e32 v218, v80, v203
	global_load_dwordx4 v[0:3], v218, s[44:45]
	v_pk_fma_f32 v[144:145], v[184:185], v[112:113], v[144:145] op_sel_hi:[1,0,1]
	v_pk_fma_f32 v[146:147], v[186:187], v[112:113], v[146:147] op_sel_hi:[1,0,1]
	v_pk_fma_f32 v[148:149], v[188:189], v[112:113], v[148:149] op_sel_hi:[1,0,1]
	v_pk_fma_f32 v[150:151], v[190:191], v[112:113], v[150:151] op_sel_hi:[1,0,1]
	v_pk_fma_f32 v[152:153], v[192:193], v[112:113], v[152:153] op_sel_hi:[1,0,1]
	v_pk_fma_f32 v[154:155], v[194:195], v[112:113], v[154:155] op_sel_hi:[1,0,1]
	v_pk_fma_f32 v[156:157], v[196:197], v[112:113], v[156:157] op_sel_hi:[1,0,1]
	v_pk_fma_f32 v[158:159], v[198:199], v[112:113], v[158:159] op_sel_hi:[1,0,1]
	s_waitcnt vmcnt(15)
	v_cvt_pk_f32_fp8_e32 v[184:185], v4
	v_cvt_pk_f32_fp8_sdwa v[186:187], v4 src0_sel:WORD_1
	v_cvt_pk_f32_fp8_e32 v[188:189], v5
	v_cvt_pk_f32_fp8_sdwa v[190:191], v5 src0_sel:WORD_1
	v_cvt_pk_f32_fp8_e32 v[192:193], v6
	v_cvt_pk_f32_fp8_sdwa v[194:195], v6 src0_sel:WORD_1
	v_cvt_pk_f32_fp8_e32 v[196:197], v7
	v_cvt_pk_f32_fp8_sdwa v[198:199], v7 src0_sel:WORD_1
	v_or_b32_e32 v218, v81, v203
	global_load_dwordx4 v[4:7], v218, s[44:45]
	v_pk_fma_f32 v[144:145], v[184:185], v[112:113], v[144:145] op_sel:[0,1,0] op_sel_hi:[1,1,1]
	v_pk_fma_f32 v[146:147], v[186:187], v[112:113], v[146:147] op_sel:[0,1,0] op_sel_hi:[1,1,1]
	v_pk_fma_f32 v[148:149], v[188:189], v[112:113], v[148:149] op_sel:[0,1,0] op_sel_hi:[1,1,1]
	v_pk_fma_f32 v[150:151], v[190:191], v[112:113], v[150:151] op_sel:[0,1,0] op_sel_hi:[1,1,1]
	v_pk_fma_f32 v[152:153], v[192:193], v[112:113], v[152:153] op_sel:[0,1,0] op_sel_hi:[1,1,1]
	v_pk_fma_f32 v[154:155], v[194:195], v[112:113], v[154:155] op_sel:[0,1,0] op_sel_hi:[1,1,1]
	v_pk_fma_f32 v[156:157], v[196:197], v[112:113], v[156:157] op_sel:[0,1,0] op_sel_hi:[1,1,1]
	v_pk_fma_f32 v[158:159], v[198:199], v[112:113], v[158:159] op_sel:[0,1,0] op_sel_hi:[1,1,1]
	s_waitcnt vmcnt(15)
	v_cvt_pk_f32_fp8_e32 v[184:185], v8
	v_cvt_pk_f32_fp8_sdwa v[186:187], v8 src0_sel:WORD_1
	v_cvt_pk_f32_fp8_e32 v[188:189], v9
	v_cvt_pk_f32_fp8_sdwa v[190:191], v9 src0_sel:WORD_1
	v_cvt_pk_f32_fp8_e32 v[192:193], v10
	v_cvt_pk_f32_fp8_sdwa v[194:195], v10 src0_sel:WORD_1
	v_cvt_pk_f32_fp8_e32 v[196:197], v11
	v_cvt_pk_f32_fp8_sdwa v[198:199], v11 src0_sel:WORD_1
	v_or_b32_e32 v218, v82, v203
	global_load_dwordx4 v[8:11], v218, s[44:45]
	v_pk_fma_f32 v[144:145], v[184:185], v[114:115], v[144:145] op_sel_hi:[1,0,1]
	v_pk_fma_f32 v[146:147], v[186:187], v[114:115], v[146:147] op_sel_hi:[1,0,1]
	v_pk_fma_f32 v[148:149], v[188:189], v[114:115], v[148:149] op_sel_hi:[1,0,1]
	v_pk_fma_f32 v[150:151], v[190:191], v[114:115], v[150:151] op_sel_hi:[1,0,1]
	v_pk_fma_f32 v[152:153], v[192:193], v[114:115], v[152:153] op_sel_hi:[1,0,1]
	v_pk_fma_f32 v[154:155], v[194:195], v[114:115], v[154:155] op_sel_hi:[1,0,1]
	v_pk_fma_f32 v[156:157], v[196:197], v[114:115], v[156:157] op_sel_hi:[1,0,1]
	v_pk_fma_f32 v[158:159], v[198:199], v[114:115], v[158:159] op_sel_hi:[1,0,1]
	s_waitcnt vmcnt(15)
	v_cvt_pk_f32_fp8_e32 v[184:185], v12
	v_cvt_pk_f32_fp8_sdwa v[186:187], v12 src0_sel:WORD_1
	v_cvt_pk_f32_fp8_e32 v[188:189], v13
	v_cvt_pk_f32_fp8_sdwa v[190:191], v13 src0_sel:WORD_1
	v_cvt_pk_f32_fp8_e32 v[192:193], v14
	v_cvt_pk_f32_fp8_sdwa v[194:195], v14 src0_sel:WORD_1
	v_cvt_pk_f32_fp8_e32 v[196:197], v15
	v_cvt_pk_f32_fp8_sdwa v[198:199], v15 src0_sel:WORD_1
	v_or_b32_e32 v218, v83, v203
	global_load_dwordx4 v[12:15], v218, s[44:45]
	v_pk_fma_f32 v[144:145], v[184:185], v[114:115], v[144:145] op_sel:[0,1,0] op_sel_hi:[1,1,1]
	v_pk_fma_f32 v[146:147], v[186:187], v[114:115], v[146:147] op_sel:[0,1,0] op_sel_hi:[1,1,1]
	v_pk_fma_f32 v[148:149], v[188:189], v[114:115], v[148:149] op_sel:[0,1,0] op_sel_hi:[1,1,1]
	v_pk_fma_f32 v[150:151], v[190:191], v[114:115], v[150:151] op_sel:[0,1,0] op_sel_hi:[1,1,1]
	v_pk_fma_f32 v[152:153], v[192:193], v[114:115], v[152:153] op_sel:[0,1,0] op_sel_hi:[1,1,1]
	v_pk_fma_f32 v[154:155], v[194:195], v[114:115], v[154:155] op_sel:[0,1,0] op_sel_hi:[1,1,1]
	v_pk_fma_f32 v[156:157], v[196:197], v[114:115], v[156:157] op_sel:[0,1,0] op_sel_hi:[1,1,1]
	v_pk_fma_f32 v[158:159], v[198:199], v[114:115], v[158:159] op_sel:[0,1,0] op_sel_hi:[1,1,1]
	s_waitcnt vmcnt(15)
	v_cvt_pk_f32_fp8_e32 v[184:185], v16
	v_cvt_pk_f32_fp8_sdwa v[186:187], v16 src0_sel:WORD_1
	v_cvt_pk_f32_fp8_e32 v[188:189], v17
	v_cvt_pk_f32_fp8_sdwa v[190:191], v17 src0_sel:WORD_1
	v_cvt_pk_f32_fp8_e32 v[192:193], v18
	v_cvt_pk_f32_fp8_sdwa v[194:195], v18 src0_sel:WORD_1
	v_cvt_pk_f32_fp8_e32 v[196:197], v19
	v_cvt_pk_f32_fp8_sdwa v[198:199], v19 src0_sel:WORD_1
	v_or_b32_e32 v218, v84, v203
	global_load_dwordx4 v[16:19], v218, s[44:45]
	v_pk_fma_f32 v[144:145], v[184:185], v[116:117], v[144:145] op_sel_hi:[1,0,1]
	v_pk_fma_f32 v[146:147], v[186:187], v[116:117], v[146:147] op_sel_hi:[1,0,1]
	v_pk_fma_f32 v[148:149], v[188:189], v[116:117], v[148:149] op_sel_hi:[1,0,1]
	v_pk_fma_f32 v[150:151], v[190:191], v[116:117], v[150:151] op_sel_hi:[1,0,1]
	v_pk_fma_f32 v[152:153], v[192:193], v[116:117], v[152:153] op_sel_hi:[1,0,1]
	v_pk_fma_f32 v[154:155], v[194:195], v[116:117], v[154:155] op_sel_hi:[1,0,1]
	v_pk_fma_f32 v[156:157], v[196:197], v[116:117], v[156:157] op_sel_hi:[1,0,1]
	v_pk_fma_f32 v[158:159], v[198:199], v[116:117], v[158:159] op_sel_hi:[1,0,1]
	s_waitcnt vmcnt(15)
; #define LAS __attribute__((address_space(3)))
; template <int Q> __device__ __forceinline__ void s9_issue_v(unsigned (&vv)[8], const unsigned char* V8h, LAS const unsigned* otw, int half, int l4) {
; #pragma unroll
;     for (int u2 = 0; u2 < 8; ++u2) vv[u2] = *(const unsigned*)(V8h + (otw[2 * (Q * 8 + u2) + half] | (unsigned)l4));
; }
; template <int Q> __device__ __forceinline__ void s9_pv(const unsigned (&vv)[8], LAS const float* ptw, int half, f32x2_t& oa, f32x2_t& ob) {
; #pragma unroll
;     for (int u2 = 0; u2 < 8; ++u2) { const float p = ptw[2 * (Q * 8 + u2) + half];
;         oa = __builtin_amdgcn_cvt_pk_f32_fp8((int)vv[u2], false) * p + oa; ob = __builtin_amdgcn_cvt_pk_f32_fp8((int)vv[u2], true) * p + ob; }
; }
; __device__ __forceinline__ void sparse_unit7(const bf16_t* QKV, const unsigned char* K8, const unsigned char* V8, const int (&selv)[4], bf16_t* OB, LAS unsigned char* wl, int t, int h, int lane) {
;     ...
;             s9_pv<0>(va, pt, half, oa, ob);
;             s9_issue_v<2>(va, V8h, ot, half, l4);
;             s9_pv<1>(vb, pt, half, oa, ob);
;             s9_issue_v<3>(vb, V8h, ot, half, l4);
;             s9_pv<2>(va, pt, half, oa, ob);
;             s9_issue_v<0>(va, V8h, otw + 64 * sn_, half, l4);
;             s9_pv<3>(vb, pt, half, oa, ob);
	v_cvt_pk_f32_fp8_e32 v[184:185], v20
	v_cvt_pk_f32_fp8_sdwa v[186:187], v20 src0_sel:WORD_1
	v_cvt_pk_f32_fp8_e32 v[188:189], v21
	v_cvt_pk_f32_fp8_sdwa v[190:191], v21 src0_sel:WORD_1
	v_cvt_pk_f32_fp8_e32 v[192:193], v22
	v_cvt_pk_f32_fp8_sdwa v[194:195], v22 src0_sel:WORD_1
	v_cvt_pk_f32_fp8_e32 v[196:197], v23
	v_cvt_pk_f32_fp8_sdwa v[198:199], v23 src0_sel:WORD_1
	v_or_b32_e32 v218, v85, v203
	global_load_dwordx4 v[20:23], v218, s[44:45]
	v_pk_fma_f32 v[144:145], v[184:185], v[116:117], v[144:145] op_sel:[0,1,0] op_sel_hi:[1,1,1]
	v_pk_fma_f32 v[146:147], v[186:187], v[116:117], v[146:147] op_sel:[0,1,0] op_sel_hi:[1,1,1]
	v_pk_fma_f32 v[148:149], v[188:189], v[116:117], v[148:149] op_sel:[0,1,0] op_sel_hi:[1,1,1]
	v_pk_fma_f32 v[150:151], v[190:191], v[116:117], v[150:151] op_sel:[0,1,0] op_sel_hi:[1,1,1]
	v_pk_fma_f32 v[152:153], v[192:193], v[116:117], v[152:153] op_sel:[0,1,0] op_sel_hi:[1,1,1]
	v_pk_fma_f32 v[154:155], v[194:195], v[116:117], v[154:155] op_sel:[0,1,0] op_sel_hi:[1,1,1]
	v_pk_fma_f32 v[156:157], v[196:197], v[116:117], v[156:157] op_sel:[0,1,0] op_sel_hi:[1,1,1]
	v_pk_fma_f32 v[158:159], v[198:199], v[116:117], v[158:159] op_sel:[0,1,0] op_sel_hi:[1,1,1]
	s_waitcnt vmcnt(15)
	v_cvt_pk_f32_fp8_e32 v[184:185], v24
	v_cvt_pk_f32_fp8_sdwa v[186:187], v24 src0_sel:WORD_1
	v_cvt_pk_f32_fp8_e32 v[188:189], v25
	v_cvt_pk_f32_fp8_sdwa v[190:191], v25 src0_sel:WORD_1
	v_cvt_pk_f32_fp8_e32 v[192:193], v26
	v_cvt_pk_f32_fp8_sdwa v[194:195], v26 src0_sel:WORD_1
	v_cvt_pk_f32_fp8_e32 v[196:197], v27
	v_cvt_pk_f32_fp8_sdwa v[198:199], v27 src0_sel:WORD_1
	v_or_b32_e32 v218, v86, v203
	global_load_dwordx4 v[24:27], v218, s[44:45]
	v_pk_fma_f32 v[144:145], v[184:185], v[118:119], v[144:145] op_sel_hi:[1,0,1]
	v_pk_fma_f32 v[146:147], v[186:187], v[118:119], v[146:147] op_sel_hi:[1,0,1]
	v_pk_fma_f32 v[148:149], v[188:189], v[118:119], v[148:149] op_sel_hi:[1,0,1]
	v_pk_fma_f32 v[150:151], v[190:191], v[118:119], v[150:151] op_sel_hi:[1,0,1]
	v_pk_fma_f32 v[152:153], v[192:193], v[118:119], v[152:153] op_sel_hi:[1,0,1]
	v_pk_fma_f32 v[154:155], v[194:195], v[118:119], v[154:155] op_sel_hi:[1,0,1]
	v_pk_fma_f32 v[156:157], v[196:197], v[118:119], v[156:157] op_sel_hi:[1,0,1]
	v_pk_fma_f32 v[158:159], v[198:199], v[118:119], v[158:159] op_sel_hi:[1,0,1]
	s_waitcnt vmcnt(15)
	v_cvt_pk_f32_fp8_e32 v[184:185], v28
	v_cvt_pk_f32_fp8_sdwa v[186:187], v28 src0_sel:WORD_1
	v_cvt_pk_f32_fp8_e32 v[188:189], v29
	v_cvt_pk_f32_fp8_sdwa v[190:191], v29 src0_sel:WORD_1
	v_cvt_pk_f32_fp8_e32 v[192:193], v30
	v_cvt_pk_f32_fp8_sdwa v[194:195], v30 src0_sel:WORD_1
	v_cvt_pk_f32_fp8_e32 v[196:197], v31
	v_cvt_pk_f32_fp8_sdwa v[198:199], v31 src0_sel:WORD_1
	v_or_b32_e32 v218, v87, v203
	global_load_dwordx4 v[28:31], v218, s[44:45]
	v_pk_fma_f32 v[144:145], v[184:185], v[118:119], v[144:145] op_sel:[0,1,0] op_sel_hi:[1,1,1]
	v_pk_fma_f32 v[146:147], v[186:187], v[118:119], v[146:147] op_sel:[0,1,0] op_sel_hi:[1,1,1]
	v_pk_fma_f32 v[148:149], v[188:189], v[118:119], v[148:149] op_sel:[0,1,0] op_sel_hi:[1,1,1]
	v_pk_fma_f32 v[150:151], v[190:191], v[118:119], v[150:151] op_sel:[0,1,0] op_sel_hi:[1,1,1]
	v_pk_fma_f32 v[152:153], v[192:193], v[118:119], v[152:153] op_sel:[0,1,0] op_sel_hi:[1,1,1]
	v_pk_fma_f32 v[154:155], v[194:195], v[118:119], v[154:155] op_sel:[0,1,0] op_sel_hi:[1,1,1]
	v_pk_fma_f32 v[156:157], v[196:197], v[118:119], v[156:157] op_sel:[0,1,0] op_sel_hi:[1,1,1]
	v_pk_fma_f32 v[158:159], v[198:199], v[118:119], v[158:159] op_sel:[0,1,0] op_sel_hi:[1,1,1]
	s_waitcnt vmcnt(15)
	v_cvt_pk_f32_fp8_e32 v[184:185], v32
	v_cvt_pk_f32_fp8_sdwa v[186:187], v32 src0_sel:WORD_1
	v_cvt_pk_f32_fp8_e32 v[188:189], v33
	v_cvt_pk_f32_fp8_sdwa v[190:191], v33 src0_sel:WORD_1
	v_cvt_pk_f32_fp8_e32 v[192:193], v34
	v_cvt_pk_f32_fp8_sdwa v[194:195], v34 src0_sel:WORD_1
	v_cvt_pk_f32_fp8_e32 v[196:197], v35
	v_cvt_pk_f32_fp8_sdwa v[198:199], v35 src0_sel:WORD_1
	v_or_b32_e32 v218, v88, v203
	global_load_dwordx4 v[32:35], v218, s[44:45]
	v_pk_fma_f32 v[144:145], v[184:185], v[120:121], v[144:145] op_sel_hi:[1,0,1]
	v_pk_fma_f32 v[146:147], v[186:187], v[120:121], v[146:147] op_sel_hi:[1,0,1]
	v_pk_fma_f32 v[148:149], v[188:189], v[120:121], v[148:149] op_sel_hi:[1,0,1]
	v_pk_fma_f32 v[150:151], v[190:191], v[120:121], v[150:151] op_sel_hi:[1,0,1]
	v_pk_fma_f32 v[152:153], v[192:193], v[120:121], v[152:153] op_sel_hi:[1,0,1]
	v_pk_fma_f32 v[154:155], v[194:195], v[120:121], v[154:155] op_sel_hi:[1,0,1]
	v_pk_fma_f32 v[156:157], v[196:197], v[120:121], v[156:157] op_sel_hi:[1,0,1]
	v_pk_fma_f32 v[158:159], v[198:199], v[120:121], v[158:159] op_sel_hi:[1,0,1]
	s_waitcnt vmcnt(15)
	v_cvt_pk_f32_fp8_e32 v[184:185], v36
	v_cvt_pk_f32_fp8_sdwa v[186:187], v36 src0_sel:WORD_1
	v_cvt_pk_f32_fp8_e32 v[188:189], v37
	v_cvt_pk_f32_fp8_sdwa v[190:191], v37 src0_sel:WORD_1
	v_cvt_pk_f32_fp8_e32 v[192:193], v38
	v_cvt_pk_f32_fp8_sdwa v[194:195], v38 src0_sel:WORD_1
	v_cvt_pk_f32_fp8_e32 v[196:197], v39
	v_cvt_pk_f32_fp8_sdwa v[198:199], v39 src0_sel:WORD_1
	v_or_b32_e32 v218, v89, v203
	global_load_dwordx4 v[36:39], v218, s[44:45]
	v_pk_fma_f32 v[144:145], v[184:185], v[120:121], v[144:145] op_sel:[0,1,0] op_sel_hi:[1,1,1]
	v_pk_fma_f32 v[146:147], v[186:187], v[120:121], v[146:147] op_sel:[0,1,0] op_sel_hi:[1,1,1]
	v_pk_fma_f32 v[148:149], v[188:189], v[120:121], v[148:149] op_sel:[0,1,0] op_sel_hi:[1,1,1]
	v_pk_fma_f32 v[150:151], v[190:191], v[120:121], v[150:151] op_sel:[0,1,0] op_sel_hi:[1,1,1]
	v_pk_fma_f32 v[152:153], v[192:193], v[120:121], v[152:153] op_sel:[0,1,0] op_sel_hi:[1,1,1]
	v_pk_fma_f32 v[154:155], v[194:195], v[120:121], v[154:155] op_sel:[0,1,0] op_sel_hi:[1,1,1]
	v_pk_fma_f32 v[156:157], v[196:197], v[120:121], v[156:157] op_sel:[0,1,0] op_sel_hi:[1,1,1]
	v_pk_fma_f32 v[158:159], v[198:199], v[120:121], v[158:159] op_sel:[0,1,0] op_sel_hi:[1,1,1]
	s_waitcnt vmcnt(15)
; #define LAS __attribute__((address_space(3)))
; template <int Q> __device__ __forceinline__ void s9_issue_v(unsigned (&vv)[8], const unsigned char* V8h, LAS const unsigned* otw, int half, int l4) {
; #pragma unroll
;     for (int u2 = 0; u2 < 8; ++u2) vv[u2] = *(const unsigned*)(V8h + (otw[2 * (Q * 8 + u2) + half] | (unsigned)l4));
; }
; template <int Q> __device__ __forceinline__ void s9_pv(const unsigned (&vv)[8], LAS const float* ptw, int half, f32x2_t& oa, f32x2_t& ob) {
; #pragma unroll
;     for (int u2 = 0; u2 < 8; ++u2) { const float p = ptw[2 * (Q * 8 + u2) + half];
;         oa = __builtin_amdgcn_cvt_pk_f32_fp8((int)vv[u2], false) * p + oa; ob = __builtin_amdgcn_cvt_pk_f32_fp8((int)vv[u2], true) * p + ob; }
; }
; __device__ __forceinline__ void sparse_unit7(const bf16_t* QKV, const unsigned char* K8, const unsigned char* V8, const int (&selv)[4], bf16_t* OB, LAS unsigned char* wl, int t, int h, int lane) {
;     ...
;             s9_pv<0>(va, pt, half, oa, ob);
;             s9_issue_v<2>(va, V8h, ot, half, l4);
;             s9_pv<1>(vb, pt, half, oa, ob);
;             s9_issue_v<3>(vb, V8h, ot, half, l4);
;             s9_pv<2>(va, pt, half, oa, ob);
;             s9_issue_v<0>(va, V8h, otw + 64 * sn_, half, l4);
;             s9_pv<3>(vb, pt, half, oa, ob);
	v_cvt_pk_f32_fp8_e32 v[184:185], v40
	v_cvt_pk_f32_fp8_sdwa v[186:187], v40 src0_sel:WORD_1
	v_cvt_pk_f32_fp8_e32 v[188:189], v41
	v_cvt_pk_f32_fp8_sdwa v[190:191], v41 src0_sel:WORD_1
	v_cvt_pk_f32_fp8_e32 v[192:193], v42
	v_cvt_pk_f32_fp8_sdwa v[194:195], v42 src0_sel:WORD_1
	v_cvt_pk_f32_fp8_e32 v[196:197], v43
	v_cvt_pk_f32_fp8_sdwa v[198:199], v43 src0_sel:WORD_1
	v_or_b32_e32 v218, v90, v203
	global_load_dwordx4 v[40:43], v218, s[44:45]
	v_pk_fma_f32 v[144:145], v[184:185], v[122:123], v[144:145] op_sel_hi:[1,0,1]
	v_pk_fma_f32 v[146:147], v[186:187], v[122:123], v[146:147] op_sel_hi:[1,0,1]
	v_pk_fma_f32 v[148:149], v[188:189], v[122:123], v[148:149] op_sel_hi:[1,0,1]
	v_pk_fma_f32 v[150:151], v[190:191], v[122:123], v[150:151] op_sel_hi:[1,0,1]
	v_pk_fma_f32 v[152:153], v[192:193], v[122:123], v[152:153] op_sel_hi:[1,0,1]
	v_pk_fma_f32 v[154:155], v[194:195], v[122:123], v[154:155] op_sel_hi:[1,0,1]
	v_pk_fma_f32 v[156:157], v[196:197], v[122:123], v[156:157] op_sel_hi:[1,0,1]
	v_pk_fma_f32 v[158:159], v[198:199], v[122:123], v[158:159] op_sel_hi:[1,0,1]
	s_waitcnt vmcnt(15)
	v_cvt_pk_f32_fp8_e32 v[184:185], v44
	v_cvt_pk_f32_fp8_sdwa v[186:187], v44 src0_sel:WORD_1
	v_cvt_pk_f32_fp8_e32 v[188:189], v45
	v_cvt_pk_f32_fp8_sdwa v[190:191], v45 src0_sel:WORD_1
	v_cvt_pk_f32_fp8_e32 v[192:193], v46
	v_cvt_pk_f32_fp8_sdwa v[194:195], v46 src0_sel:WORD_1
	v_cvt_pk_f32_fp8_e32 v[196:197], v47
	v_cvt_pk_f32_fp8_sdwa v[198:199], v47 src0_sel:WORD_1
	v_or_b32_e32 v218, v91, v203
	global_load_dwordx4 v[44:47], v218, s[44:45]
	v_pk_fma_f32 v[144:145], v[184:185], v[122:123], v[144:145] op_sel:[0,1,0] op_sel_hi:[1,1,1]
	v_pk_fma_f32 v[146:147], v[186:187], v[122:123], v[146:147] op_sel:[0,1,0] op_sel_hi:[1,1,1]
	v_pk_fma_f32 v[148:149], v[188:189], v[122:123], v[148:149] op_sel:[0,1,0] op_sel_hi:[1,1,1]
	v_pk_fma_f32 v[150:151], v[190:191], v[122:123], v[150:151] op_sel:[0,1,0] op_sel_hi:[1,1,1]
	v_pk_fma_f32 v[152:153], v[192:193], v[122:123], v[152:153] op_sel:[0,1,0] op_sel_hi:[1,1,1]
	v_pk_fma_f32 v[154:155], v[194:195], v[122:123], v[154:155] op_sel:[0,1,0] op_sel_hi:[1,1,1]
	v_pk_fma_f32 v[156:157], v[196:197], v[122:123], v[156:157] op_sel:[0,1,0] op_sel_hi:[1,1,1]
	v_pk_fma_f32 v[158:159], v[198:199], v[122:123], v[158:159] op_sel:[0,1,0] op_sel_hi:[1,1,1]
	s_waitcnt vmcnt(15)
	v_cvt_pk_f32_fp8_e32 v[184:185], v48
	v_cvt_pk_f32_fp8_sdwa v[186:187], v48 src0_sel:WORD_1
	v_cvt_pk_f32_fp8_e32 v[188:189], v49
	v_cvt_pk_f32_fp8_sdwa v[190:191], v49 src0_sel:WORD_1
	v_cvt_pk_f32_fp8_e32 v[192:193], v50
	v_cvt_pk_f32_fp8_sdwa v[194:195], v50 src0_sel:WORD_1
	v_cvt_pk_f32_fp8_e32 v[196:197], v51
	v_cvt_pk_f32_fp8_sdwa v[198:199], v51 src0_sel:WORD_1
	v_or_b32_e32 v218, v92, v203
	global_load_dwordx4 v[48:51], v218, s[44:45]
	v_pk_fma_f32 v[144:145], v[184:185], v[124:125], v[144:145] op_sel_hi:[1,0,1]
	v_pk_fma_f32 v[146:147], v[186:187], v[124:125], v[146:147] op_sel_hi:[1,0,1]
	v_pk_fma_f32 v[148:149], v[188:189], v[124:125], v[148:149] op_sel_hi:[1,0,1]
	v_pk_fma_f32 v[150:151], v[190:191], v[124:125], v[150:151] op_sel_hi:[1,0,1]
	v_pk_fma_f32 v[152:153], v[192:193], v[124:125], v[152:153] op_sel_hi:[1,0,1]
	v_pk_fma_f32 v[154:155], v[194:195], v[124:125], v[154:155] op_sel_hi:[1,0,1]
	v_pk_fma_f32 v[156:157], v[196:197], v[124:125], v[156:157] op_sel_hi:[1,0,1]
	v_pk_fma_f32 v[158:159], v[198:199], v[124:125], v[158:159] op_sel_hi:[1,0,1]
	s_waitcnt vmcnt(15)
	v_cvt_pk_f32_fp8_e32 v[184:185], v52
	v_cvt_pk_f32_fp8_sdwa v[186:187], v52 src0_sel:WORD_1
	v_cvt_pk_f32_fp8_e32 v[188:189], v53
	v_cvt_pk_f32_fp8_sdwa v[190:191], v53 src0_sel:WORD_1
	v_cvt_pk_f32_fp8_e32 v[192:193], v54
	v_cvt_pk_f32_fp8_sdwa v[194:195], v54 src0_sel:WORD_1
	v_cvt_pk_f32_fp8_e32 v[196:197], v55
	v_cvt_pk_f32_fp8_sdwa v[198:199], v55 src0_sel:WORD_1
	v_or_b32_e32 v218, v93, v203
	global_load_dwordx4 v[52:55], v218, s[44:45]
	v_pk_fma_f32 v[144:145], v[184:185], v[124:125], v[144:145] op_sel:[0,1,0] op_sel_hi:[1,1,1]
	v_pk_fma_f32 v[146:147], v[186:187], v[124:125], v[146:147] op_sel:[0,1,0] op_sel_hi:[1,1,1]
	v_pk_fma_f32 v[148:149], v[188:189], v[124:125], v[148:149] op_sel:[0,1,0] op_sel_hi:[1,1,1]
	v_pk_fma_f32 v[150:151], v[190:191], v[124:125], v[150:151] op_sel:[0,1,0] op_sel_hi:[1,1,1]
	v_pk_fma_f32 v[152:153], v[192:193], v[124:125], v[152:153] op_sel:[0,1,0] op_sel_hi:[1,1,1]
	v_pk_fma_f32 v[154:155], v[194:195], v[124:125], v[154:155] op_sel:[0,1,0] op_sel_hi:[1,1,1]
	v_pk_fma_f32 v[156:157], v[196:197], v[124:125], v[156:157] op_sel:[0,1,0] op_sel_hi:[1,1,1]
	v_pk_fma_f32 v[158:159], v[198:199], v[124:125], v[158:159] op_sel:[0,1,0] op_sel_hi:[1,1,1]
	s_waitcnt vmcnt(15)
	v_cvt_pk_f32_fp8_e32 v[184:185], v56
	v_cvt_pk_f32_fp8_sdwa v[186:187], v56 src0_sel:WORD_1
	v_cvt_pk_f32_fp8_e32 v[188:189], v57
	v_cvt_pk_f32_fp8_sdwa v[190:191], v57 src0_sel:WORD_1
	v_cvt_pk_f32_fp8_e32 v[192:193], v58
	v_cvt_pk_f32_fp8_sdwa v[194:195], v58 src0_sel:WORD_1
	v_cvt_pk_f32_fp8_e32 v[196:197], v59
	v_cvt_pk_f32_fp8_sdwa v[198:199], v59 src0_sel:WORD_1
	v_or_b32_e32 v218, v94, v203
	global_load_dwordx4 v[56:59], v218, s[44:45]
	v_pk_fma_f32 v[144:145], v[184:185], v[126:127], v[144:145] op_sel_hi:[1,0,1]
	v_pk_fma_f32 v[146:147], v[186:187], v[126:127], v[146:147] op_sel_hi:[1,0,1]
	v_pk_fma_f32 v[148:149], v[188:189], v[126:127], v[148:149] op_sel_hi:[1,0,1]
	v_pk_fma_f32 v[150:151], v[190:191], v[126:127], v[150:151] op_sel_hi:[1,0,1]
	v_pk_fma_f32 v[152:153], v[192:193], v[126:127], v[152:153] op_sel_hi:[1,0,1]
	v_pk_fma_f32 v[154:155], v[194:195], v[126:127], v[154:155] op_sel_hi:[1,0,1]
	v_pk_fma_f32 v[156:157], v[196:197], v[126:127], v[156:157] op_sel_hi:[1,0,1]
	v_pk_fma_f32 v[158:159], v[198:199], v[126:127], v[158:159] op_sel_hi:[1,0,1]
	s_waitcnt vmcnt(15)
; #define LAS __attribute__((address_space(3)))
; template <int Q> __device__ __forceinline__ void s9_pv(const unsigned (&vv)[8], LAS const float* ptw, int half, f32x2_t& oa, f32x2_t& ob) {
; #pragma unroll
;     for (int u2 = 0; u2 < 8; ++u2) { const float p = ptw[2 * (Q * 8 + u2) + half];
;         oa = __builtin_amdgcn_cvt_pk_f32_fp8((int)vv[u2], false) * p + oa; ob = __builtin_amdgcn_cvt_pk_f32_fp8((int)vv[u2], true) * p + ob; }
; }
; __device__ __forceinline__ void sparse_unit7(const bf16_t* QKV, const unsigned char* K8, const unsigned char* V8, const int (&selv)[4], bf16_t* OB, LAS unsigned char* wl, int t, int h, int lane) {
;     ...
;             s9_pv<0>(va, pt, half, oa, ob);
;             s9_issue_v<2>(va, V8h, ot, half, l4);
;             s9_pv<1>(vb, pt, half, oa, ob);
;             s9_issue_v<3>(vb, V8h, ot, half, l4);
;             s9_pv<2>(va, pt, half, oa, ob);
;             s9_issue_v<0>(va, V8h, otw + 64 * sn_, half, l4);
;             s9_pv<3>(vb, pt, half, oa, ob);
	v_cvt_pk_f32_fp8_e32 v[184:185], v60
	v_cvt_pk_f32_fp8_sdwa v[186:187], v60 src0_sel:WORD_1
	v_cvt_pk_f32_fp8_e32 v[188:189], v61
	v_cvt_pk_f32_fp8_sdwa v[190:191], v61 src0_sel:WORD_1
	v_cvt_pk_f32_fp8_e32 v[192:193], v62
	v_cvt_pk_f32_fp8_sdwa v[194:195], v62 src0_sel:WORD_1
	v_cvt_pk_f32_fp8_e32 v[196:197], v63
	v_cvt_pk_f32_fp8_sdwa v[198:199], v63 src0_sel:WORD_1
	v_or_b32_e32 v218, v95, v203
	global_load_dwordx4 v[60:63], v218, s[44:45]
	v_pk_fma_f32 v[144:145], v[184:185], v[126:127], v[144:145] op_sel:[0,1,0] op_sel_hi:[1,1,1]
	v_pk_fma_f32 v[146:147], v[186:187], v[126:127], v[146:147] op_sel:[0,1,0] op_sel_hi:[1,1,1]
	v_pk_fma_f32 v[148:149], v[188:189], v[126:127], v[148:149] op_sel:[0,1,0] op_sel_hi:[1,1,1]
	v_pk_fma_f32 v[150:151], v[190:191], v[126:127], v[150:151] op_sel:[0,1,0] op_sel_hi:[1,1,1]
	v_pk_fma_f32 v[152:153], v[192:193], v[126:127], v[152:153] op_sel:[0,1,0] op_sel_hi:[1,1,1]
	v_pk_fma_f32 v[154:155], v[194:195], v[126:127], v[154:155] op_sel:[0,1,0] op_sel_hi:[1,1,1]
	v_pk_fma_f32 v[156:157], v[196:197], v[126:127], v[156:157] op_sel:[0,1,0] op_sel_hi:[1,1,1]
	v_pk_fma_f32 v[158:159], v[198:199], v[126:127], v[158:159] op_sel:[0,1,0] op_sel_hi:[1,1,1]
	ds_read_b128 v[112:115], v214 offset:64
	ds_read_b128 v[116:119], v214 offset:80
	ds_read_b128 v[120:123], v214 offset:96
	ds_read_b128 v[124:127], v214 offset:112
	s_waitcnt lgkmcnt(0)
	s_waitcnt vmcnt(15)
	v_cvt_pk_f32_fp8_e32 v[184:185], v0
	v_cvt_pk_f32_fp8_sdwa v[186:187], v0 src0_sel:WORD_1
	v_cvt_pk_f32_fp8_e32 v[188:189], v1
	v_cvt_pk_f32_fp8_sdwa v[190:191], v1 src0_sel:WORD_1
	v_cvt_pk_f32_fp8_e32 v[192:193], v2
	v_cvt_pk_f32_fp8_sdwa v[194:195], v2 src0_sel:WORD_1
	v_cvt_pk_f32_fp8_e32 v[196:197], v3
	v_cvt_pk_f32_fp8_sdwa v[198:199], v3 src0_sel:WORD_1
	v_pk_fma_f32 v[144:145], v[184:185], v[112:113], v[144:145] op_sel_hi:[1,0,1]
	v_pk_fma_f32 v[146:147], v[186:187], v[112:113], v[146:147] op_sel_hi:[1,0,1]
	v_pk_fma_f32 v[148:149], v[188:189], v[112:113], v[148:149] op_sel_hi:[1,0,1]
	v_pk_fma_f32 v[150:151], v[190:191], v[112:113], v[150:151] op_sel_hi:[1,0,1]
	v_pk_fma_f32 v[152:153], v[192:193], v[112:113], v[152:153] op_sel_hi:[1,0,1]
	v_pk_fma_f32 v[154:155], v[194:195], v[112:113], v[154:155] op_sel_hi:[1,0,1]
	v_pk_fma_f32 v[156:157], v[196:197], v[112:113], v[156:157] op_sel_hi:[1,0,1]
	v_pk_fma_f32 v[158:159], v[198:199], v[112:113], v[158:159] op_sel_hi:[1,0,1]
	s_waitcnt vmcnt(14)
	v_cvt_pk_f32_fp8_e32 v[184:185], v4
	v_cvt_pk_f32_fp8_sdwa v[186:187], v4 src0_sel:WORD_1
	v_cvt_pk_f32_fp8_e32 v[188:189], v5
	v_cvt_pk_f32_fp8_sdwa v[190:191], v5 src0_sel:WORD_1
	v_cvt_pk_f32_fp8_e32 v[192:193], v6
	v_cvt_pk_f32_fp8_sdwa v[194:195], v6 src0_sel:WORD_1
	v_cvt_pk_f32_fp8_e32 v[196:197], v7
	v_cvt_pk_f32_fp8_sdwa v[198:199], v7 src0_sel:WORD_1
	v_pk_fma_f32 v[144:145], v[184:185], v[112:113], v[144:145] op_sel:[0,1,0] op_sel_hi:[1,1,1]
	v_pk_fma_f32 v[146:147], v[186:187], v[112:113], v[146:147] op_sel:[0,1,0] op_sel_hi:[1,1,1]
	v_pk_fma_f32 v[148:149], v[188:189], v[112:113], v[148:149] op_sel:[0,1,0] op_sel_hi:[1,1,1]
	v_pk_fma_f32 v[150:151], v[190:191], v[112:113], v[150:151] op_sel:[0,1,0] op_sel_hi:[1,1,1]
	v_pk_fma_f32 v[152:153], v[192:193], v[112:113], v[152:153] op_sel:[0,1,0] op_sel_hi:[1,1,1]
	v_pk_fma_f32 v[154:155], v[194:195], v[112:113], v[154:155] op_sel:[0,1,0] op_sel_hi:[1,1,1]
	v_pk_fma_f32 v[156:157], v[196:197], v[112:113], v[156:157] op_sel:[0,1,0] op_sel_hi:[1,1,1]
	v_pk_fma_f32 v[158:159], v[198:199], v[112:113], v[158:159] op_sel:[0,1,0] op_sel_hi:[1,1,1]
	s_waitcnt vmcnt(13)
	v_cvt_pk_f32_fp8_e32 v[184:185], v8
	v_cvt_pk_f32_fp8_sdwa v[186:187], v8 src0_sel:WORD_1
	v_cvt_pk_f32_fp8_e32 v[188:189], v9
	v_cvt_pk_f32_fp8_sdwa v[190:191], v9 src0_sel:WORD_1
	v_cvt_pk_f32_fp8_e32 v[192:193], v10
	v_cvt_pk_f32_fp8_sdwa v[194:195], v10 src0_sel:WORD_1
	v_cvt_pk_f32_fp8_e32 v[196:197], v11
	v_cvt_pk_f32_fp8_sdwa v[198:199], v11 src0_sel:WORD_1
	v_pk_fma_f32 v[144:145], v[184:185], v[114:115], v[144:145] op_sel_hi:[1,0,1]
	v_pk_fma_f32 v[146:147], v[186:187], v[114:115], v[146:147] op_sel_hi:[1,0,1]
	v_pk_fma_f32 v[148:149], v[188:189], v[114:115], v[148:149] op_sel_hi:[1,0,1]
	v_pk_fma_f32 v[150:151], v[190:191], v[114:115], v[150:151] op_sel_hi:[1,0,1]
	v_pk_fma_f32 v[152:153], v[192:193], v[114:115], v[152:153] op_sel_hi:[1,0,1]
	v_pk_fma_f32 v[154:155], v[194:195], v[114:115], v[154:155] op_sel_hi:[1,0,1]
	v_pk_fma_f32 v[156:157], v[196:197], v[114:115], v[156:157] op_sel_hi:[1,0,1]
	v_pk_fma_f32 v[158:159], v[198:199], v[114:115], v[158:159] op_sel_hi:[1,0,1]
	s_waitcnt vmcnt(12)
	v_cvt_pk_f32_fp8_e32 v[184:185], v12
	v_cvt_pk_f32_fp8_sdwa v[186:187], v12 src0_sel:WORD_1
	v_cvt_pk_f32_fp8_e32 v[188:189], v13
	v_cvt_pk_f32_fp8_sdwa v[190:191], v13 src0_sel:WORD_1
	v_cvt_pk_f32_fp8_e32 v[192:193], v14
	v_cvt_pk_f32_fp8_sdwa v[194:195], v14 src0_sel:WORD_1
	v_cvt_pk_f32_fp8_e32 v[196:197], v15
	v_cvt_pk_f32_fp8_sdwa v[198:199], v15 src0_sel:WORD_1
	v_pk_fma_f32 v[144:145], v[184:185], v[114:115], v[144:145] op_sel:[0,1,0] op_sel_hi:[1,1,1]
	v_pk_fma_f32 v[146:147], v[186:187], v[114:115], v[146:147] op_sel:[0,1,0] op_sel_hi:[1,1,1]
	v_pk_fma_f32 v[148:149], v[188:189], v[114:115], v[148:149] op_sel:[0,1,0] op_sel_hi:[1,1,1]
	v_pk_fma_f32 v[150:151], v[190:191], v[114:115], v[150:151] op_sel:[0,1,0] op_sel_hi:[1,1,1]
	v_pk_fma_f32 v[152:153], v[192:193], v[114:115], v[152:153] op_sel:[0,1,0] op_sel_hi:[1,1,1]
	v_pk_fma_f32 v[154:155], v[194:195], v[114:115], v[154:155] op_sel:[0,1,0] op_sel_hi:[1,1,1]
	v_pk_fma_f32 v[156:157], v[196:197], v[114:115], v[156:157] op_sel:[0,1,0] op_sel_hi:[1,1,1]
	v_pk_fma_f32 v[158:159], v[198:199], v[114:115], v[158:159] op_sel:[0,1,0] op_sel_hi:[1,1,1]
	s_waitcnt vmcnt(11)
; #define LAS __attribute__((address_space(3)))
; template <int Q> __device__ __forceinline__ void s9_pv(const unsigned (&vv)[8], LAS const float* ptw, int half, f32x2_t& oa, f32x2_t& ob) {
; #pragma unroll
;     for (int u2 = 0; u2 < 8; ++u2) { const float p = ptw[2 * (Q * 8 + u2) + half];
;         oa = __builtin_amdgcn_cvt_pk_f32_fp8((int)vv[u2], false) * p + oa; ob = __builtin_amdgcn_cvt_pk_f32_fp8((int)vv[u2], true) * p + ob; }
; }
; __device__ __forceinline__ void sparse_unit7(const bf16_t* QKV, const unsigned char* K8, const unsigned char* V8, const int (&selv)[4], bf16_t* OB, LAS unsigned char* wl, int t, int h, int lane) {
;     ...
;             s9_pv<2>(va, pt, half, oa, ob);
;             s9_issue_v<0>(va, V8h, otw + 64 * sn_, half, l4);
;             s9_pv<3>(vb, pt, half, oa, ob);
	v_cvt_pk_f32_fp8_e32 v[184:185], v16
	v_cvt_pk_f32_fp8_sdwa v[186:187], v16 src0_sel:WORD_1
	v_cvt_pk_f32_fp8_e32 v[188:189], v17
	v_cvt_pk_f32_fp8_sdwa v[190:191], v17 src0_sel:WORD_1
	v_cvt_pk_f32_fp8_e32 v[192:193], v18
	v_cvt_pk_f32_fp8_sdwa v[194:195], v18 src0_sel:WORD_1
	v_cvt_pk_f32_fp8_e32 v[196:197], v19
	v_cvt_pk_f32_fp8_sdwa v[198:199], v19 src0_sel:WORD_1
	v_pk_fma_f32 v[144:145], v[184:185], v[116:117], v[144:145] op_sel_hi:[1,0,1]
	v_pk_fma_f32 v[146:147], v[186:187], v[116:117], v[146:147] op_sel_hi:[1,0,1]
	v_pk_fma_f32 v[148:149], v[188:189], v[116:117], v[148:149] op_sel_hi:[1,0,1]
	v_pk_fma_f32 v[150:151], v[190:191], v[116:117], v[150:151] op_sel_hi:[1,0,1]
	v_pk_fma_f32 v[152:153], v[192:193], v[116:117], v[152:153] op_sel_hi:[1,0,1]
	v_pk_fma_f32 v[154:155], v[194:195], v[116:117], v[154:155] op_sel_hi:[1,0,1]
	v_pk_fma_f32 v[156:157], v[196:197], v[116:117], v[156:157] op_sel_hi:[1,0,1]
	v_pk_fma_f32 v[158:159], v[198:199], v[116:117], v[158:159] op_sel_hi:[1,0,1]
	s_waitcnt vmcnt(10)
	v_cvt_pk_f32_fp8_e32 v[184:185], v20
	v_cvt_pk_f32_fp8_sdwa v[186:187], v20 src0_sel:WORD_1
	v_cvt_pk_f32_fp8_e32 v[188:189], v21
	v_cvt_pk_f32_fp8_sdwa v[190:191], v21 src0_sel:WORD_1
	v_cvt_pk_f32_fp8_e32 v[192:193], v22
	v_cvt_pk_f32_fp8_sdwa v[194:195], v22 src0_sel:WORD_1
	v_cvt_pk_f32_fp8_e32 v[196:197], v23
	v_cvt_pk_f32_fp8_sdwa v[198:199], v23 src0_sel:WORD_1
	v_pk_fma_f32 v[144:145], v[184:185], v[116:117], v[144:145] op_sel:[0,1,0] op_sel_hi:[1,1,1]
	v_pk_fma_f32 v[146:147], v[186:187], v[116:117], v[146:147] op_sel:[0,1,0] op_sel_hi:[1,1,1]
	v_pk_fma_f32 v[148:149], v[188:189], v[116:117], v[148:149] op_sel:[0,1,0] op_sel_hi:[1,1,1]
	v_pk_fma_f32 v[150:151], v[190:191], v[116:117], v[150:151] op_sel:[0,1,0] op_sel_hi:[1,1,1]
	v_pk_fma_f32 v[152:153], v[192:193], v[116:117], v[152:153] op_sel:[0,1,0] op_sel_hi:[1,1,1]
	v_pk_fma_f32 v[154:155], v[194:195], v[116:117], v[154:155] op_sel:[0,1,0] op_sel_hi:[1,1,1]
	v_pk_fma_f32 v[156:157], v[196:197], v[116:117], v[156:157] op_sel:[0,1,0] op_sel_hi:[1,1,1]
	v_pk_fma_f32 v[158:159], v[198:199], v[116:117], v[158:159] op_sel:[0,1,0] op_sel_hi:[1,1,1]
	s_waitcnt vmcnt(9)
	v_cvt_pk_f32_fp8_e32 v[184:185], v24
	v_cvt_pk_f32_fp8_sdwa v[186:187], v24 src0_sel:WORD_1
	v_cvt_pk_f32_fp8_e32 v[188:189], v25
	v_cvt_pk_f32_fp8_sdwa v[190:191], v25 src0_sel:WORD_1
	v_cvt_pk_f32_fp8_e32 v[192:193], v26
	v_cvt_pk_f32_fp8_sdwa v[194:195], v26 src0_sel:WORD_1
	v_cvt_pk_f32_fp8_e32 v[196:197], v27
	v_cvt_pk_f32_fp8_sdwa v[198:199], v27 src0_sel:WORD_1
	v_pk_fma_f32 v[144:145], v[184:185], v[118:119], v[144:145] op_sel_hi:[1,0,1]
	v_pk_fma_f32 v[146:147], v[186:187], v[118:119], v[146:147] op_sel_hi:[1,0,1]
	v_pk_fma_f32 v[148:149], v[188:189], v[118:119], v[148:149] op_sel_hi:[1,0,1]
	v_pk_fma_f32 v[150:151], v[190:191], v[118:119], v[150:151] op_sel_hi:[1,0,1]
	v_pk_fma_f32 v[152:153], v[192:193], v[118:119], v[152:153] op_sel_hi:[1,0,1]
	v_pk_fma_f32 v[154:155], v[194:195], v[118:119], v[154:155] op_sel_hi:[1,0,1]
	v_pk_fma_f32 v[156:157], v[196:197], v[118:119], v[156:157] op_sel_hi:[1,0,1]
	v_pk_fma_f32 v[158:159], v[198:199], v[118:119], v[158:159] op_sel_hi:[1,0,1]
	s_waitcnt vmcnt(8)
	v_cvt_pk_f32_fp8_e32 v[184:185], v28
	v_cvt_pk_f32_fp8_sdwa v[186:187], v28 src0_sel:WORD_1
	v_cvt_pk_f32_fp8_e32 v[188:189], v29
	v_cvt_pk_f32_fp8_sdwa v[190:191], v29 src0_sel:WORD_1
	v_cvt_pk_f32_fp8_e32 v[192:193], v30
	v_cvt_pk_f32_fp8_sdwa v[194:195], v30 src0_sel:WORD_1
	v_cvt_pk_f32_fp8_e32 v[196:197], v31
	v_cvt_pk_f32_fp8_sdwa v[198:199], v31 src0_sel:WORD_1
	v_pk_fma_f32 v[144:145], v[184:185], v[118:119], v[144:145] op_sel:[0,1,0] op_sel_hi:[1,1,1]
	v_pk_fma_f32 v[146:147], v[186:187], v[118:119], v[146:147] op_sel:[0,1,0] op_sel_hi:[1,1,1]
	v_pk_fma_f32 v[148:149], v[188:189], v[118:119], v[148:149] op_sel:[0,1,0] op_sel_hi:[1,1,1]
	v_pk_fma_f32 v[150:151], v[190:191], v[118:119], v[150:151] op_sel:[0,1,0] op_sel_hi:[1,1,1]
	v_pk_fma_f32 v[152:153], v[192:193], v[118:119], v[152:153] op_sel:[0,1,0] op_sel_hi:[1,1,1]
	v_pk_fma_f32 v[154:155], v[194:195], v[118:119], v[154:155] op_sel:[0,1,0] op_sel_hi:[1,1,1]
	v_pk_fma_f32 v[156:157], v[196:197], v[118:119], v[156:157] op_sel:[0,1,0] op_sel_hi:[1,1,1]
	v_pk_fma_f32 v[158:159], v[198:199], v[118:119], v[158:159] op_sel:[0,1,0] op_sel_hi:[1,1,1]
	s_waitcnt vmcnt(7)
	v_cvt_pk_f32_fp8_e32 v[184:185], v32
	v_cvt_pk_f32_fp8_sdwa v[186:187], v32 src0_sel:WORD_1
	v_cvt_pk_f32_fp8_e32 v[188:189], v33
	v_cvt_pk_f32_fp8_sdwa v[190:191], v33 src0_sel:WORD_1
	v_cvt_pk_f32_fp8_e32 v[192:193], v34
	v_cvt_pk_f32_fp8_sdwa v[194:195], v34 src0_sel:WORD_1
	v_cvt_pk_f32_fp8_e32 v[196:197], v35
	v_cvt_pk_f32_fp8_sdwa v[198:199], v35 src0_sel:WORD_1
	v_pk_fma_f32 v[144:145], v[184:185], v[120:121], v[144:145] op_sel_hi:[1,0,1]
	v_pk_fma_f32 v[146:147], v[186:187], v[120:121], v[146:147] op_sel_hi:[1,0,1]
	v_pk_fma_f32 v[148:149], v[188:189], v[120:121], v[148:149] op_sel_hi:[1,0,1]
	v_pk_fma_f32 v[150:151], v[190:191], v[120:121], v[150:151] op_sel_hi:[1,0,1]
	v_pk_fma_f32 v[152:153], v[192:193], v[120:121], v[152:153] op_sel_hi:[1,0,1]
	v_pk_fma_f32 v[154:155], v[194:195], v[120:121], v[154:155] op_sel_hi:[1,0,1]
	v_pk_fma_f32 v[156:157], v[196:197], v[120:121], v[156:157] op_sel_hi:[1,0,1]
	v_pk_fma_f32 v[158:159], v[198:199], v[120:121], v[158:159] op_sel_hi:[1,0,1]
	s_waitcnt vmcnt(6)
; #define LAS __attribute__((address_space(3)))
; template <int Q> __device__ __forceinline__ void s9_pv(const unsigned (&vv)[8], LAS const float* ptw, int half, f32x2_t& oa, f32x2_t& ob) {
; #pragma unroll
;     for (int u2 = 0; u2 < 8; ++u2) { const float p = ptw[2 * (Q * 8 + u2) + half];
;         oa = __builtin_amdgcn_cvt_pk_f32_fp8((int)vv[u2], false) * p + oa; ob = __builtin_amdgcn_cvt_pk_f32_fp8((int)vv[u2], true) * p + ob; }
; }
; __device__ __forceinline__ void sparse_unit7(const bf16_t* QKV, const unsigned char* K8, const unsigned char* V8, const int (&selv)[4], bf16_t* OB, LAS unsigned char* wl, int t, int h, int lane) {
;     ...
;             s9_pv<2>(va, pt, half, oa, ob);
;             s9_issue_v<0>(va, V8h, otw + 64 * sn_, half, l4);
;             s9_pv<3>(vb, pt, half, oa, ob);
	v_cvt_pk_f32_fp8_e32 v[184:185], v36
	v_cvt_pk_f32_fp8_sdwa v[186:187], v36 src0_sel:WORD_1
	v_cvt_pk_f32_fp8_e32 v[188:189], v37
	v_cvt_pk_f32_fp8_sdwa v[190:191], v37 src0_sel:WORD_1
	v_cvt_pk_f32_fp8_e32 v[192:193], v38
	v_cvt_pk_f32_fp8_sdwa v[194:195], v38 src0_sel:WORD_1
	v_cvt_pk_f32_fp8_e32 v[196:197], v39
	v_cvt_pk_f32_fp8_sdwa v[198:199], v39 src0_sel:WORD_1
	v_pk_fma_f32 v[144:145], v[184:185], v[120:121], v[144:145] op_sel:[0,1,0] op_sel_hi:[1,1,1]
	v_pk_fma_f32 v[146:147], v[186:187], v[120:121], v[146:147] op_sel:[0,1,0] op_sel_hi:[1,1,1]
	v_pk_fma_f32 v[148:149], v[188:189], v[120:121], v[148:149] op_sel:[0,1,0] op_sel_hi:[1,1,1]
	v_pk_fma_f32 v[150:151], v[190:191], v[120:121], v[150:151] op_sel:[0,1,0] op_sel_hi:[1,1,1]
	v_pk_fma_f32 v[152:153], v[192:193], v[120:121], v[152:153] op_sel:[0,1,0] op_sel_hi:[1,1,1]
	v_pk_fma_f32 v[154:155], v[194:195], v[120:121], v[154:155] op_sel:[0,1,0] op_sel_hi:[1,1,1]
	v_pk_fma_f32 v[156:157], v[196:197], v[120:121], v[156:157] op_sel:[0,1,0] op_sel_hi:[1,1,1]
	v_pk_fma_f32 v[158:159], v[198:199], v[120:121], v[158:159] op_sel:[0,1,0] op_sel_hi:[1,1,1]
	s_waitcnt vmcnt(5)
	v_cvt_pk_f32_fp8_e32 v[184:185], v40
	v_cvt_pk_f32_fp8_sdwa v[186:187], v40 src0_sel:WORD_1
	v_cvt_pk_f32_fp8_e32 v[188:189], v41
	v_cvt_pk_f32_fp8_sdwa v[190:191], v41 src0_sel:WORD_1
	v_cvt_pk_f32_fp8_e32 v[192:193], v42
	v_cvt_pk_f32_fp8_sdwa v[194:195], v42 src0_sel:WORD_1
	v_cvt_pk_f32_fp8_e32 v[196:197], v43
	v_cvt_pk_f32_fp8_sdwa v[198:199], v43 src0_sel:WORD_1
	v_pk_fma_f32 v[144:145], v[184:185], v[122:123], v[144:145] op_sel_hi:[1,0,1]
	v_pk_fma_f32 v[146:147], v[186:187], v[122:123], v[146:147] op_sel_hi:[1,0,1]
	v_pk_fma_f32 v[148:149], v[188:189], v[122:123], v[148:149] op_sel_hi:[1,0,1]
	v_pk_fma_f32 v[150:151], v[190:191], v[122:123], v[150:151] op_sel_hi:[1,0,1]
	v_pk_fma_f32 v[152:153], v[192:193], v[122:123], v[152:153] op_sel_hi:[1,0,1]
	v_pk_fma_f32 v[154:155], v[194:195], v[122:123], v[154:155] op_sel_hi:[1,0,1]
	v_pk_fma_f32 v[156:157], v[196:197], v[122:123], v[156:157] op_sel_hi:[1,0,1]
	v_pk_fma_f32 v[158:159], v[198:199], v[122:123], v[158:159] op_sel_hi:[1,0,1]
	s_waitcnt vmcnt(4)
	v_cvt_pk_f32_fp8_e32 v[184:185], v44
	v_cvt_pk_f32_fp8_sdwa v[186:187], v44 src0_sel:WORD_1
	v_cvt_pk_f32_fp8_e32 v[188:189], v45
	v_cvt_pk_f32_fp8_sdwa v[190:191], v45 src0_sel:WORD_1
	v_cvt_pk_f32_fp8_e32 v[192:193], v46
	v_cvt_pk_f32_fp8_sdwa v[194:195], v46 src0_sel:WORD_1
	v_cvt_pk_f32_fp8_e32 v[196:197], v47
	v_cvt_pk_f32_fp8_sdwa v[198:199], v47 src0_sel:WORD_1
	v_pk_fma_f32 v[144:145], v[184:185], v[122:123], v[144:145] op_sel:[0,1,0] op_sel_hi:[1,1,1]
	v_pk_fma_f32 v[146:147], v[186:187], v[122:123], v[146:147] op_sel:[0,1,0] op_sel_hi:[1,1,1]
	v_pk_fma_f32 v[148:149], v[188:189], v[122:123], v[148:149] op_sel:[0,1,0] op_sel_hi:[1,1,1]
	v_pk_fma_f32 v[150:151], v[190:191], v[122:123], v[150:151] op_sel:[0,1,0] op_sel_hi:[1,1,1]
	v_pk_fma_f32 v[152:153], v[192:193], v[122:123], v[152:153] op_sel:[0,1,0] op_sel_hi:[1,1,1]
	v_pk_fma_f32 v[154:155], v[194:195], v[122:123], v[154:155] op_sel:[0,1,0] op_sel_hi:[1,1,1]
	v_pk_fma_f32 v[156:157], v[196:197], v[122:123], v[156:157] op_sel:[0,1,0] op_sel_hi:[1,1,1]
	v_pk_fma_f32 v[158:159], v[198:199], v[122:123], v[158:159] op_sel:[0,1,0] op_sel_hi:[1,1,1]
	s_waitcnt vmcnt(3)
	v_cvt_pk_f32_fp8_e32 v[184:185], v48
	v_cvt_pk_f32_fp8_sdwa v[186:187], v48 src0_sel:WORD_1
	v_cvt_pk_f32_fp8_e32 v[188:189], v49
	v_cvt_pk_f32_fp8_sdwa v[190:191], v49 src0_sel:WORD_1
	v_cvt_pk_f32_fp8_e32 v[192:193], v50
	v_cvt_pk_f32_fp8_sdwa v[194:195], v50 src0_sel:WORD_1
	v_cvt_pk_f32_fp8_e32 v[196:197], v51
	v_cvt_pk_f32_fp8_sdwa v[198:199], v51 src0_sel:WORD_1
	v_pk_fma_f32 v[144:145], v[184:185], v[124:125], v[144:145] op_sel_hi:[1,0,1]
	v_pk_fma_f32 v[146:147], v[186:187], v[124:125], v[146:147] op_sel_hi:[1,0,1]
	v_pk_fma_f32 v[148:149], v[188:189], v[124:125], v[148:149] op_sel_hi:[1,0,1]
	v_pk_fma_f32 v[150:151], v[190:191], v[124:125], v[150:151] op_sel_hi:[1,0,1]
	v_pk_fma_f32 v[152:153], v[192:193], v[124:125], v[152:153] op_sel_hi:[1,0,1]
	v_pk_fma_f32 v[154:155], v[194:195], v[124:125], v[154:155] op_sel_hi:[1,0,1]
	v_pk_fma_f32 v[156:157], v[196:197], v[124:125], v[156:157] op_sel_hi:[1,0,1]
	v_pk_fma_f32 v[158:159], v[198:199], v[124:125], v[158:159] op_sel_hi:[1,0,1]
	s_waitcnt vmcnt(2)
	v_cvt_pk_f32_fp8_e32 v[184:185], v52
	v_cvt_pk_f32_fp8_sdwa v[186:187], v52 src0_sel:WORD_1
	v_cvt_pk_f32_fp8_e32 v[188:189], v53
	v_cvt_pk_f32_fp8_sdwa v[190:191], v53 src0_sel:WORD_1
	v_cvt_pk_f32_fp8_e32 v[192:193], v54
	v_cvt_pk_f32_fp8_sdwa v[194:195], v54 src0_sel:WORD_1
	v_cvt_pk_f32_fp8_e32 v[196:197], v55
	v_cvt_pk_f32_fp8_sdwa v[198:199], v55 src0_sel:WORD_1
	v_pk_fma_f32 v[144:145], v[184:185], v[124:125], v[144:145] op_sel:[0,1,0] op_sel_hi:[1,1,1]
	v_pk_fma_f32 v[146:147], v[186:187], v[124:125], v[146:147] op_sel:[0,1,0] op_sel_hi:[1,1,1]
	v_pk_fma_f32 v[148:149], v[188:189], v[124:125], v[148:149] op_sel:[0,1,0] op_sel_hi:[1,1,1]
	v_pk_fma_f32 v[150:151], v[190:191], v[124:125], v[150:151] op_sel:[0,1,0] op_sel_hi:[1,1,1]
	v_pk_fma_f32 v[152:153], v[192:193], v[124:125], v[152:153] op_sel:[0,1,0] op_sel_hi:[1,1,1]
	v_pk_fma_f32 v[154:155], v[194:195], v[124:125], v[154:155] op_sel:[0,1,0] op_sel_hi:[1,1,1]
	v_pk_fma_f32 v[156:157], v[196:197], v[124:125], v[156:157] op_sel:[0,1,0] op_sel_hi:[1,1,1]
	v_pk_fma_f32 v[158:159], v[198:199], v[124:125], v[158:159] op_sel:[0,1,0] op_sel_hi:[1,1,1]
	s_waitcnt vmcnt(1)
; __device__ __forceinline__ unsigned pk2(float lo, float hi) { return f2bf(lo) | (f2bf(hi) << 16); }
; __device__ __forceinline__ float swap32_sum(float a, float b) { unsigned x, y; pl32(__builtin_bit_cast(unsigned, a), __builtin_bit_cast(unsigned, b), x, y); return __builtin_bit_cast(float, x) + __builtin_bit_cast(float, y); }
; __device__ __forceinline__ void sparse_unit7(const bf16_t* QKV, const unsigned char* K8, const unsigned char* V8, const int (&selv)[4], bf16_t* OB, LAS unsigned char* wl, int t, int h, int lane) {
;     ...
;     const float inv = 1.f / wave_sum(l);
;     const float r0 = swap32_sum(oa.x, oa.x), r1 = swap32_sum(oa.y, oa.y), r2 = swap32_sum(ob.x, ob.x), r3 = swap32_sum(ob.y, ob.y);
;     if (half == 0) { u32x2 o; o.x = pk2(r0 * inv, r1 * inv); o.y = pk2(r2 * inv, r3 * inv); *(u32x2*)(OB + (size_t)t * 1024 + h * 128 + l4) = o; }
;     asm volatile("" ::: "memory");
; __global__ void __launch_bounds__(NTHREADS, 2) mega(Args a) {
;     ...
;                     for (int t = qg; t < SEQ; t += nqg) { int selc[4];
; #pragma unroll
;                         for (int s = 0; s < 4; ++s) selc[s] = seln[s];
;                         const int tn = min(t + nqg, SEQ - 1);
; #pragma unroll
;                         for (int s = 0; s < 4; ++s) seln[s] = (int)SEL[(size_t)tn * 256 + 64 * s + lane];
;                         sparse_unit7(QKV, K8, V8, selc, OB, lds + wave * 4096, t, h, lane); } }
	v_cvt_pk_f32_fp8_e32 v[184:185], v56
	v_cvt_pk_f32_fp8_sdwa v[186:187], v56 src0_sel:WORD_1
	v_cvt_pk_f32_fp8_e32 v[188:189], v57
	v_cvt_pk_f32_fp8_sdwa v[190:191], v57 src0_sel:WORD_1
	v_cvt_pk_f32_fp8_e32 v[192:193], v58
	v_cvt_pk_f32_fp8_sdwa v[194:195], v58 src0_sel:WORD_1
	v_cvt_pk_f32_fp8_e32 v[196:197], v59
	v_cvt_pk_f32_fp8_sdwa v[198:199], v59 src0_sel:WORD_1
	v_pk_fma_f32 v[144:145], v[184:185], v[126:127], v[144:145] op_sel_hi:[1,0,1]
	v_pk_fma_f32 v[146:147], v[186:187], v[126:127], v[146:147] op_sel_hi:[1,0,1]
	v_pk_fma_f32 v[148:149], v[188:189], v[126:127], v[148:149] op_sel_hi:[1,0,1]
	v_pk_fma_f32 v[150:151], v[190:191], v[126:127], v[150:151] op_sel_hi:[1,0,1]
	v_pk_fma_f32 v[152:153], v[192:193], v[126:127], v[152:153] op_sel_hi:[1,0,1]
	v_pk_fma_f32 v[154:155], v[194:195], v[126:127], v[154:155] op_sel_hi:[1,0,1]
	v_pk_fma_f32 v[156:157], v[196:197], v[126:127], v[156:157] op_sel_hi:[1,0,1]
	v_pk_fma_f32 v[158:159], v[198:199], v[126:127], v[158:159] op_sel_hi:[1,0,1]
	s_waitcnt vmcnt(0)
	v_cvt_pk_f32_fp8_e32 v[184:185], v60
	v_cvt_pk_f32_fp8_sdwa v[186:187], v60 src0_sel:WORD_1
	v_cvt_pk_f32_fp8_e32 v[188:189], v61
	v_cvt_pk_f32_fp8_sdwa v[190:191], v61 src0_sel:WORD_1
	v_cvt_pk_f32_fp8_e32 v[192:193], v62
	v_cvt_pk_f32_fp8_sdwa v[194:195], v62 src0_sel:WORD_1
	v_cvt_pk_f32_fp8_e32 v[196:197], v63
	v_cvt_pk_f32_fp8_sdwa v[198:199], v63 src0_sel:WORD_1
	v_pk_fma_f32 v[144:145], v[184:185], v[126:127], v[144:145] op_sel:[0,1,0] op_sel_hi:[1,1,1]
	v_pk_fma_f32 v[146:147], v[186:187], v[126:127], v[146:147] op_sel:[0,1,0] op_sel_hi:[1,1,1]
	v_pk_fma_f32 v[148:149], v[188:189], v[126:127], v[148:149] op_sel:[0,1,0] op_sel_hi:[1,1,1]
	v_pk_fma_f32 v[150:151], v[190:191], v[126:127], v[150:151] op_sel:[0,1,0] op_sel_hi:[1,1,1]
	v_pk_fma_f32 v[152:153], v[192:193], v[126:127], v[152:153] op_sel:[0,1,0] op_sel_hi:[1,1,1]
	v_pk_fma_f32 v[154:155], v[194:195], v[126:127], v[154:155] op_sel:[0,1,0] op_sel_hi:[1,1,1]
	v_pk_fma_f32 v[156:157], v[196:197], v[126:127], v[156:157] op_sel:[0,1,0] op_sel_hi:[1,1,1]
	v_pk_fma_f32 v[158:159], v[198:199], v[126:127], v[158:159] op_sel:[0,1,0] op_sel_hi:[1,1,1]
	v_rcp_f32_e32 v218, v246
	s_nop 1
	v_fma_f32 v219, -v246, v218, 1.0
	v_fma_f32 v218, v219, v218, v218
	v_add_f32_dpp v144, v144, v144 row_ror:8 row_mask:0xf bank_mask:0xf bound_ctrl:1
	v_add_f32_dpp v145, v145, v145 row_ror:8 row_mask:0xf bank_mask:0xf bound_ctrl:1
	v_add_f32_dpp v146, v146, v146 row_ror:8 row_mask:0xf bank_mask:0xf bound_ctrl:1
	v_add_f32_dpp v147, v147, v147 row_ror:8 row_mask:0xf bank_mask:0xf bound_ctrl:1
	v_add_f32_dpp v148, v148, v148 row_ror:8 row_mask:0xf bank_mask:0xf bound_ctrl:1
	v_add_f32_dpp v149, v149, v149 row_ror:8 row_mask:0xf bank_mask:0xf bound_ctrl:1
	v_add_f32_dpp v150, v150, v150 row_ror:8 row_mask:0xf bank_mask:0xf bound_ctrl:1
	v_add_f32_dpp v151, v151, v151 row_ror:8 row_mask:0xf bank_mask:0xf bound_ctrl:1
	v_add_f32_dpp v152, v152, v152 row_ror:8 row_mask:0xf bank_mask:0xf bound_ctrl:1
	v_add_f32_dpp v153, v153, v153 row_ror:8 row_mask:0xf bank_mask:0xf bound_ctrl:1
	v_add_f32_dpp v154, v154, v154 row_ror:8 row_mask:0xf bank_mask:0xf bound_ctrl:1
	v_add_f32_dpp v155, v155, v155 row_ror:8 row_mask:0xf bank_mask:0xf bound_ctrl:1
	v_add_f32_dpp v156, v156, v156 row_ror:8 row_mask:0xf bank_mask:0xf bound_ctrl:1
	v_add_f32_dpp v157, v157, v157 row_ror:8 row_mask:0xf bank_mask:0xf bound_ctrl:1
	v_add_f32_dpp v158, v158, v158 row_ror:8 row_mask:0xf bank_mask:0xf bound_ctrl:1
	v_add_f32_dpp v159, v159, v159 row_ror:8 row_mask:0xf bank_mask:0xf bound_ctrl:1
	s_nop 1
	v_permlane16_swap_b32_e32 v144, v148
	v_permlane16_swap_b32_e32 v145, v149
	v_permlane16_swap_b32_e32 v146, v150
	v_permlane16_swap_b32_e32 v147, v151
	v_permlane16_swap_b32_e32 v152, v156
	v_permlane16_swap_b32_e32 v153, v157
	v_permlane16_swap_b32_e32 v154, v158
	v_permlane16_swap_b32_e32 v155, v159
	s_nop 1
	v_add_f32_e32 v144, v144, v148
	v_add_f32_e32 v145, v145, v149
	v_add_f32_e32 v146, v146, v150
	v_add_f32_e32 v147, v147, v151
	v_add_f32_e32 v152, v152, v156
	v_add_f32_e32 v153, v153, v157
	v_add_f32_e32 v154, v154, v158
	v_add_f32_e32 v155, v155, v159
	s_nop 1
	v_permlane32_swap_b32_e32 v144, v152
	v_permlane32_swap_b32_e32 v145, v153
	v_permlane32_swap_b32_e32 v146, v154
	v_permlane32_swap_b32_e32 v147, v155
	s_nop 1
	v_add_f32_e32 v144, v144, v152
	v_add_f32_e32 v145, v145, v153
	v_add_f32_e32 v146, v146, v154
	v_add_f32_e32 v147, v147, v155
	v_mul_f32_e32 v144, v144, v218
	v_mul_f32_e32 v145, v145, v218
	v_mul_f32_e32 v146, v146, v218
	v_mul_f32_e32 v147, v147, v218
	v_cvt_pk_bf16_f32 v246, v144, v145
	v_cvt_pk_bf16_f32 v247, v146, v147
	s_lshl_b32 s0, s34, 11
	s_add_u32 s0, s46, s0
	s_addc_u32 s1, s47, 0
	s_mov_b64 s[4:5], exec
	s_mov_b32 exec_lo, 0x00ff00ff
	s_mov_b32 exec_hi, 0x00ff00ff
	global_store_dwordx2 v215, v[246:247], s[0:1]
	s_mov_b64 exec, s[4:5]
	s_add_i32 s34, s34, s48
	s_cmpk_lt_i32 s34, 0x4000
	s_cbranch_scc1 .Lsp_unit
	s_waitcnt vmcnt(0)
	s_branch .LBB0_190

; #define LAS __attribute__((address_space(3)))
; __device__ __forceinline__ void dilated_block(const bf16_t* QKV, bf16_t* OG, float* LSE, LAS unsigned char* lds, int u, int tid) {
;     ...
;     __syncthreads();
; #pragma unroll
;     for (int i = 0; i < 8; ++i) { const int c = tid + 512 * i, row = c >> 4, ch = c & 15, m = mbase + row; u32x4 v = {0u, 0u, 0u, 0u};
;         if (m >= 0) v = *(const u32x4*)(QKV + (size_t)((m << rsh) + p) * QKVW + COL_AV + head * 128 + ch * 8);
;         *(LAS u32x4*)(lds + row * VRS + ch * 16) = v; }
;     __syncthreads();
.LBB0_197:
	s_ashr_i32 s0, s8, 9
	s_lshl_b32 s13, s0, 1
	s_lshr_b32 s4, 0x80, s13
	s_and_b32 s1, s8, 0x7f
	s_sub_i32 s5, 7, s13
	s_add_i32 s4, s4, -1
	s_lshr_b32 s19, s1, s5
	s_and_b32 s5, s4, s1
	s_bfe_u32 s9, s8, 0x20007
	s_lshl_b32 s1, s0, 2
	s_lshl_b32 s28, s5, 7
	s_or_b32 s4, s1, s9
	s_add_i32 s23, s28, 0xffffff80
	s_lshl_b32 s10, s4, 7
	v_add_u32_e32 v1, s23, v51
	s_ashr_i32 s11, s10, 31
	v_cmp_lt_i32_e32 vcc, -1, v1
	v_mov_b32_e32 v0, 0
	v_lshlrev_b32_e32 v6, 1, v48
	v_mov_b32_e32 v2, 0
	v_mov_b32_e32 v3, 0
	v_mov_b32_e32 v4, 0
	v_mov_b32_e32 v5, 0
	s_barrier
	v_mov_b32_e32 v7, v161
	s_movk_i32 s1, 0x3c00
	v_mov_b64_e32 v[94:95], 0
	v_mov_b64_e32 v[96:97], 0
	v_mov_b64_e32 v[98:99], 0
	v_mov_b64_e32 v[100:101], 0
	v_mov_b64_e32 v[102:103], 0
	v_mov_b64_e32 v[104:105], 0
	v_mov_b64_e32 v[106:107], 0
	v_mov_b64_e32 v[108:109], 0
	v_mov_b64_e32 v[110:111], 0
	v_mov_b64_e32 v[112:113], 0
	v_mov_b64_e32 v[114:115], 0
	v_mov_b64_e32 v[116:117], 0
	v_mov_b64_e32 v[118:119], 0
	v_mov_b64_e32 v[120:121], 0
	v_mov_b64_e32 v[122:123], 0
	v_mov_b64_e32 v[124:125], 0
	v_add_u32_e32 v126, s23, v51
	v_cmp_lt_i32_e32 vcc, -1, v126
	s_and_saveexec_b64 s[16:17], vcc
	v_lshlrev_b32_e32 v126, s13, v126
	v_add_u32_e32 v126, s19, v126
	v_mov_b64_e32 v[128:129], s[20:21]
	v_mad_i64_i32 v[128:129], s[34:35], v126, s1, v[128:129]
	v_lshl_add_u64 v[128:129], s[10:11], 1, v[128:129]
	v_lshl_add_u64 v[128:129], v[128:129], 0, v[6:7]
	v_add_co_u32_e32 v128, vcc, 0x1000, v128
	s_nop 1
	v_addc_co_u32_e32 v129, vcc, 0, v129, vcc
	global_load_dwordx4 v[94:97], v[128:129], off offset:2048
	s_or_b64 exec, exec, s[16:17]
	v_add_u32_e32 v126, s23, v56
	v_cmp_lt_i32_e32 vcc, -1, v126
	s_and_saveexec_b64 s[16:17], vcc
	v_lshlrev_b32_e32 v126, s13, v126
	v_add_u32_e32 v126, s19, v126
	v_mov_b64_e32 v[128:129], s[20:21]
	v_mad_i64_i32 v[128:129], s[34:35], v126, s1, v[128:129]
	v_lshl_add_u64 v[128:129], s[10:11], 1, v[128:129]
	v_lshl_add_u64 v[128:129], v[128:129], 0, v[6:7]
	v_add_co_u32_e32 v128, vcc, 0x1000, v128
	s_nop 1
	v_addc_co_u32_e32 v129, vcc, 0, v129, vcc
	global_load_dwordx4 v[98:101], v[128:129], off offset:2048
	s_or_b64 exec, exec, s[16:17]
	v_add_u32_e32 v126, s23, v57
	v_cmp_lt_i32_e32 vcc, -1, v126
	s_and_saveexec_b64 s[16:17], vcc
	v_lshlrev_b32_e32 v126, s13, v126
	v_add_u32_e32 v126, s19, v126
	v_mov_b64_e32 v[128:129], s[20:21]
	v_mad_i64_i32 v[128:129], s[34:35], v126, s1, v[128:129]
	v_lshl_add_u64 v[128:129], s[10:11], 1, v[128:129]
	v_lshl_add_u64 v[128:129], v[128:129], 0, v[6:7]
	v_add_co_u32_e32 v128, vcc, 0x1000, v128
	s_nop 1
	v_addc_co_u32_e32 v129, vcc, 0, v129, vcc
	global_load_dwordx4 v[102:105], v[128:129], off offset:2048
	s_or_b64 exec, exec, s[16:17]
	v_add_u32_e32 v126, s23, v58
	v_cmp_lt_i32_e32 vcc, -1, v126
	s_and_saveexec_b64 s[16:17], vcc
	v_lshlrev_b32_e32 v126, s13, v126
	v_add_u32_e32 v126, s19, v126
	v_mov_b64_e32 v[128:129], s[20:21]
	v_mad_i64_i32 v[128:129], s[34:35], v126, s1, v[128:129]
	v_lshl_add_u64 v[128:129], s[10:11], 1, v[128:129]
	v_lshl_add_u64 v[128:129], v[128:129], 0, v[6:7]
	v_add_co_u32_e32 v128, vcc, 0x1000, v128
	s_nop 1
	v_addc_co_u32_e32 v129, vcc, 0, v129, vcc
	global_load_dwordx4 v[106:109], v[128:129], off offset:2048
	s_or_b64 exec, exec, s[16:17]
	v_add_u32_e32 v126, s23, v59
	v_cmp_lt_i32_e32 vcc, -1, v126
	s_and_saveexec_b64 s[16:17], vcc
	v_lshlrev_b32_e32 v126, s13, v126
	v_add_u32_e32 v126, s19, v126
	v_mov_b64_e32 v[128:129], s[20:21]
	v_mad_i64_i32 v[128:129], s[34:35], v126, s1, v[128:129]
	v_lshl_add_u64 v[128:129], s[10:11], 1, v[128:129]
	v_lshl_add_u64 v[128:129], v[128:129], 0, v[6:7]
	v_add_co_u32_e32 v128, vcc, 0x1000, v128
	s_nop 1
	v_addc_co_u32_e32 v129, vcc, 0, v129, vcc
	global_load_dwordx4 v[110:113], v[128:129], off offset:2048
	s_or_b64 exec, exec, s[16:17]
	v_add_u32_e32 v126, s23, v60
	v_cmp_lt_i32_e32 vcc, -1, v126
	s_and_saveexec_b64 s[16:17], vcc
	v_lshlrev_b32_e32 v126, s13, v126
	v_add_u32_e32 v126, s19, v126
	v_mov_b64_e32 v[128:129], s[20:21]
	v_mad_i64_i32 v[128:129], s[34:35], v126, s1, v[128:129]
	v_lshl_add_u64 v[128:129], s[10:11], 1, v[128:129]
	v_lshl_add_u64 v[128:129], v[128:129], 0, v[6:7]
	v_add_co_u32_e32 v128, vcc, 0x1000, v128
	s_nop 1
	v_addc_co_u32_e32 v129, vcc, 0, v129, vcc
	global_load_dwordx4 v[114:117], v[128:129], off offset:2048
	s_or_b64 exec, exec, s[16:17]
	v_add_u32_e32 v126, s23, v61
	v_cmp_lt_i32_e32 vcc, -1, v126
	s_and_saveexec_b64 s[16:17], vcc
	v_lshlrev_b32_e32 v126, s13, v126
	v_add_u32_e32 v126, s19, v126
	v_mov_b64_e32 v[128:129], s[20:21]
	v_mad_i64_i32 v[128:129], s[34:35], v126, s1, v[128:129]
	v_lshl_add_u64 v[128:129], s[10:11], 1, v[128:129]
	v_lshl_add_u64 v[128:129], v[128:129], 0, v[6:7]
	v_add_co_u32_e32 v128, vcc, 0x1000, v128
	s_nop 1
	v_addc_co_u32_e32 v129, vcc, 0, v129, vcc
	global_load_dwordx4 v[118:121], v[128:129], off offset:2048
	s_or_b64 exec, exec, s[16:17]
	v_add_u32_e32 v126, s23, v62
	v_cmp_lt_i32_e32 vcc, -1, v126
	s_and_saveexec_b64 s[16:17], vcc
	v_lshlrev_b32_e32 v126, s13, v126
	v_add_u32_e32 v126, s19, v126
	v_mov_b64_e32 v[128:129], s[20:21]
	v_mad_i64_i32 v[128:129], s[34:35], v126, s1, v[128:129]
	v_lshl_add_u64 v[128:129], s[10:11], 1, v[128:129]
	v_lshl_add_u64 v[128:129], v[128:129], 0, v[6:7]
	v_add_co_u32_e32 v128, vcc, 0x1000, v128
	s_nop 1
	v_addc_co_u32_e32 v129, vcc, 0, v129, vcc
	global_load_dwordx4 v[122:125], v[128:129], off offset:2048
	s_or_b64 exec, exec, s[16:17]
	v_readfirstlane_b32 s1, v212
	s_ashr_i32 s22, s1, 2
	s_and_b32 s1, s22, -16
	s_add_i32 s16, s1, s28
	s_waitcnt vmcnt(0)
	ds_write_b128 v65, v[94:97]
	ds_write_b128 v66, v[98:101]
	ds_write_b128 v67, v[102:105]
	ds_write_b128 v68, v[106:109]
	ds_write_b128 v69, v[110:113]
	ds_write_b128 v70, v[114:117]
	ds_write_b128 v71, v[118:121]
	ds_write_b128 v72, v[122:125]
	v_or_b32_e32 v0, s16, v154
	v_lshlrev_b32_e32 v0, s13, v0
	v_add_u32_e32 v52, s19, v0
	v_mov_b64_e32 v[54:55], s[20:21]
	s_movk_i32 s28, 0x3c00
	v_mad_i64_i32 v[0:1], s[16:17], v52, s28, v[54:55]
	s_lshl_b64 s[10:11], s[10:11], 1
	v_lshl_add_u64 v[0:1], v[0:1], 0, s[10:11]
	v_lshl_add_u64 v[0:1], v[0:1], 0, v[160:161]
	s_waitcnt lgkmcnt(0)
	s_barrier
; __device__ __forceinline__ void dilated_block(const bf16_t* QKV, bf16_t* OG, float* LSE, LAS unsigned char* lds, int u, int tid) {
;     ...
;     const int i0 = wave * 16;
;     const int tq = ((mbase + 128 + i0 + n16) << rsh) + p;
;     bf16x8 qf[4];
; #pragma unroll
;     for (int ks = 0; ks < 4; ++ks) qf[ks] = *(const bf16x8*)(QKV + (size_t)tq * QKVW + COL_AQ + head * 128 + ks * 32 + slab * 8);
;     f32x4 sacc[10];
; #pragma unroll
;     for (int jt = 0; jt < 9; ++jt) { int m = mbase + i0 + 16 * jt + n16; m = max(m, 0);
;         const bf16_t* kp = QKV + (size_t)((m << rsh) + p) * QKVW + COL_AK + head * 128 + slab * 8;
;         f32x4 acc = {0.f, 0.f, 0.f, 0.f};
; #pragma unroll
;         for (int ks = 0; ks < 4; ++ks) acc = __builtin_amdgcn_mfma_f32_16x16x32_bf16(*(const bf16x8*)(kp + ks * 32), qf[ks], acc, 0, 0, 0);
;         sacc[jt] = acc; }
	global_load_dwordx4 v[20:23], v[0:1], off
	global_load_dwordx4 v[16:19], v[0:1], off offset:64
	global_load_dwordx4 v[12:15], v[0:1], off offset:128
	global_load_dwordx4 v[4:7], v[0:1], off offset:192
	v_or_b32_e32 v0, s23, v154
	v_add_u32_e32 v53, s1, v0
	v_max_i32_e32 v0, 0, v53
	v_lshlrev_b32_e32 v0, s13, v0
	v_add_u32_e32 v0, s19, v0
	v_mad_i64_i32 v[0:1], s[16:17], v0, s28, v[54:55]
	v_lshl_add_u64 v[0:1], v[0:1], 0, s[10:11]
	v_lshl_add_u64 v[24:25], v[0:1], 0, v[160:161]
	global_load_dwordx4 v[0:3], v[24:25], off offset:3072
	global_load_dwordx4 v[94:97], v[24:25], off offset:3136
	s_cmp_lg_u32 s5, 0
	global_load_dwordx4 v[98:101], v[24:25], off offset:3200
	global_load_dwordx4 v[102:105], v[24:25], off offset:3264
	v_max_i32_e32 v8, -16, v53
	v_add_lshl_u32 v8, v8, 16, s13
	v_add_u32_e32 v8, s19, v8
	v_mad_i64_i32 v[8:9], s[16:17], v8, s28, v[54:55]
	v_lshl_add_u64 v[8:9], v[8:9], 0, s[10:11]
	v_lshl_add_u64 v[28:29], v[8:9], 0, v[160:161]
	global_load_dwordx4 v[8:11], v[28:29], off offset:3072
	global_load_dwordx4 v[106:109], v[28:29], off offset:3136
	global_load_dwordx4 v[110:113], v[28:29], off offset:3200
	global_load_dwordx4 v[114:117], v[28:29], off offset:3264
	v_max_i32_e32 v24, 0xffffffe0, v53
	v_add_lshl_u32 v24, v24, 32, s13
	v_add_u32_e32 v24, s19, v24
	v_mad_i64_i32 v[24:25], s[16:17], v24, s28, v[54:55]
	v_lshl_add_u64 v[24:25], v[24:25], 0, s[10:11]
	v_lshl_add_u64 v[32:33], v[24:25], 0, v[160:161]
	global_load_dwordx4 v[24:27], v[32:33], off offset:3072
	global_load_dwordx4 v[118:121], v[32:33], off offset:3136
	global_load_dwordx4 v[122:125], v[32:33], off offset:3200
	global_load_dwordx4 v[126:129], v[32:33], off offset:3264
	v_max_i32_e32 v28, 0xffffffd0, v53
	v_add_lshl_u32 v28, v28, 48, s13
	v_add_u32_e32 v28, s19, v28
	v_mad_i64_i32 v[28:29], s[16:17], v28, s28, v[54:55]
	v_lshl_add_u64 v[28:29], v[28:29], 0, s[10:11]
	v_lshl_add_u64 v[36:37], v[28:29], 0, v[160:161]
	global_load_dwordx4 v[28:31], v[36:37], off offset:3072
	global_load_dwordx4 v[130:133], v[36:37], off offset:3136
	global_load_dwordx4 v[134:137], v[36:37], off offset:3200
	global_load_dwordx4 v[138:141], v[36:37], off offset:3264
	v_max_i32_e32 v32, 0xffffffc0, v53
	v_add_lshl_u32 v32, v32, 64, s13
	v_add_u32_e32 v32, s19, v32
	v_mad_i64_i32 v[32:33], s[16:17], v32, s28, v[54:55]
	v_lshl_add_u64 v[32:33], v[32:33], 0, s[10:11]
	v_lshl_add_u64 v[40:41], v[32:33], 0, v[160:161]
	global_load_dwordx4 v[32:35], v[40:41], off offset:3072
	global_load_dwordx4 v[142:145], v[40:41], off offset:3136
	global_load_dwordx4 v[146:149], v[40:41], off offset:3200
	global_load_dwordx4 v[150:153], v[40:41], off offset:3264
	v_max_i32_e32 v36, 0xffffffb0, v53
	v_add_u32_e32 v36, 0x50, v36
	v_lshlrev_b32_e32 v36, s13, v36
	v_add_u32_e32 v36, s19, v36
	v_mad_i64_i32 v[36:37], s[16:17], v36, s28, v[54:55]
	v_lshl_add_u64 v[36:37], v[36:37], 0, s[10:11]
	v_lshl_add_u64 v[44:45], v[36:37], 0, v[160:161]
	global_load_dwordx4 v[36:39], v[44:45], off offset:3072
	global_load_dwordx4 v[184:187], v[44:45], off offset:3136
	global_load_dwordx4 v[188:191], v[44:45], off offset:3200
	global_load_dwordx4 v[192:195], v[44:45], off offset:3264
	v_max_i32_e32 v40, 0xffffffa0, v53
	v_add_u32_e32 v40, 0x60, v40
	v_lshlrev_b32_e32 v40, s13, v40
	v_add_u32_e32 v40, s19, v40
	v_mad_i64_i32 v[40:41], s[16:17], v40, s28, v[54:55]
	v_lshl_add_u64 v[40:41], v[40:41], 0, s[10:11]
	v_lshl_add_u64 v[74:75], v[40:41], 0, v[160:161]
	global_load_dwordx4 v[40:43], v[74:75], off offset:3072
	global_load_dwordx4 v[196:199], v[74:75], off offset:3136
	global_load_dwordx4 v[200:203], v[74:75], off offset:3200
	global_load_dwordx4 v[214:217], v[74:75], off offset:3264
	v_max_i32_e32 v44, 0xffffff90, v53
	v_add_u32_e32 v44, 0x70, v44
	v_lshlrev_b32_e32 v44, s13, v44
	v_add_u32_e32 v44, s19, v44
	v_mad_i64_i32 v[44:45], s[16:17], v44, s28, v[54:55]
	v_lshl_add_u64 v[44:45], v[44:45], 0, s[10:11]
	v_lshl_add_u64 v[78:79], v[44:45], 0, v[160:161]
	global_load_dwordx4 v[44:47], v[78:79], off offset:3072
	global_load_dwordx4 v[218:221], v[78:79], off offset:3136
	v_max_i32_e32 v53, 0xffffff80, v53
	v_add_u32_e32 v53, 0x80, v53
	v_lshlrev_b32_e32 v53, s13, v53
	v_add_u32_e32 v53, s19, v53
	v_mad_i64_i32 v[54:55], s[16:17], v53, s28, v[54:55]
	v_lshl_add_u64 v[54:55], v[54:55], 0, s[10:11]
	v_lshl_add_u64 v[54:55], v[54:55], 0, v[160:161]
	s_cselect_b64 s[10:11], -1, 0
	global_load_dwordx4 v[222:225], v[78:79], off offset:3200
	global_load_dwordx4 v[226:229], v[78:79], off offset:3264
	global_load_dwordx4 v[230:233], v[54:55], off offset:3072
	global_load_dwordx4 v[234:237], v[54:55], off offset:3136
	global_load_dwordx4 v[238:241], v[54:55], off offset:3200
	global_load_dwordx4 v[242:245], v[54:55], off offset:3264
	s_waitcnt vmcnt(35)
	v_mfma_f32_16x16x32_bf16 v[0:3], v[0:3], v[20:23], 0
	s_waitcnt vmcnt(34)
	v_mfma_f32_16x16x32_bf16 v[0:3], v[94:97], v[16:19], v[0:3]
	s_waitcnt vmcnt(33)
	v_mfma_f32_16x16x32_bf16 v[0:3], v[98:101], v[12:15], v[0:3]
	s_waitcnt vmcnt(32)
	v_mfma_f32_16x16x32_bf16 v[0:3], v[102:105], v[4:7], v[0:3]
	s_waitcnt vmcnt(31)
	v_mfma_f32_16x16x32_bf16 v[8:11], v[8:11], v[20:23], 0
	s_waitcnt vmcnt(30)
	v_mfma_f32_16x16x32_bf16 v[8:11], v[106:109], v[16:19], v[8:11]
	s_waitcnt vmcnt(29)
	v_mfma_f32_16x16x32_bf16 v[8:11], v[110:113], v[12:15], v[8:11]
	s_waitcnt vmcnt(28)
	v_mfma_f32_16x16x32_bf16 v[8:11], v[114:117], v[4:7], v[8:11]
	s_waitcnt vmcnt(27)
	v_mfma_f32_16x16x32_bf16 v[24:27], v[24:27], v[20:23], 0
	s_waitcnt vmcnt(26)
	v_mfma_f32_16x16x32_bf16 v[24:27], v[118:121], v[16:19], v[24:27]
	s_waitcnt vmcnt(25)
	v_mfma_f32_16x16x32_bf16 v[24:27], v[122:125], v[12:15], v[24:27]
	s_waitcnt vmcnt(24)
; __device__ __forceinline__ void dilated_block(const bf16_t* QKV, bf16_t* OG, float* LSE, LAS unsigned char* lds, int u, int tid) {
;     ...
;     for (int jt = 0; jt < 9; ++jt) { int m = mbase + i0 + 16 * jt + n16; m = max(m, 0);
;         const bf16_t* kp = QKV + (size_t)((m << rsh) + p) * QKVW + COL_AK + head * 128 + slab * 8;
;         f32x4 acc = {0.f, 0.f, 0.f, 0.f};
; #pragma unroll
;         for (int ks = 0; ks < 4; ++ks) acc = __builtin_amdgcn_mfma_f32_16x16x32_bf16(*(const bf16x8*)(kp + ks * 32), qf[ks], acc, 0, 0, 0);
;         sacc[jt] = acc; }
;     float mx = -INFINITY;
; #pragma unroll
;     for (int jt = 0; jt < 9; ++jt)
; #pragma unroll
;         for (int i = 0; i < 4; ++i) { const int d = 128 + n16 - 16 * jt - 4 * slab - i, kk = i0 + 16 * jt + 4 * slab + i;
;             const bool ok = (d >= 0) && (d <= 128) && (nb > 0 || kk >= 128);
;             const float s = ok ? sacc[jt][i] * 0.08838834764831845f : -INFINITY; sacc[jt][i] = s; mx = fmaxf(mx, s); }
	v_mfma_f32_16x16x32_bf16 v[24:27], v[126:129], v[4:7], v[24:27]
	s_waitcnt vmcnt(23)
	v_mfma_f32_16x16x32_bf16 v[28:31], v[28:31], v[20:23], 0
	s_waitcnt vmcnt(22)
	v_mfma_f32_16x16x32_bf16 v[28:31], v[130:133], v[16:19], v[28:31]
	s_waitcnt vmcnt(21)
	v_mfma_f32_16x16x32_bf16 v[28:31], v[134:137], v[12:15], v[28:31]
	s_waitcnt vmcnt(20)
	v_mfma_f32_16x16x32_bf16 v[28:31], v[138:141], v[4:7], v[28:31]
	s_waitcnt vmcnt(19)
	v_mfma_f32_16x16x32_bf16 v[32:35], v[32:35], v[20:23], 0
	s_waitcnt vmcnt(18)
	v_mfma_f32_16x16x32_bf16 v[32:35], v[142:145], v[16:19], v[32:35]
	s_waitcnt vmcnt(17)
	v_mfma_f32_16x16x32_bf16 v[32:35], v[146:149], v[12:15], v[32:35]
	s_waitcnt vmcnt(16)
	v_mfma_f32_16x16x32_bf16 v[32:35], v[150:153], v[4:7], v[32:35]
	s_waitcnt vmcnt(15)
	v_mfma_f32_16x16x32_bf16 v[36:39], v[36:39], v[20:23], 0
	s_waitcnt vmcnt(14)
	v_mfma_f32_16x16x32_bf16 v[36:39], v[184:187], v[16:19], v[36:39]
	s_waitcnt vmcnt(13)
	v_mfma_f32_16x16x32_bf16 v[36:39], v[188:191], v[12:15], v[36:39]
	s_waitcnt vmcnt(12)
	v_mfma_f32_16x16x32_bf16 v[36:39], v[192:195], v[4:7], v[36:39]
	s_waitcnt vmcnt(11)
	v_mfma_f32_16x16x32_bf16 v[40:43], v[40:43], v[20:23], 0
	s_waitcnt vmcnt(10)
	v_mfma_f32_16x16x32_bf16 v[40:43], v[196:199], v[16:19], v[40:43]
	s_waitcnt vmcnt(9)
	v_mfma_f32_16x16x32_bf16 v[40:43], v[200:203], v[12:15], v[40:43]
	s_waitcnt vmcnt(8)
	v_mfma_f32_16x16x32_bf16 v[40:43], v[214:217], v[4:7], v[40:43]
	s_waitcnt vmcnt(7)
	v_mfma_f32_16x16x32_bf16 v[44:47], v[44:47], v[20:23], 0
	s_waitcnt vmcnt(6)
	v_mfma_f32_16x16x32_bf16 v[44:47], v[218:221], v[16:19], v[44:47]
	s_waitcnt vmcnt(5)
	v_mfma_f32_16x16x32_bf16 v[44:47], v[222:225], v[12:15], v[44:47]
	s_waitcnt vmcnt(4)
	v_mfma_f32_16x16x32_bf16 v[44:47], v[226:229], v[4:7], v[44:47]
	s_waitcnt vmcnt(3)
	v_mfma_f32_16x16x32_bf16 v[20:23], v[230:233], v[20:23], 0
	s_waitcnt vmcnt(2)
	v_mfma_f32_16x16x32_bf16 v[16:19], v[234:237], v[16:19], v[20:23]
	s_waitcnt vmcnt(1)
	v_mfma_f32_16x16x32_bf16 v[12:15], v[238:241], v[12:15], v[16:19]
	s_waitcnt vmcnt(0)
	v_mfma_f32_16x16x32_bf16 v[4:7], v[242:245], v[4:7], v[12:15]
	s_nop 7
	s_nop 2
	v_or_b32_e32 v14, s1, v49
	v_mov_b32_e32 v12, 0xff800000
	v_mov_b32_e32 v13, 0xff800000
	s_and_saveexec_b64 s[16:17], s[42:43]
	v_or_b32_e32 v13, 2, v14
	s_movk_i32 s5, 0x7f
	v_cmp_lt_i32_e32 vcc, s5, v13
	v_mul_f32_e32 v2, 0x3db504f3, v2
	s_or_b64 vcc, s[10:11], vcc
	v_cndmask_b32_e32 v13, v208, v2, vcc
	s_or_b64 exec, exec, s[16:17]
	s_and_saveexec_b64 s[16:17], s[44:45]
	v_or_b32_e32 v2, 3, v14
	s_movk_i32 s5, 0x7f
	v_cmp_lt_i32_e32 vcc, s5, v2
	v_mul_f32_e32 v2, 0x3db504f3, v3
	s_or_b64 vcc, s[10:11], vcc
	v_cndmask_b32_e32 v12, v208, v2, vcc
	s_or_b64 exec, exec, s[16:17]
	s_movk_i32 s5, 0x7f
	v_cmp_lt_i32_e32 vcc, s5, v14
	s_or_b64 s[16:17], s[10:11], vcc
	v_mul_f32_e32 v0, 0x3db504f3, v0
	s_and_b64 vcc, s[38:39], s[16:17]
	s_movk_i32 s5, 0x7e
	v_cndmask_b32_e32 v0, v208, v0, vcc
	v_cmp_lt_i32_e32 vcc, s5, v14
	s_or_b64 s[16:17], s[10:11], vcc
	v_mul_f32_e32 v1, 0x3db504f3, v1
	s_and_b64 vcc, s[40:41], s[16:17]
	v_cndmask_b32_e32 v1, v208, v1, vcc
	s_mov_b32 s5, 0xff800000
	v_max3_f32 v2, v0, s5, v1
	s_movk_i32 s5, 0x6f
	v_cmp_lt_i32_e32 vcc, s5, v14
	v_mul_f32_e32 v3, 0x3db504f3, v8
	s_or_b64 vcc, s[10:11], vcc
	s_movk_i32 s5, 0x6e
	v_cndmask_b32_e32 v3, v208, v3, vcc
	v_cmp_lt_i32_e32 vcc, s5, v14
	v_mul_f32_e32 v8, 0x3db504f3, v9
	s_or_b64 vcc, s[10:11], vcc
	s_movk_i32 s5, 0x6d
	v_cndmask_b32_e32 v8, v208, v8, vcc
	v_cmp_lt_i32_e32 vcc, s5, v14
	v_mul_f32_e32 v9, 0x3db504f3, v10
	s_or_b64 vcc, s[10:11], vcc
	s_movk_i32 s5, 0x6c
	v_cndmask_b32_e32 v9, v208, v9, vcc
	v_cmp_lt_i32_e32 vcc, s5, v14
	v_mul_f32_e32 v10, 0x3db504f3, v11
	s_or_b64 vcc, s[10:11], vcc
	s_movk_i32 s5, 0x5f
	v_cndmask_b32_e32 v10, v208, v10, vcc
	v_cmp_lt_i32_e32 vcc, s5, v14
	v_mul_f32_e32 v11, 0x3db504f3, v24
	s_or_b64 vcc, s[10:11], vcc
	s_movk_i32 s5, 0x5e
	v_cndmask_b32_e32 v11, v208, v11, vcc
	v_cmp_lt_i32_e32 vcc, s5, v14
	v_mul_f32_e32 v15, 0x3db504f3, v25
	s_or_b64 vcc, s[10:11], vcc
	s_movk_i32 s5, 0x5d
	v_cndmask_b32_e32 v15, v208, v15, vcc
	v_cmp_lt_i32_e32 vcc, s5, v14
	v_mul_f32_e32 v16, 0x3db504f3, v26
	s_or_b64 vcc, s[10:11], vcc
	s_movk_i32 s5, 0x5c
	v_cndmask_b32_e32 v16, v208, v16, vcc
	v_cmp_lt_i32_e32 vcc, s5, v14
	v_mul_f32_e32 v17, 0x3db504f3, v27
	s_or_b64 vcc, s[10:11], vcc
	s_movk_i32 s5, 0x4f
	v_cndmask_b32_e32 v17, v208, v17, vcc
	v_cmp_lt_i32_e32 vcc, s5, v14
	v_mul_f32_e32 v18, 0x3db504f3, v28
	s_or_b64 vcc, s[10:11], vcc
	s_movk_i32 s5, 0x4e
	v_cndmask_b32_e32 v18, v208, v18, vcc
	v_cmp_lt_i32_e32 vcc, s5, v14
	v_mul_f32_e32 v19, 0x3db504f3, v29
	s_or_b64 vcc, s[10:11], vcc
	s_movk_i32 s5, 0x4d
	v_cndmask_b32_e32 v19, v208, v19, vcc
	v_cmp_lt_i32_e32 vcc, s5, v14
	v_mul_f32_e32 v20, 0x3db504f3, v30
	s_or_b64 vcc, s[10:11], vcc
	s_movk_i32 s5, 0x4c
	v_cndmask_b32_e32 v20, v208, v20, vcc
	v_cmp_lt_i32_e32 vcc, s5, v14
	v_mul_f32_e32 v21, 0x3db504f3, v31
	s_or_b64 vcc, s[10:11], vcc
	v_cndmask_b32_e32 v28, v208, v21, vcc
	v_cmp_lt_i32_e32 vcc, 63, v14
	v_mul_f32_e32 v21, 0x3db504f3, v32
	s_or_b64 vcc, s[10:11], vcc
	v_cndmask_b32_e32 v54, v208, v21, vcc
	v_cmp_lt_i32_e32 vcc, 62, v14
	v_mul_f32_e32 v21, 0x3db504f3, v33
	s_or_b64 vcc, s[10:11], vcc
	v_cndmask_b32_e32 v55, v208, v21, vcc
	v_cmp_lt_i32_e32 vcc, 61, v14
	v_mul_f32_e32 v21, 0x3db504f3, v34
	s_or_b64 vcc, s[10:11], vcc
	v_cndmask_b32_e32 v73, v208, v21, vcc
	v_cmp_lt_i32_e32 vcc, 60, v14
	v_mul_f32_e32 v21, 0x3db504f3, v35
	s_or_b64 vcc, s[10:11], vcc
	v_cndmask_b32_e32 v74, v208, v21, vcc
	v_cmp_lt_i32_e32 vcc, 47, v14
	v_mul_f32_e32 v21, 0x3db504f3, v36
	s_or_b64 vcc, s[10:11], vcc
; __device__ __forceinline__ void pl32(unsigned a, unsigned b, unsigned& ra, unsigned& rb) { asm volatile("" : "+v"(b)); auto r = __builtin_amdgcn_permlane32_swap(a, b, false, false); ra = r[0]; rb = r[1]; asm volatile("" : "+v"(ra), "+v"(rb)); }
; __device__ __forceinline__ void pl16(unsigned a, unsigned b, unsigned& ra, unsigned& rb) { asm volatile("" : "+v"(b)); auto r = __builtin_amdgcn_permlane16_swap(a, b, false, false); ra = r[0]; rb = r[1]; asm volatile("" : "+v"(ra), "+v"(rb)); }
; __device__ __forceinline__ void dilated_block(const bf16_t* QKV, bf16_t* OG, float* LSE, LAS unsigned char* lds, int u, int tid) {
;     ...
;     float mx = -INFINITY;
; #pragma unroll
;     for (int jt = 0; jt < 9; ++jt)
; #pragma unroll
;         for (int i = 0; i < 4; ++i) { const int d = 128 + n16 - 16 * jt - 4 * slab - i, kk = i0 + 16 * jt + 4 * slab + i;
;             const bool ok = (d >= 0) && (d <= 128) && (nb > 0 || kk >= 128);
;             const float s = ok ? sacc[jt][i] * 0.08838834764831845f : -INFINITY; sacc[jt][i] = s; mx = fmaxf(mx, s); }
;     { unsigned x, y; pl16(__builtin_bit_cast(unsigned, mx), __builtin_bit_cast(unsigned, mx), x, y); mx = fmaxf(__builtin_bit_cast(float, x), __builtin_bit_cast(float, y));
;       pl32(__builtin_bit_cast(unsigned, mx), __builtin_bit_cast(unsigned, mx), x, y); mx = fmaxf(__builtin_bit_cast(float, x), __builtin_bit_cast(float, y)); }
;     float lsum = 0.f;
; #pragma unroll
;     for (int jt = 0; jt < 9; ++jt)
; #pragma unroll
;         for (int i = 0; i < 4; ++i) { const float pe = __expf(sacc[jt][i] - mx); sacc[jt][i] = pe; lsum += pe; }
	v_cndmask_b32_e32 v75, v208, v21, vcc
	v_cmp_lt_i32_e32 vcc, 46, v14
	v_mul_f32_e32 v21, 0x3db504f3, v37
	s_or_b64 vcc, s[10:11], vcc
	v_cndmask_b32_e32 v76, v208, v21, vcc
	v_cmp_lt_i32_e32 vcc, 45, v14
	v_mul_f32_e32 v21, 0x3db504f3, v38
	s_or_b64 vcc, s[10:11], vcc
	v_cndmask_b32_e32 v38, v208, v21, vcc
	v_cmp_lt_i32_e32 vcc, 44, v14
	v_mul_f32_e32 v21, 0x3db504f3, v39
	s_or_b64 vcc, s[10:11], vcc
	v_cndmask_b32_e32 v39, v208, v21, vcc
	v_cmp_lt_i32_e32 vcc, 31, v14
	v_mul_f32_e32 v21, 0x3db504f3, v40
	s_or_b64 vcc, s[10:11], vcc
	v_cndmask_b32_e32 v40, v208, v21, vcc
	v_cmp_lt_i32_e32 vcc, 30, v14
	v_mul_f32_e32 v21, 0x3db504f3, v41
	s_or_b64 vcc, s[10:11], vcc
	v_cndmask_b32_e32 v41, v208, v21, vcc
	v_cmp_lt_i32_e32 vcc, 29, v14
	v_mul_f32_e32 v21, 0x3db504f3, v42
	s_or_b64 vcc, s[10:11], vcc
	v_cndmask_b32_e32 v42, v208, v21, vcc
	v_cmp_lt_i32_e32 vcc, 28, v14
	v_mul_f32_e32 v21, 0x3db504f3, v43
	s_or_b64 vcc, s[10:11], vcc
	v_cndmask_b32_e32 v43, v208, v21, vcc
	v_cmp_lt_i32_e32 vcc, 15, v14
	v_mul_f32_e32 v21, 0x3db504f3, v44
	s_or_b64 vcc, s[10:11], vcc
	v_cndmask_b32_e32 v44, v208, v21, vcc
	v_cmp_lt_i32_e32 vcc, 14, v14
	v_mul_f32_e32 v21, 0x3db504f3, v45
	s_or_b64 vcc, s[10:11], vcc
	v_cndmask_b32_e32 v45, v208, v21, vcc
	v_cmp_lt_i32_e32 vcc, 13, v14
	v_mul_f32_e32 v21, 0x3db504f3, v46
	s_or_b64 vcc, s[10:11], vcc
	v_max3_f32 v2, v2, v13, v12
	v_cndmask_b32_e32 v46, v208, v21, vcc
	v_cmp_lt_i32_e32 vcc, 12, v14
	v_max3_f32 v2, v2, v3, v8
	s_or_b64 vcc, s[10:11], vcc
	v_max3_f32 v2, v2, v9, v10
	s_cmp_gt_i32 s22, -1
	v_max3_f32 v2, v2, v11, v15
	s_cselect_b64 s[16:17], -1, 0
	v_max3_f32 v2, v2, v16, v17
	v_mul_f32_e32 v21, 0x3db504f3, v47
	s_or_b64 s[16:17], s[10:11], s[16:17]
	v_max3_f32 v2, v2, v18, v19
	v_cndmask_b32_e32 v47, v208, v21, vcc
	v_mul_f32_e32 v4, 0x3db504f3, v4
	s_and_b64 vcc, s[46:47], s[16:17]
	v_max3_f32 v2, v2, v20, v28
	v_cndmask_b32_e32 v4, v208, v4, vcc
	v_cmp_lt_i32_e32 vcc, -2, v14
	v_max3_f32 v2, v2, v54, v55
	s_or_b64 s[16:17], s[10:11], vcc
	v_max3_f32 v2, v2, v73, v74
	v_mul_f32_e32 v5, 0x3db504f3, v5
	s_and_b64 vcc, s[48:49], s[16:17]
	v_max3_f32 v2, v2, v75, v76
	v_cndmask_b32_e32 v77, v208, v5, vcc
	v_cmp_lt_i32_e32 vcc, -3, v14
	v_max3_f32 v2, v2, v38, v39
	s_or_b64 s[16:17], s[10:11], vcc
	v_max3_f32 v2, v2, v40, v41
	v_mul_f32_e32 v5, 0x3db504f3, v6
	s_and_b64 vcc, s[50:51], s[16:17]
	v_max3_f32 v2, v2, v42, v43
	v_cndmask_b32_e32 v78, v208, v5, vcc
	v_cmp_lt_i32_e32 vcc, -4, v14
	v_max3_f32 v2, v2, v44, v45
	s_or_b64 s[10:11], s[10:11], vcc
	v_max3_f32 v2, v2, v46, v47
	v_mul_f32_e32 v5, 0x3db504f3, v7
	s_and_b64 vcc, s[52:53], s[10:11]
	v_max3_f32 v2, v2, v4, v77
	v_cndmask_b32_e32 v79, v208, v5, vcc
	v_max3_f32 v2, v2, v78, v79
	v_mov_b32_e32 v5, v2
	v_ashrrev_i32_e32 v53, 31, v52
	s_nop 0
	v_permlane16_swap_b32_e32 v2, v5
	s_nop 0
	v_max_f32_e32 v5, v5, v5
	v_max_f32_e32 v2, v2, v2
	v_max_f32_e32 v2, v2, v5
	v_mov_b32_e32 v5, v2
	s_nop 1
	v_permlane32_swap_b32_e32 v2, v5
	s_nop 0
	v_max_f32_e32 v5, v5, v5
	v_max_f32_e32 v2, v2, v2
	v_max_f32_e32 v37, v2, v5
	v_sub_f32_e32 v0, v0, v37
	v_mul_f32_e32 v0, 0x3fb8aa3b, v0
	v_exp_f32_e32 v29, v0
	v_sub_f32_e32 v0, v1, v37
	v_sub_f32_e32 v1, v3, v37
	v_mul_f32_e32 v1, 0x3fb8aa3b, v1
	v_exp_f32_e32 v32, v1
	v_sub_f32_e32 v1, v8, v37
	v_mul_f32_e32 v1, 0x3fb8aa3b, v1
	v_exp_f32_e32 v35, v1
	v_sub_f32_e32 v1, v9, v37
	v_mul_f32_e32 v1, 0x3fb8aa3b, v1
	v_exp_f32_e32 v34, v1
	v_sub_f32_e32 v1, v10, v37
	v_mul_f32_e32 v1, 0x3fb8aa3b, v1
	v_exp_f32_e32 v36, v1
	v_sub_f32_e32 v1, v11, v37
	v_mul_f32_e32 v1, 0x3fb8aa3b, v1
	v_exp_f32_e32 v21, v1
	v_sub_f32_e32 v1, v15, v37
	v_mul_f32_e32 v1, 0x3fb8aa3b, v1
	v_exp_f32_e32 v23, v1
	v_sub_f32_e32 v1, v16, v37
	v_mul_f32_e32 v1, 0x3fb8aa3b, v1
	v_exp_f32_e32 v22, v1
	v_sub_f32_e32 v1, v17, v37
	v_mul_f32_e32 v1, 0x3fb8aa3b, v1
	v_exp_f32_e32 v25, v1
	v_sub_f32_e32 v1, v18, v37
	v_mul_f32_e32 v1, 0x3fb8aa3b, v1
	v_exp_f32_e32 v24, v1
	v_sub_f32_e32 v1, v19, v37
	v_mul_f32_e32 v1, 0x3fb8aa3b, v1
	v_exp_f32_e32 v27, v1
	v_sub_f32_e32 v1, v20, v37
; __device__ __forceinline__ void pl32(unsigned a, unsigned b, unsigned& ra, unsigned& rb) { asm volatile("" : "+v"(b)); auto r = __builtin_amdgcn_permlane32_swap(a, b, false, false); ra = r[0]; rb = r[1]; asm volatile("" : "+v"(ra), "+v"(rb)); }
; __device__ __forceinline__ void pl16(unsigned a, unsigned b, unsigned& ra, unsigned& rb) { asm volatile("" : "+v"(b)); auto r = __builtin_amdgcn_permlane16_swap(a, b, false, false); ra = r[0]; rb = r[1]; asm volatile("" : "+v"(ra), "+v"(rb)); }
; __device__ __forceinline__ float swap32_sum(float a, float b) { unsigned x, y; pl32(__builtin_bit_cast(unsigned, a), __builtin_bit_cast(unsigned, b), x, y); return __builtin_bit_cast(float, x) + __builtin_bit_cast(float, y); }
; __device__ __forceinline__ float swap16_sum(float a, float b) { unsigned x, y; pl16(__builtin_bit_cast(unsigned, a), __builtin_bit_cast(unsigned, b), x, y); return __builtin_bit_cast(float, x) + __builtin_bit_cast(float, y); }
; __device__ __forceinline__ void dilated_block(const bf16_t* QKV, bf16_t* OG, float* LSE, LAS unsigned char* lds, int u, int tid) {
;     ...
;     { unsigned x, y; pl16(__builtin_bit_cast(unsigned, mx), __builtin_bit_cast(unsigned, mx), x, y); mx = fmaxf(__builtin_bit_cast(float, x), __builtin_bit_cast(float, y));
;       pl32(__builtin_bit_cast(unsigned, mx), __builtin_bit_cast(unsigned, mx), x, y); mx = fmaxf(__builtin_bit_cast(float, x), __builtin_bit_cast(float, y)); }
;     float lsum = 0.f;
; #pragma unroll
;     for (int jt = 0; jt < 9; ++jt)
; #pragma unroll
;         for (int i = 0; i < 4; ++i) { const float pe = __expf(sacc[jt][i] - mx); sacc[jt][i] = pe; lsum += pe; }
;     sacc[9] = (f32x4){0.f, 0.f, 0.f, 0.f};
;     lsum = swap16_sum(lsum, lsum); lsum = swap32_sum(lsum, lsum);
;     if (slab == 0) LSE[(size_t)tq * 12 + head] = mx + __logf(lsum);
	v_mul_f32_e32 v1, 0x3fb8aa3b, v1
	v_exp_f32_e32 v26, v1
	v_sub_f32_e32 v1, v28, v37
	v_mul_f32_e32 v1, 0x3fb8aa3b, v1
	v_exp_f32_e32 v28, v1
	v_sub_f32_e32 v1, v54, v37
	v_mul_f32_e32 v0, 0x3fb8aa3b, v0
	v_mul_f32_e32 v1, 0x3fb8aa3b, v1
	v_exp_f32_e32 v31, v0
	v_sub_f32_e32 v0, v13, v37
	v_exp_f32_e32 v13, v1
	v_sub_f32_e32 v1, v55, v37
	v_mul_f32_e32 v0, 0x3fb8aa3b, v0
	v_mul_f32_e32 v1, 0x3fb8aa3b, v1
	v_exp_f32_e32 v30, v0
	v_sub_f32_e32 v0, v12, v37
	v_exp_f32_e32 v15, v1
	v_sub_f32_e32 v1, v73, v37
	v_mul_f32_e32 v0, 0x3fb8aa3b, v0
	v_mul_f32_e32 v1, 0x3fb8aa3b, v1
	v_exp_f32_e32 v33, v0
	v_exp_f32_e32 v14, v1
	v_sub_f32_e32 v1, v74, v37
	v_add_f32_e32 v0, 0, v29
	v_mul_f32_e32 v1, 0x3fb8aa3b, v1
	v_add_f32_e32 v0, v31, v0
	v_exp_f32_e32 v17, v1
	v_sub_f32_e32 v1, v75, v37
	v_add_f32_e32 v0, v30, v0
	v_mul_f32_e32 v1, 0x3fb8aa3b, v1
	v_add_f32_e32 v0, v33, v0
	v_exp_f32_e32 v16, v1
	v_sub_f32_e32 v1, v76, v37
	v_add_f32_e32 v0, v32, v0
	v_mul_f32_e32 v1, 0x3fb8aa3b, v1
	v_add_f32_e32 v0, v35, v0
	v_exp_f32_e32 v19, v1
	v_sub_f32_e32 v1, v38, v37
	v_add_f32_e32 v0, v34, v0
	v_mul_f32_e32 v1, 0x3fb8aa3b, v1
	v_add_f32_e32 v0, v36, v0
	v_exp_f32_e32 v18, v1
	v_sub_f32_e32 v1, v39, v37
	v_add_f32_e32 v0, v21, v0
	v_mul_f32_e32 v1, 0x3fb8aa3b, v1
	v_add_f32_e32 v0, v23, v0
	v_exp_f32_e32 v20, v1
	v_sub_f32_e32 v1, v40, v37
	v_add_f32_e32 v0, v22, v0
	v_mul_f32_e32 v1, 0x3fb8aa3b, v1
	v_add_f32_e32 v0, v25, v0
	v_exp_f32_e32 v5, v1
	v_sub_f32_e32 v1, v41, v37
	v_add_f32_e32 v0, v24, v0
	v_mul_f32_e32 v1, 0x3fb8aa3b, v1
	v_add_f32_e32 v0, v27, v0
	v_exp_f32_e32 v7, v1
	v_sub_f32_e32 v1, v42, v37
	v_add_f32_e32 v0, v26, v0
	v_mul_f32_e32 v1, 0x3fb8aa3b, v1
	v_add_f32_e32 v0, v28, v0
	v_exp_f32_e32 v6, v1
	v_sub_f32_e32 v1, v43, v37
	v_add_f32_e32 v0, v13, v0
	v_mul_f32_e32 v1, 0x3fb8aa3b, v1
	v_add_f32_e32 v0, v15, v0
	v_exp_f32_e32 v9, v1
	v_sub_f32_e32 v1, v44, v37
	v_add_f32_e32 v0, v14, v0
	v_mul_f32_e32 v1, 0x3fb8aa3b, v1
	v_add_f32_e32 v0, v17, v0
	v_exp_f32_e32 v8, v1
	v_sub_f32_e32 v1, v45, v37
	v_add_f32_e32 v0, v16, v0
	v_mul_f32_e32 v1, 0x3fb8aa3b, v1
	v_add_f32_e32 v0, v19, v0
	v_exp_f32_e32 v11, v1
	v_sub_f32_e32 v1, v46, v37
	v_add_f32_e32 v0, v18, v0
	v_mul_f32_e32 v1, 0x3fb8aa3b, v1
	v_add_f32_e32 v0, v20, v0
	v_exp_f32_e32 v10, v1
	v_sub_f32_e32 v1, v47, v37
	v_add_f32_e32 v0, v5, v0
	v_mul_f32_e32 v1, 0x3fb8aa3b, v1
	v_add_f32_e32 v0, v7, v0
	v_exp_f32_e32 v12, v1
	v_sub_f32_e32 v1, v4, v37
	v_add_f32_e32 v0, v6, v0
	v_mul_f32_e32 v1, 0x3fb8aa3b, v1
	v_add_f32_e32 v0, v9, v0
	v_exp_f32_e32 v2, v1
	v_sub_f32_e32 v1, v77, v37
	v_add_f32_e32 v0, v8, v0
	v_mul_f32_e32 v1, 0x3fb8aa3b, v1
	v_sub_f32_e32 v3, v78, v37
	v_add_f32_e32 v0, v11, v0
	v_exp_f32_e32 v1, v1
	v_mul_f32_e32 v3, 0x3fb8aa3b, v3
	v_sub_f32_e32 v4, v79, v37
	v_add_f32_e32 v0, v10, v0
	v_exp_f32_e32 v3, v3
	v_mul_f32_e32 v4, 0x3fb8aa3b, v4
	v_add_f32_e32 v0, v12, v0
	v_exp_f32_e32 v4, v4
	v_add_f32_e32 v0, v2, v0
	v_add_f32_e32 v0, v1, v0
	v_add_f32_e32 v0, v3, v0
	v_add_f32_e32 v0, v4, v0
	v_mov_b32_e32 v38, v0
	s_nop 1
	v_permlane16_swap_b32_e32 v0, v38
	s_nop 0
	v_add_f32_e32 v0, v0, v38
	v_mov_b32_e32 v38, v0
	s_nop 1
	v_permlane32_swap_b32_e32 v0, v38
	s_nop 0
	v_add_f32_e32 v0, v0, v38
	s_and_saveexec_b64 s[10:11], s[54:55]
	s_cbranch_execz .LBB0_196
	s_mov_b32 s5, 0x800000
	v_cmp_gt_f32_e32 vcc, s5, v0
	s_mov_b32 s5, 0x3f317217
	v_readlane_b32 s16, v251, 19
	v_cndmask_b32_e64 v38, 0, 32, vcc
	v_ldexp_f32 v38, v0, v38
	v_log_f32_e32 v38, v38
	v_cndmask_b32_e32 v39, 0, v209, vcc
	v_readlane_b32 s17, v251, 20
	v_mul_f32_e32 v40, 0x3f317217, v38
	v_fma_f32 v40, v38, s5, -v40
	v_fmac_f32_e32 v40, 0x3377d1cf, v38
	s_mov_b32 s5, 0x7f800000
	v_fmac_f32_e32 v40, 0x3f317217, v38
	v_cmp_lt_f32_e64 vcc, |v38|, s5
	s_ashr_i32 s5, s4, 31
	s_nop 0
	v_cndmask_b32_e32 v38, v38, v40, vcc
	v_sub_f32_e32 v38, v38, v39
	v_add_f32_e32 v37, v37, v38
	v_mad_i64_i32 v[38:39], s[16:17], v52, 48, s[16:17]
	v_lshl_add_u64 v[38:39], s[4:5], 2, v[38:39]
	global_store_dword v[38:39], v37, off
	s_branch .LBB0_196

; __device__ __forceinline__ void indexer_unit(const bf16_t* IQ, const bf16_t* IK, const float* IW, unsigned short* SEL, LAS unsigned char* wlds, int t0, int lane) {
;     ...
;     for (int q = 0; q < NQI; ++q) { const size_t t = (size_t)(t0 + q);
;         a0[q] = *(const bf16x8*)(IQ + t * 1024 + n16 * 64 + slab * 8); a1[q] = *(const bf16x8*)(IQ + t * 1024 + n16 * 64 + 32 + slab * 8);
;         const f32x4 wv = *(const f32x4*)(IW + t * 16 + slab * 4); const h4_t wh = {(_Float16)wv[0], (_Float16)wv[1], (_Float16)wv[2], (_Float16)wv[3]};
;         const h4_t hz = {(_Float16)0, (_Float16)0, (_Float16)0, (_Float16)0};
; #pragma unroll
;         for (int g = 0; g < 4; ++g) wa[q][g] = (n16 == 4 * g) ? wh : hz;
;         cnt[q] = 0; tau[q] = -INFINITY; }
;     const int nkb = t0 / 64 + 1;
; #pragma unroll
;     for (int q = 0; q < NQI; ++q) asm volatile("" :: "v"(a0[q]), "v"(a1[q]), "v"(wa[q][0]), "v"(wa[q][1]), "v"(wa[q][2]), "v"(wa[q][3]));
;     bf16x8 fa[8], fb[8];
; #pragma unroll
;     for (int i = 0; i < 8; ++i) { fa[i] = (bf16x8){0, 0, 0, 0, 0, 0, 0, 0}; fb[i] = fa[i]; }
;     idx_load(fa, IK, 0, n16, slab);
; #pragma unroll 1
;     for (int kb = 0; kb < nkb; kb += 2) {
;         idx_load(fb, IK, min(kb + 1, nkb - 1), n16, slab);
.Lix_noinit:
	s_lshr_b32 s0, s82, 4
	s_add_i32 m0, s0, 147456
	s_nop 0
	global_load_lds_dwordx4 v185, s[76:77]
	v_subrev_u32_e32 v116, 64, v182
	v_mov_b32_e32 v100, v208
	v_mov_b32_e32 v104, v208
	v_mov_b32_e32 v108, v208
	v_mov_b32_e32 v112, v208
	s_waitcnt vmcnt(1)
	v_cvt_pk_f16_f32 v190, v224, v225
	v_cvt_pk_f16_f32 v191, v226, v227
	s_nop 0
	v_cndmask_b32_e64 v32, 0, v190, s[8:9]
	v_cndmask_b32_e64 v33, 0, v191, s[8:9]
	v_cndmask_b32_e64 v34, 0, v190, s[10:11]
	v_cndmask_b32_e64 v35, 0, v191, s[10:11]
	v_cndmask_b32_e64 v36, 0, v190, s[16:17]
	v_cndmask_b32_e64 v37, 0, v191, s[16:17]
	v_cndmask_b32_e64 v38, 0, v190, s[22:23]
	v_cndmask_b32_e64 v39, 0, v191, s[22:23]
	v_cvt_pk_f16_f32 v190, v228, v229
	v_cvt_pk_f16_f32 v191, v230, v231
	s_nop 0
	v_cndmask_b32_e64 v40, 0, v190, s[8:9]
	v_cndmask_b32_e64 v41, 0, v191, s[8:9]
	v_cndmask_b32_e64 v42, 0, v190, s[10:11]
	v_cndmask_b32_e64 v43, 0, v191, s[10:11]
	v_cndmask_b32_e64 v44, 0, v190, s[16:17]
	v_cndmask_b32_e64 v45, 0, v191, s[16:17]
	v_cndmask_b32_e64 v46, 0, v190, s[22:23]
	v_cndmask_b32_e64 v47, 0, v191, s[22:23]
	v_cvt_pk_f16_f32 v190, v232, v233
	v_cvt_pk_f16_f32 v191, v234, v235
	s_nop 0
	v_cndmask_b32_e64 v48, 0, v190, s[8:9]
	v_cndmask_b32_e64 v49, 0, v191, s[8:9]
	v_cndmask_b32_e64 v50, 0, v190, s[10:11]
	v_cndmask_b32_e64 v51, 0, v191, s[10:11]
	v_cndmask_b32_e64 v52, 0, v190, s[16:17]
	v_cndmask_b32_e64 v53, 0, v191, s[16:17]
	v_cndmask_b32_e64 v54, 0, v190, s[22:23]
	v_cndmask_b32_e64 v55, 0, v191, s[22:23]
	v_cvt_pk_f16_f32 v190, v236, v237
	v_cvt_pk_f16_f32 v191, v238, v239
	s_nop 0
	v_cndmask_b32_e64 v56, 0, v190, s[8:9]
	v_cndmask_b32_e64 v57, 0, v191, s[8:9]
	v_cndmask_b32_e64 v58, 0, v190, s[10:11]
	v_cndmask_b32_e64 v59, 0, v191, s[10:11]
	v_cndmask_b32_e64 v60, 0, v190, s[16:17]
	v_cndmask_b32_e64 v61, 0, v191, s[16:17]
	v_cndmask_b32_e64 v62, 0, v190, s[22:23]
	v_cndmask_b32_e64 v63, 0, v191, s[22:23]

; #define LAS __attribute__((address_space(3)))
; __device__ __forceinline__ int lane_prefix(unsigned long long mask) { return __builtin_amdgcn_mbcnt_hi((unsigned)(mask >> 32), __builtin_amdgcn_mbcnt_lo((unsigned)mask, 0)); }
; __device__ __forceinline__ float idx_score(const bf16x8 (&f)[8], const bf16x8 a0, const bf16x8 a1, const h4_t (&wa)[4]) {
;     f32x4 s = {0.f, 0.f, 0.f, 0.f}; const h2_t z = {(_Float16)0, (_Float16)0};
; #pragma unroll
;     for (int g = 0; g < 4; ++g) {
;         f32x4 acc = {0.f, 0.f, 0.f, 0.f};
;         acc = __builtin_amdgcn_mfma_f32_16x16x32_bf16(a0, f[2 * g], acc, 0, 0, 0);
;         acc = __builtin_amdgcn_mfma_f32_16x16x32_bf16(a1, f[2 * g + 1], acc, 0, 0, 0);
;         h2_t lo = {(_Float16)acc[0], (_Float16)acc[1]}, hi = {(_Float16)acc[2], (_Float16)acc[3]};
;         lo = __builtin_elementwise_max(lo, z); hi = __builtin_elementwise_max(hi, z);
;         const h4_t bb = {lo[0], lo[1], hi[0], hi[1]};
;         s = __builtin_amdgcn_mfma_f32_16x16x16f16(wa[g], bb, s, 0, 0, 0);
;     }
;     return s[0];
; }
; __device__ __forceinline__ void idx_append(float score, LAS float* bs, LAS unsigned* bi, int& cnt, float& tau, int kb, int t, int lane) {
;     const int kidx = kb * 64 + lane;
;     const bool valid = (kidx <= t) && (score > tau);
;     const unsigned long long vm = __ballot(valid); const int pos = cnt + lane_prefix(vm);
;     if (valid) { bs[pos] = score; bi[pos] = (unsigned)kidx; }
;     cnt += __popcll(vm);
;     __builtin_amdgcn_wave_barrier();
;     if (cnt > ICAP - 64) idx_compact(bs, bi, cnt, tau, lane);
; }
.Lix_ncq0_3:
.Lix_nocomp0:
	v_mfma_f32_16x16x32_bf16 v[144:147], v[0:3], v[64:67], 0
	v_mfma_f32_16x16x32_bf16 v[144:147], v[16:19], v[68:71], v[144:147]
	v_mfma_f32_16x16x32_bf16 v[148:151], v[0:3], v[72:75], 0
	v_mfma_f32_16x16x32_bf16 v[148:151], v[16:19], v[76:79], v[148:151]
	v_mfma_f32_16x16x32_bf16 v[152:155], v[0:3], v[80:83], 0
	v_mfma_f32_16x16x32_bf16 v[152:155], v[16:19], v[84:87], v[152:155]
	v_mfma_f32_16x16x32_bf16 v[156:159], v[0:3], v[88:91], 0
	s_nop 2
	v_cvt_pk_f16_f32 v196, v144, v145
	v_cvt_pk_f16_f32 v197, v146, v147
	v_mfma_f32_16x16x32_bf16 v[156:159], v[16:19], v[92:95], v[156:159]
	v_pk_max_f16 v196, v196, 0
	v_pk_max_f16 v197, v197, 0
	v_cmp_lt_f32_e64 s[0:1], s58, v100
	s_cmp_eq_u64 s[0:1], 0
	s_cbranch_scc1 .Lix_skip0
	s_mov_b64 s[4:5], exec
	s_mov_b64 exec, s[0:1]
	v_mbcnt_lo_u32_b32 v190, s0, 0
	v_mbcnt_hi_u32_b32 v190, s1, v190
	v_add_u32_e32 v190, s52, v190
	v_lshl_add_u32 v190, v190, 2, s82
	ds_write2st64_b32 v190, v100, v116 offset0:0 offset1:8
	s_mov_b64 exec, s[4:5]
	s_bcnt1_i32_b64 s0, s[0:1]
	s_add_i32 s52, s52, s0
.Lix_skip0:
	v_mfma_f32_16x16x32_bf16 v[144:147], v[4:7], v[64:67], 0
	v_cvt_pk_f16_f32 v198, v148, v149
	v_cvt_pk_f16_f32 v199, v150, v151
	v_mfma_f32_16x16x32_bf16 v[144:147], v[20:23], v[68:71], v[144:147]
	v_pk_max_f16 v198, v198, 0
	v_pk_max_f16 v199, v199, 0
	v_mfma_f32_16x16x32_bf16 v[148:151], v[4:7], v[72:75], 0
	v_cvt_pk_f16_f32 v200, v152, v153
	v_cvt_pk_f16_f32 v201, v154, v155
	v_mfma_f32_16x16x32_bf16 v[148:151], v[20:23], v[76:79], v[148:151]
	v_pk_max_f16 v200, v200, 0
	v_pk_max_f16 v201, v201, 0
	v_mfma_f32_16x16x32_f16 v[128:131], v[32:35], v[196:199], 0
	v_mfma_f32_16x16x32_bf16 v[152:155], v[4:7], v[80:83], 0
	v_cvt_pk_f16_f32 v202, v156, v157
	v_cvt_pk_f16_f32 v203, v158, v159
	v_mfma_f32_16x16x32_bf16 v[152:155], v[20:23], v[84:87], v[152:155]
	v_pk_max_f16 v202, v202, 0
	v_pk_max_f16 v203, v203, 0
	v_mfma_f32_16x16x32_bf16 v[156:159], v[4:7], v[88:91], 0
	v_cvt_pk_f16_f32 v196, v144, v145
	v_cvt_pk_f16_f32 v197, v146, v147
	v_mfma_f32_16x16x32_bf16 v[156:159], v[20:23], v[92:95], v[156:159]
	v_pk_max_f16 v196, v196, 0
	v_pk_max_f16 v197, v197, 0
	v_mfma_f32_16x16x32_f16 v[128:131], v[36:39], v[200:203], v[128:131]
	v_cmp_lt_f32_e64 s[0:1], s59, v104
	s_cmp_eq_u64 s[0:1], 0
	s_cbranch_scc1 .Lix_skip1
	s_mov_b64 s[4:5], exec
	s_mov_b64 exec, s[0:1]
	v_mbcnt_lo_u32_b32 v190, s0, 0
	v_mbcnt_hi_u32_b32 v190, s1, v190
	v_add_u32_e32 v190, s53, v190
	v_lshl_add_u32 v190, v190, 2, s82
	ds_write2st64_b32 v190, v104, v116 offset0:16 offset1:24
	s_mov_b64 exec, s[4:5]
	s_bcnt1_i32_b64 s0, s[0:1]
	s_add_i32 s53, s53, s0
.Lix_skip1:
	v_mfma_f32_16x16x32_bf16 v[144:147], v[8:11], v[64:67], 0
	v_cvt_pk_f16_f32 v198, v148, v149
	v_cvt_pk_f16_f32 v199, v150, v151
	v_mfma_f32_16x16x32_bf16 v[144:147], v[24:27], v[68:71], v[144:147]
	v_pk_max_f16 v198, v198, 0
	v_pk_max_f16 v199, v199, 0
	v_mfma_f32_16x16x32_bf16 v[148:151], v[8:11], v[72:75], 0
	v_cvt_pk_f16_f32 v200, v152, v153
	v_cvt_pk_f16_f32 v201, v154, v155
	v_mfma_f32_16x16x32_bf16 v[148:151], v[24:27], v[76:79], v[148:151]
	v_pk_max_f16 v200, v200, 0
	v_pk_max_f16 v201, v201, 0
	v_mfma_f32_16x16x32_f16 v[132:135], v[40:43], v[196:199], 0
	v_mfma_f32_16x16x32_bf16 v[152:155], v[8:11], v[80:83], 0
	v_cvt_pk_f16_f32 v202, v156, v157
	v_cvt_pk_f16_f32 v203, v158, v159
	v_mfma_f32_16x16x32_bf16 v[152:155], v[24:27], v[84:87], v[152:155]
	v_pk_max_f16 v202, v202, 0
	v_pk_max_f16 v203, v203, 0
	v_mfma_f32_16x16x32_bf16 v[156:159], v[8:11], v[88:91], 0
	v_cvt_pk_f16_f32 v196, v144, v145
	v_cvt_pk_f16_f32 v197, v146, v147
	v_mfma_f32_16x16x32_bf16 v[156:159], v[24:27], v[92:95], v[156:159]
	v_pk_max_f16 v196, v196, 0
	v_pk_max_f16 v197, v197, 0
	v_mfma_f32_16x16x32_f16 v[132:135], v[44:47], v[200:203], v[132:135]
	v_cmp_lt_f32_e64 s[0:1], s60, v108
	s_cmp_eq_u64 s[0:1], 0
	s_cbranch_scc1 .Lix_skip2
	s_mov_b64 s[4:5], exec
	s_mov_b64 exec, s[0:1]
	v_mbcnt_lo_u32_b32 v190, s0, 0
	v_mbcnt_hi_u32_b32 v190, s1, v190
	v_add_u32_e32 v190, s54, v190
	v_lshl_add_u32 v190, v190, 2, s82
	ds_write2st64_b32 v190, v108, v116 offset0:32 offset1:40
	s_mov_b64 exec, s[4:5]
	s_bcnt1_i32_b64 s0, s[0:1]
	s_add_i32 s54, s54, s0
.Lix_skip2:
	v_mfma_f32_16x16x32_bf16 v[144:147], v[12:15], v[64:67], 0
	v_cvt_pk_f16_f32 v198, v148, v149
	v_cvt_pk_f16_f32 v199, v150, v151
	v_mfma_f32_16x16x32_bf16 v[144:147], v[28:31], v[68:71], v[144:147]
	v_pk_max_f16 v198, v198, 0
	v_pk_max_f16 v199, v199, 0
	v_mfma_f32_16x16x32_bf16 v[148:151], v[12:15], v[72:75], 0
	v_cvt_pk_f16_f32 v200, v152, v153
	v_cvt_pk_f16_f32 v201, v154, v155
	v_mfma_f32_16x16x32_bf16 v[148:151], v[28:31], v[76:79], v[148:151]
	v_pk_max_f16 v200, v200, 0
	v_pk_max_f16 v201, v201, 0
	v_mfma_f32_16x16x32_f16 v[136:139], v[48:51], v[196:199], 0
	v_mfma_f32_16x16x32_bf16 v[152:155], v[12:15], v[80:83], 0
	v_cvt_pk_f16_f32 v202, v156, v157
	v_cvt_pk_f16_f32 v203, v158, v159
	v_mfma_f32_16x16x32_bf16 v[152:155], v[28:31], v[84:87], v[152:155]
	v_pk_max_f16 v202, v202, 0
	v_pk_max_f16 v203, v203, 0
	v_mfma_f32_16x16x32_bf16 v[156:159], v[12:15], v[88:91], 0
	v_cvt_pk_f16_f32 v196, v144, v145
	v_cvt_pk_f16_f32 v197, v146, v147
	v_mfma_f32_16x16x32_bf16 v[156:159], v[28:31], v[92:95], v[156:159]
	v_pk_max_f16 v196, v196, 0
	v_pk_max_f16 v197, v197, 0
	v_mfma_f32_16x16x32_f16 v[136:139], v[52:55], v[200:203], v[136:139]
	v_cmp_lt_f32_e64 s[0:1], s61, v112
	s_cmp_eq_u64 s[0:1], 0
	s_cbranch_scc1 .Lix_skip3
	s_mov_b64 s[4:5], exec
	s_mov_b64 exec, s[0:1]
	v_mbcnt_lo_u32_b32 v190, s0, 0
	v_mbcnt_hi_u32_b32 v190, s1, v190
	v_add_u32_e32 v190, s55, v190
	v_lshl_add_u32 v190, v190, 2, s82
	ds_write2st64_b32 v190, v112, v116 offset0:48 offset1:56
	s_mov_b64 exec, s[4:5]
	s_bcnt1_i32_b64 s0, s[0:1]
	s_add_i32 s55, s55, s0
.Lix_skip3:
	v_cvt_pk_f16_f32 v198, v148, v149
	v_cvt_pk_f16_f32 v199, v150, v151
	v_pk_max_f16 v198, v198, 0
	v_pk_max_f16 v199, v199, 0
	v_cvt_pk_f16_f32 v200, v152, v153
	v_cvt_pk_f16_f32 v201, v154, v155
	v_pk_max_f16 v200, v200, 0
	v_pk_max_f16 v201, v201, 0
	v_mfma_f32_16x16x32_f16 v[140:143], v[56:59], v[196:199], 0
	v_cvt_pk_f16_f32 v202, v156, v157
	v_cvt_pk_f16_f32 v203, v158, v159
	v_pk_max_f16 v202, v202, 0
	v_pk_max_f16 v203, v203, 0
	s_nop 1
	v_mfma_f32_16x16x32_f16 v[140:143], v[60:63], v[200:203], v[140:143]
	v_add_u32_e32 v116, 64, v116
	s_mov_b32 s0, 0
	s_cmpk_gt_i32 s52, 0x1c0
	s_cselect_b32 s1, 1, 0
	s_or_b32 s0, s0, s1
	s_cmpk_gt_i32 s53, 0x1c0
	s_cselect_b32 s1, 2, 0
	s_or_b32 s0, s0, s1
	s_cmpk_gt_i32 s54, 0x1c0
	s_cselect_b32 s1, 4, 0
	s_or_b32 s0, s0, s1
	s_cmpk_gt_i32 s55, 0x1c0
	s_cselect_b32 s1, 8, 0
	s_or_b32 s0, s0, s1
	s_cmp_eq_u32 s0, 0
	s_cbranch_scc1 .Lix_noreq0
	v_mov_b32_e32 v190, s101
	v_mov_b32_e32 v191, s0
	s_mov_b64 s[4:5], exec
	s_mov_b64 exec, 1
	ds_or_b32 v190, v191
	s_mov_b64 exec, s[4:5]
	s_waitcnt lgkmcnt(0)

; #define LAS __attribute__((address_space(3)))
; __device__ __forceinline__ int lane_prefix(unsigned long long mask) { return __builtin_amdgcn_mbcnt_hi((unsigned)(mask >> 32), __builtin_amdgcn_mbcnt_lo((unsigned)mask, 0)); }
; __device__ __forceinline__ float idx_score(const bf16x8 (&f)[8], const bf16x8 a0, const bf16x8 a1, const h4_t (&wa)[4]) {
;     f32x4 s = {0.f, 0.f, 0.f, 0.f}; const h2_t z = {(_Float16)0, (_Float16)0};
; #pragma unroll
;     for (int g = 0; g < 4; ++g) {
;         f32x4 acc = {0.f, 0.f, 0.f, 0.f};
;         acc = __builtin_amdgcn_mfma_f32_16x16x32_bf16(a0, f[2 * g], acc, 0, 0, 0);
;         acc = __builtin_amdgcn_mfma_f32_16x16x32_bf16(a1, f[2 * g + 1], acc, 0, 0, 0);
;         h2_t lo = {(_Float16)acc[0], (_Float16)acc[1]}, hi = {(_Float16)acc[2], (_Float16)acc[3]};
;         lo = __builtin_elementwise_max(lo, z); hi = __builtin_elementwise_max(hi, z);
;         const h4_t bb = {lo[0], lo[1], hi[0], hi[1]};
;         s = __builtin_amdgcn_mfma_f32_16x16x16f16(wa[g], bb, s, 0, 0, 0);
;     }
;     return s[0];
; }
; __device__ __forceinline__ void idx_append(float score, LAS float* bs, LAS unsigned* bi, int& cnt, float& tau, int kb, int t, int lane) {
;     const int kidx = kb * 64 + lane;
;     const bool valid = (kidx <= t) && (score > tau);
;     const unsigned long long vm = __ballot(valid); const int pos = cnt + lane_prefix(vm);
;     if (valid) { bs[pos] = score; bi[pos] = (unsigned)kidx; }
;     cnt += __popcll(vm);
;     __builtin_amdgcn_wave_barrier();
;     if (cnt > ICAP - 64) idx_compact(bs, bi, cnt, tau, lane);
; }
.Lix_ncq1_3:
.Lix_nocomp1:
	v_mfma_f32_16x16x32_bf16 v[144:147], v[0:3], v[64:67], 0
	v_mfma_f32_16x16x32_bf16 v[144:147], v[16:19], v[68:71], v[144:147]
	v_mfma_f32_16x16x32_bf16 v[148:151], v[0:3], v[72:75], 0
	v_mfma_f32_16x16x32_bf16 v[148:151], v[16:19], v[76:79], v[148:151]
	v_mfma_f32_16x16x32_bf16 v[152:155], v[0:3], v[80:83], 0
	v_mfma_f32_16x16x32_bf16 v[152:155], v[16:19], v[84:87], v[152:155]
	v_mfma_f32_16x16x32_bf16 v[156:159], v[0:3], v[88:91], 0
	s_nop 2
	v_cvt_pk_f16_f32 v196, v144, v145
	v_cvt_pk_f16_f32 v197, v146, v147
	v_mfma_f32_16x16x32_bf16 v[156:159], v[16:19], v[92:95], v[156:159]
	v_pk_max_f16 v196, v196, 0
	v_pk_max_f16 v197, v197, 0
	v_cmp_lt_f32_e64 s[0:1], s58, v128
	s_cmp_eq_u64 s[0:1], 0
	s_cbranch_scc1 .Lix_skip4
	s_mov_b64 s[4:5], exec
	s_mov_b64 exec, s[0:1]
	v_mbcnt_lo_u32_b32 v190, s0, 0
	v_mbcnt_hi_u32_b32 v190, s1, v190
	v_add_u32_e32 v190, s52, v190
	v_lshl_add_u32 v190, v190, 2, s82
	ds_write2st64_b32 v190, v128, v116 offset0:0 offset1:8
	s_mov_b64 exec, s[4:5]
	s_bcnt1_i32_b64 s0, s[0:1]
	s_add_i32 s52, s52, s0
.Lix_skip4:
	v_mfma_f32_16x16x32_bf16 v[144:147], v[4:7], v[64:67], 0
	v_cvt_pk_f16_f32 v198, v148, v149
	v_cvt_pk_f16_f32 v199, v150, v151
	v_mfma_f32_16x16x32_bf16 v[144:147], v[20:23], v[68:71], v[144:147]
	v_pk_max_f16 v198, v198, 0
	v_pk_max_f16 v199, v199, 0
	v_mfma_f32_16x16x32_bf16 v[148:151], v[4:7], v[72:75], 0
	v_cvt_pk_f16_f32 v200, v152, v153
	v_cvt_pk_f16_f32 v201, v154, v155
	v_mfma_f32_16x16x32_bf16 v[148:151], v[20:23], v[76:79], v[148:151]
	v_pk_max_f16 v200, v200, 0
	v_pk_max_f16 v201, v201, 0
	v_mfma_f32_16x16x32_f16 v[100:103], v[32:35], v[196:199], 0
	v_mfma_f32_16x16x32_bf16 v[152:155], v[4:7], v[80:83], 0
	v_cvt_pk_f16_f32 v202, v156, v157
	v_cvt_pk_f16_f32 v203, v158, v159
	v_mfma_f32_16x16x32_bf16 v[152:155], v[20:23], v[84:87], v[152:155]
	v_pk_max_f16 v202, v202, 0
	v_pk_max_f16 v203, v203, 0
	v_mfma_f32_16x16x32_bf16 v[156:159], v[4:7], v[88:91], 0
	v_cvt_pk_f16_f32 v196, v144, v145
	v_cvt_pk_f16_f32 v197, v146, v147
	v_mfma_f32_16x16x32_bf16 v[156:159], v[20:23], v[92:95], v[156:159]
	v_pk_max_f16 v196, v196, 0
	v_pk_max_f16 v197, v197, 0
	v_mfma_f32_16x16x32_f16 v[100:103], v[36:39], v[200:203], v[100:103]
	v_cmp_lt_f32_e64 s[0:1], s59, v132
	s_cmp_eq_u64 s[0:1], 0
	s_cbranch_scc1 .Lix_skip5
	s_mov_b64 s[4:5], exec
	s_mov_b64 exec, s[0:1]
	v_mbcnt_lo_u32_b32 v190, s0, 0
	v_mbcnt_hi_u32_b32 v190, s1, v190
	v_add_u32_e32 v190, s53, v190
	v_lshl_add_u32 v190, v190, 2, s82
	ds_write2st64_b32 v190, v132, v116 offset0:16 offset1:24
	s_mov_b64 exec, s[4:5]
	s_bcnt1_i32_b64 s0, s[0:1]
	s_add_i32 s53, s53, s0
.Lix_skip5:
	v_mfma_f32_16x16x32_bf16 v[144:147], v[8:11], v[64:67], 0
	v_cvt_pk_f16_f32 v198, v148, v149
	v_cvt_pk_f16_f32 v199, v150, v151
	v_mfma_f32_16x16x32_bf16 v[144:147], v[24:27], v[68:71], v[144:147]
	v_pk_max_f16 v198, v198, 0
	v_pk_max_f16 v199, v199, 0
	v_mfma_f32_16x16x32_bf16 v[148:151], v[8:11], v[72:75], 0
	v_cvt_pk_f16_f32 v200, v152, v153
	v_cvt_pk_f16_f32 v201, v154, v155
	v_mfma_f32_16x16x32_bf16 v[148:151], v[24:27], v[76:79], v[148:151]
	v_pk_max_f16 v200, v200, 0
	v_pk_max_f16 v201, v201, 0
	v_mfma_f32_16x16x32_f16 v[104:107], v[40:43], v[196:199], 0
	v_mfma_f32_16x16x32_bf16 v[152:155], v[8:11], v[80:83], 0
	v_cvt_pk_f16_f32 v202, v156, v157
	v_cvt_pk_f16_f32 v203, v158, v159
	v_mfma_f32_16x16x32_bf16 v[152:155], v[24:27], v[84:87], v[152:155]
	v_pk_max_f16 v202, v202, 0
	v_pk_max_f16 v203, v203, 0
	v_mfma_f32_16x16x32_bf16 v[156:159], v[8:11], v[88:91], 0
	v_cvt_pk_f16_f32 v196, v144, v145
	v_cvt_pk_f16_f32 v197, v146, v147
	v_mfma_f32_16x16x32_bf16 v[156:159], v[24:27], v[92:95], v[156:159]
	v_pk_max_f16 v196, v196, 0
	v_pk_max_f16 v197, v197, 0
	v_mfma_f32_16x16x32_f16 v[104:107], v[44:47], v[200:203], v[104:107]
	v_cmp_lt_f32_e64 s[0:1], s60, v136
	s_cmp_eq_u64 s[0:1], 0
	s_cbranch_scc1 .Lix_skip6
	s_mov_b64 s[4:5], exec
	s_mov_b64 exec, s[0:1]
	v_mbcnt_lo_u32_b32 v190, s0, 0
	v_mbcnt_hi_u32_b32 v190, s1, v190
	v_add_u32_e32 v190, s54, v190
	v_lshl_add_u32 v190, v190, 2, s82
	ds_write2st64_b32 v190, v136, v116 offset0:32 offset1:40
	s_mov_b64 exec, s[4:5]
	s_bcnt1_i32_b64 s0, s[0:1]
	s_add_i32 s54, s54, s0
; #define LAS __attribute__((address_space(3)))
; __device__ __forceinline__ float idx_score(const bf16x8 (&f)[8], const bf16x8 a0, const bf16x8 a1, const h4_t (&wa)[4]) {
;     f32x4 s = {0.f, 0.f, 0.f, 0.f}; const h2_t z = {(_Float16)0, (_Float16)0};
; #pragma unroll
;     for (int g = 0; g < 4; ++g) {
;         f32x4 acc = {0.f, 0.f, 0.f, 0.f};
;         acc = __builtin_amdgcn_mfma_f32_16x16x32_bf16(a0, f[2 * g], acc, 0, 0, 0);
;         acc = __builtin_amdgcn_mfma_f32_16x16x32_bf16(a1, f[2 * g + 1], acc, 0, 0, 0);
;         h2_t lo = {(_Float16)acc[0], (_Float16)acc[1]}, hi = {(_Float16)acc[2], (_Float16)acc[3]};
;         lo = __builtin_elementwise_max(lo, z); hi = __builtin_elementwise_max(hi, z);
;         const h4_t bb = {lo[0], lo[1], hi[0], hi[1]};
;         s = __builtin_amdgcn_mfma_f32_16x16x16f16(wa[g], bb, s, 0, 0, 0);
;     }
;     return s[0];
; }
; __device__ __forceinline__ void idx_append(float score, LAS float* bs, LAS unsigned* bi, int& cnt, float& tau, int kb, int t, int lane) {
;     const int kidx = kb * 64 + lane;
;     const bool valid = (kidx <= t) && (score > tau);
;     const unsigned long long vm = __ballot(valid); const int pos = cnt + lane_prefix(vm);
;     if (valid) { bs[pos] = score; bi[pos] = (unsigned)kidx; }
;     cnt += __popcll(vm);
;     __builtin_amdgcn_wave_barrier();
;     if (cnt > ICAP - 64) idx_compact(bs, bi, cnt, tau, lane);
; }
; __device__ __forceinline__ void indexer_unit(const bf16_t* IQ, const bf16_t* IK, const float* IW, unsigned short* SEL, LAS unsigned char* wlds, int t0, int lane) {
;     ...
;     for (int kb = 0; kb < nkb; kb += 2) {
;         idx_load(fb, IK, min(kb + 1, nkb - 1), n16, slab);
;         idx_wait8(fa);
;         { float sc[NQI];
; #pragma unroll
;           for (int q = 0; q < NQI; ++q) sc[q] = idx_score(fa, a0[q], a1[q], wa[q]);
; #pragma unroll
;           for (int q = 0; q < NQI; ++q) idx_append(sc[q], (LAS float*)(wlds + q * 4096), (LAS unsigned*)(wlds + q * 4096 + 2048), cnt[q], tau[q], kb, t0 + q, lane); }
;         idx_load(fa, IK, min(kb + 2, nkb - 1), n16, slab);
;         idx_wait8(fb);
;         if (kb + 1 < nkb) {
;             float sc[NQI];
; #pragma unroll
;             for (int q = 0; q < NQI; ++q) sc[q] = idx_score(fb, a0[q], a1[q], wa[q]);
; #pragma unroll
.Lix_skip6:
	v_mfma_f32_16x16x32_bf16 v[144:147], v[12:15], v[64:67], 0
	v_cvt_pk_f16_f32 v198, v148, v149
	v_cvt_pk_f16_f32 v199, v150, v151
	v_mfma_f32_16x16x32_bf16 v[144:147], v[28:31], v[68:71], v[144:147]
	v_pk_max_f16 v198, v198, 0
	v_pk_max_f16 v199, v199, 0
	v_mfma_f32_16x16x32_bf16 v[148:151], v[12:15], v[72:75], 0
	v_cvt_pk_f16_f32 v200, v152, v153
	v_cvt_pk_f16_f32 v201, v154, v155
	v_mfma_f32_16x16x32_bf16 v[148:151], v[28:31], v[76:79], v[148:151]
	v_pk_max_f16 v200, v200, 0
	v_pk_max_f16 v201, v201, 0
	v_mfma_f32_16x16x32_f16 v[108:111], v[48:51], v[196:199], 0
	v_mfma_f32_16x16x32_bf16 v[152:155], v[12:15], v[80:83], 0
	v_cvt_pk_f16_f32 v202, v156, v157
	v_cvt_pk_f16_f32 v203, v158, v159
	v_mfma_f32_16x16x32_bf16 v[152:155], v[28:31], v[84:87], v[152:155]
	v_pk_max_f16 v202, v202, 0
	v_pk_max_f16 v203, v203, 0
	v_mfma_f32_16x16x32_bf16 v[156:159], v[12:15], v[88:91], 0
	v_cvt_pk_f16_f32 v196, v144, v145
	v_cvt_pk_f16_f32 v197, v146, v147
	v_mfma_f32_16x16x32_bf16 v[156:159], v[28:31], v[92:95], v[156:159]
	v_pk_max_f16 v196, v196, 0
	v_pk_max_f16 v197, v197, 0
	v_mfma_f32_16x16x32_f16 v[108:111], v[52:55], v[200:203], v[108:111]
	v_cmp_lt_f32_e64 s[0:1], s61, v140
	s_cmp_eq_u64 s[0:1], 0
	s_cbranch_scc1 .Lix_skip7
	s_mov_b64 s[4:5], exec
	s_mov_b64 exec, s[0:1]
	v_mbcnt_lo_u32_b32 v190, s0, 0
	v_mbcnt_hi_u32_b32 v190, s1, v190
	v_add_u32_e32 v190, s55, v190
	v_lshl_add_u32 v190, v190, 2, s82
	ds_write2st64_b32 v190, v140, v116 offset0:48 offset1:56
	s_mov_b64 exec, s[4:5]
	s_bcnt1_i32_b64 s0, s[0:1]
	s_add_i32 s55, s55, s0
.Lix_skip7:
	v_cvt_pk_f16_f32 v198, v148, v149
	v_cvt_pk_f16_f32 v199, v150, v151
	v_pk_max_f16 v198, v198, 0
	v_pk_max_f16 v199, v199, 0
	v_cvt_pk_f16_f32 v200, v152, v153
	v_cvt_pk_f16_f32 v201, v154, v155
	v_pk_max_f16 v200, v200, 0
	v_pk_max_f16 v201, v201, 0
	v_mfma_f32_16x16x32_f16 v[112:115], v[56:59], v[196:199], 0
	v_cvt_pk_f16_f32 v202, v156, v157
	v_cvt_pk_f16_f32 v203, v158, v159
	v_pk_max_f16 v202, v202, 0
	v_pk_max_f16 v203, v203, 0
	s_nop 1
	v_mfma_f32_16x16x32_f16 v[112:115], v[60:63], v[200:203], v[112:115]
	v_add_u32_e32 v116, 64, v116
	s_mov_b32 s0, 0
	s_cmpk_gt_i32 s52, 0x1c0
	s_cselect_b32 s1, 1, 0
	s_or_b32 s0, s0, s1
	s_cmpk_gt_i32 s53, 0x1c0
	s_cselect_b32 s1, 2, 0
	s_or_b32 s0, s0, s1
	s_cmpk_gt_i32 s54, 0x1c0
	s_cselect_b32 s1, 4, 0
	s_or_b32 s0, s0, s1
	s_cmpk_gt_i32 s55, 0x1c0
	s_cselect_b32 s1, 8, 0
	s_or_b32 s0, s0, s1
	s_cmp_eq_u32 s0, 0
	s_cbranch_scc1 .Lix_noreq1
	v_mov_b32_e32 v190, s101
	v_mov_b32_e32 v191, s0
	s_mov_b64 s[4:5], exec
	s_mov_b64 exec, 1
	ds_or_b32 v190, v191
	s_mov_b64 exec, s[4:5]
	s_waitcnt lgkmcnt(0)
.Lix_noreq1:
	s_mov_b32 s0, s13
	s_mov_b32 s13, s101
	s_mov_b32 s101, s50
	s_mov_b32 s50, s0
	s_add_i32 s47, s47, 1
	s_cmp_le_i32 s47, s48
	s_cbranch_scc1 .Lix_loop
	s_nop 7
	s_cmpk_lt_i32 s52, 0x1c1
	s_cbranch_scc1 .Lix_eok1_0
	s_add_i32 s79, s82, 0
	s_mov_b32 s80, s52
	s_mov_b32 s56, s28
	s_movk_i32 s19, 288
	s_mov_b32 s78, 8
	s_branch .Lix_compact

; #define LAS __attribute__((address_space(3)))
; __device__ __forceinline__ int lane_prefix(unsigned long long mask) { return __builtin_amdgcn_mbcnt_hi((unsigned)(mask >> 32), __builtin_amdgcn_mbcnt_lo((unsigned)mask, 0)); }
; __device__ __forceinline__ void idx_append(float score, LAS float* bs, LAS unsigned* bi, int& cnt, float& tau, int kb, int t, int lane) {
;     const int kidx = kb * 64 + lane;
;     const bool valid = (kidx <= t) && (score > tau);
;     const unsigned long long vm = __ballot(valid); const int pos = cnt + lane_prefix(vm);
;     if (valid) { bs[pos] = score; bi[pos] = (unsigned)kidx; }
;     cnt += __popcll(vm);
;     __builtin_amdgcn_wave_barrier();
;     if (cnt > ICAP - 64) idx_compact(bs, bi, cnt, tau, lane);
; }
.Lix_eok1_0:
	s_cmpk_lt_i32 s53, 0x1c1
	s_cbranch_scc1 .Lix_eok1_1
	s_add_i32 s79, s82, 4096
	s_mov_b32 s80, s53
	s_mov_b32 s56, s29
	s_movk_i32 s19, 288
	s_mov_b32 s78, 9
	s_branch .Lix_compact

; #define LAS __attribute__((address_space(3)))
; __device__ __forceinline__ int lane_prefix(unsigned long long mask) { return __builtin_amdgcn_mbcnt_hi((unsigned)(mask >> 32), __builtin_amdgcn_mbcnt_lo((unsigned)mask, 0)); }
; __device__ __forceinline__ void idx_append(float score, LAS float* bs, LAS unsigned* bi, int& cnt, float& tau, int kb, int t, int lane) {
;     const int kidx = kb * 64 + lane;
;     const bool valid = (kidx <= t) && (score > tau);
;     const unsigned long long vm = __ballot(valid); const int pos = cnt + lane_prefix(vm);
;     if (valid) { bs[pos] = score; bi[pos] = (unsigned)kidx; }
;     cnt += __popcll(vm);
;     __builtin_amdgcn_wave_barrier();
;     if (cnt > ICAP - 64) idx_compact(bs, bi, cnt, tau, lane);
; }
.Lix_eok1_1:
	s_cmpk_lt_i32 s54, 0x1c1
	s_cbranch_scc1 .Lix_eok1_2
	s_add_i32 s79, s82, 8192
	s_mov_b32 s80, s54
	s_mov_b32 s56, s34
	s_movk_i32 s19, 288
	s_mov_b32 s78, 10
	s_branch .Lix_compact

; #define LAS __attribute__((address_space(3)))
; __device__ __forceinline__ int lane_prefix(unsigned long long mask) { return __builtin_amdgcn_mbcnt_hi((unsigned)(mask >> 32), __builtin_amdgcn_mbcnt_lo((unsigned)mask, 0)); }
; __device__ __forceinline__ void idx_append(float score, LAS float* bs, LAS unsigned* bi, int& cnt, float& tau, int kb, int t, int lane) {
;     const int kidx = kb * 64 + lane;
;     const bool valid = (kidx <= t) && (score > tau);
;     const unsigned long long vm = __ballot(valid); const int pos = cnt + lane_prefix(vm);
;     if (valid) { bs[pos] = score; bi[pos] = (unsigned)kidx; }
;     cnt += __popcll(vm);
;     __builtin_amdgcn_wave_barrier();
;     if (cnt > ICAP - 64) idx_compact(bs, bi, cnt, tau, lane);
; }
.Lix_eok1_2:
	s_cmpk_lt_i32 s55, 0x1c1
	s_cbranch_scc1 .Lix_eok1_3
	s_add_i32 s79, s82, 12288
	s_mov_b32 s80, s55
	s_mov_b32 s56, s35
	s_movk_i32 s19, 288
	s_mov_b32 s78, 11
	s_branch .Lix_compact

; #define LAS __attribute__((address_space(3)))
; __device__ __forceinline__ int lane_prefix(unsigned long long mask) { return __builtin_amdgcn_mbcnt_hi((unsigned)(mask >> 32), __builtin_amdgcn_mbcnt_lo((unsigned)mask, 0)); }
; __device__ __forceinline__ void idx_append(float score, LAS float* bs, LAS unsigned* bi, int& cnt, float& tau, int kb, int t, int lane) {
;     const int kidx = kb * 64 + lane;
;     const bool valid = (kidx <= t) && (score > tau);
;     const unsigned long long vm = __ballot(valid); const int pos = cnt + lane_prefix(vm);
;     if (valid) { bs[pos] = score; bi[pos] = (unsigned)kidx; }
;     cnt += __popcll(vm);
;     __builtin_amdgcn_wave_barrier();
;     if (cnt > ICAP - 64) idx_compact(bs, bi, cnt, tau, lane);
; }
.Lix_eok1_3:
	s_add_i32 s4, s46, 0
	v_cmp_ge_i32_e32 vcc, s4, v116
	s_nop 1
	v_cndmask_b32_e32 v100, v208, v100, vcc
	s_add_i32 s4, s46, 1
	v_cmp_ge_i32_e32 vcc, s4, v116
	s_nop 1
	v_cndmask_b32_e32 v104, v208, v104, vcc
	s_add_i32 s4, s46, 2
	v_cmp_ge_i32_e32 vcc, s4, v116
	s_nop 1
	v_cndmask_b32_e32 v108, v208, v108, vcc
	s_add_i32 s4, s46, 3
	v_cmp_ge_i32_e32 vcc, s4, v116
	s_nop 1
	v_cndmask_b32_e32 v112, v208, v112, vcc
	v_cmp_lt_f32_e64 s[0:1], s58, v100
	s_cmp_eq_u64 s[0:1], 0
	s_cbranch_scc1 .Lix_skip8
	s_mov_b64 s[4:5], exec
	s_mov_b64 exec, s[0:1]
	v_mbcnt_lo_u32_b32 v190, s0, 0
	v_mbcnt_hi_u32_b32 v190, s1, v190
	v_add_u32_e32 v190, s52, v190
	v_lshl_add_u32 v190, v190, 2, s82
	ds_write2st64_b32 v190, v100, v116 offset0:0 offset1:8
	s_mov_b64 exec, s[4:5]
	s_bcnt1_i32_b64 s0, s[0:1]
	s_add_i32 s52, s52, s0
.Lix_skip8:
	v_cmp_lt_f32_e64 s[0:1], s59, v104
	s_cmp_eq_u64 s[0:1], 0
	s_cbranch_scc1 .Lix_skip9
	s_mov_b64 s[4:5], exec
	s_mov_b64 exec, s[0:1]
	v_mbcnt_lo_u32_b32 v190, s0, 0
	v_mbcnt_hi_u32_b32 v190, s1, v190
	v_add_u32_e32 v190, s53, v190
	v_lshl_add_u32 v190, v190, 2, s82
	ds_write2st64_b32 v190, v104, v116 offset0:16 offset1:24
	s_mov_b64 exec, s[4:5]
	s_bcnt1_i32_b64 s0, s[0:1]
	s_add_i32 s53, s53, s0
.Lix_skip9:
	v_cmp_lt_f32_e64 s[0:1], s60, v108
	s_cmp_eq_u64 s[0:1], 0
	s_cbranch_scc1 .Lix_skip10
	s_mov_b64 s[4:5], exec
	s_mov_b64 exec, s[0:1]
	v_mbcnt_lo_u32_b32 v190, s0, 0
	v_mbcnt_hi_u32_b32 v190, s1, v190
	v_add_u32_e32 v190, s54, v190
	v_lshl_add_u32 v190, v190, 2, s82
	ds_write2st64_b32 v190, v108, v116 offset0:32 offset1:40
	s_mov_b64 exec, s[4:5]
	s_bcnt1_i32_b64 s0, s[0:1]
	s_add_i32 s54, s54, s0
.Lix_skip10:
	v_cmp_lt_f32_e64 s[0:1], s61, v112
	s_cmp_eq_u64 s[0:1], 0
	s_cbranch_scc1 .Lix_skip11
	s_mov_b64 s[4:5], exec
	s_mov_b64 exec, s[0:1]
	v_mbcnt_lo_u32_b32 v190, s0, 0
	v_mbcnt_hi_u32_b32 v190, s1, v190
	v_add_u32_e32 v190, s55, v190
	v_lshl_add_u32 v190, v190, 2, s82
	ds_write2st64_b32 v190, v112, v116 offset0:48 offset1:56
	s_mov_b64 exec, s[4:5]
	s_bcnt1_i32_b64 s0, s[0:1]
	s_add_i32 s55, s55, s0

; #define LAS __attribute__((address_space(3)))
; __device__ __forceinline__ int lane_prefix(unsigned long long mask) { return __builtin_amdgcn_mbcnt_hi((unsigned)(mask >> 32), __builtin_amdgcn_mbcnt_lo((unsigned)mask, 0)); }
; __device__ __forceinline__ void idx_append(float score, LAS float* bs, LAS unsigned* bi, int& cnt, float& tau, int kb, int t, int lane) {
;     const int kidx = kb * 64 + lane;
;     const bool valid = (kidx <= t) && (score > tau);
;     const unsigned long long vm = __ballot(valid); const int pos = cnt + lane_prefix(vm);
;     if (valid) { bs[pos] = score; bi[pos] = (unsigned)kidx; }
;     cnt += __popcll(vm);
;     __builtin_amdgcn_wave_barrier();
;     if (cnt > ICAP - 64) idx_compact(bs, bi, cnt, tau, lane);
; }
.Lix_epi0:
	s_nop 7
	s_cmpk_lt_i32 s52, 0x1c1
	s_cbranch_scc1 .Lix_eok0_0
	s_add_i32 s79, s82, 0
	s_mov_b32 s80, s52
	s_mov_b32 s56, s28
	s_movk_i32 s19, 288
	s_mov_b32 s78, 12
	s_branch .Lix_compact

; #define LAS __attribute__((address_space(3)))
; __device__ __forceinline__ int lane_prefix(unsigned long long mask) { return __builtin_amdgcn_mbcnt_hi((unsigned)(mask >> 32), __builtin_amdgcn_mbcnt_lo((unsigned)mask, 0)); }
; __device__ __forceinline__ void idx_append(float score, LAS float* bs, LAS unsigned* bi, int& cnt, float& tau, int kb, int t, int lane) {
;     const int kidx = kb * 64 + lane;
;     const bool valid = (kidx <= t) && (score > tau);
;     const unsigned long long vm = __ballot(valid); const int pos = cnt + lane_prefix(vm);
;     if (valid) { bs[pos] = score; bi[pos] = (unsigned)kidx; }
;     cnt += __popcll(vm);
;     __builtin_amdgcn_wave_barrier();
;     if (cnt > ICAP - 64) idx_compact(bs, bi, cnt, tau, lane);
; }
.Lix_eok0_0:
	s_cmpk_lt_i32 s53, 0x1c1
	s_cbranch_scc1 .Lix_eok0_1
	s_add_i32 s79, s82, 4096
	s_mov_b32 s80, s53
	s_mov_b32 s56, s29
	s_movk_i32 s19, 288
	s_mov_b32 s78, 13
	s_branch .Lix_compact

; #define LAS __attribute__((address_space(3)))
; __device__ __forceinline__ int lane_prefix(unsigned long long mask) { return __builtin_amdgcn_mbcnt_hi((unsigned)(mask >> 32), __builtin_amdgcn_mbcnt_lo((unsigned)mask, 0)); }
; __device__ __forceinline__ void idx_append(float score, LAS float* bs, LAS unsigned* bi, int& cnt, float& tau, int kb, int t, int lane) {
;     const int kidx = kb * 64 + lane;
;     const bool valid = (kidx <= t) && (score > tau);
;     const unsigned long long vm = __ballot(valid); const int pos = cnt + lane_prefix(vm);
;     if (valid) { bs[pos] = score; bi[pos] = (unsigned)kidx; }
;     cnt += __popcll(vm);
;     __builtin_amdgcn_wave_barrier();
;     if (cnt > ICAP - 64) idx_compact(bs, bi, cnt, tau, lane);
; }
.Lix_eok0_1:
	s_cmpk_lt_i32 s54, 0x1c1
	s_cbranch_scc1 .Lix_eok0_2
	s_add_i32 s79, s82, 8192
	s_mov_b32 s80, s54
	s_mov_b32 s56, s34
	s_movk_i32 s19, 288
	s_mov_b32 s78, 14
	s_branch .Lix_compact

; #define LAS __attribute__((address_space(3)))
; __device__ __forceinline__ int lane_prefix(unsigned long long mask) { return __builtin_amdgcn_mbcnt_hi((unsigned)(mask >> 32), __builtin_amdgcn_mbcnt_lo((unsigned)mask, 0)); }
; __device__ __forceinline__ void idx_append(float score, LAS float* bs, LAS unsigned* bi, int& cnt, float& tau, int kb, int t, int lane) {
;     const int kidx = kb * 64 + lane;
;     const bool valid = (kidx <= t) && (score > tau);
;     const unsigned long long vm = __ballot(valid); const int pos = cnt + lane_prefix(vm);
;     if (valid) { bs[pos] = score; bi[pos] = (unsigned)kidx; }
;     cnt += __popcll(vm);
;     __builtin_amdgcn_wave_barrier();
;     if (cnt > ICAP - 64) idx_compact(bs, bi, cnt, tau, lane);
; }
.Lix_eok0_2:
	s_cmpk_lt_i32 s55, 0x1c1
	s_cbranch_scc1 .Lix_eok0_3
	s_add_i32 s79, s82, 12288
	s_mov_b32 s80, s55
	s_mov_b32 s56, s35
	s_movk_i32 s19, 288
	s_mov_b32 s78, 15
	s_branch .Lix_compact

; #define LAS __attribute__((address_space(3)))
; __device__ __forceinline__ int lane_prefix(unsigned long long mask) { return __builtin_amdgcn_mbcnt_hi((unsigned)(mask >> 32), __builtin_amdgcn_mbcnt_lo((unsigned)mask, 0)); }
; __device__ __forceinline__ void idx_append(float score, LAS float* bs, LAS unsigned* bi, int& cnt, float& tau, int kb, int t, int lane) {
;     const int kidx = kb * 64 + lane;
;     const bool valid = (kidx <= t) && (score > tau);
;     const unsigned long long vm = __ballot(valid); const int pos = cnt + lane_prefix(vm);
;     if (valid) { bs[pos] = score; bi[pos] = (unsigned)kidx; }
;     cnt += __popcll(vm);
;     __builtin_amdgcn_wave_barrier();
;     if (cnt > ICAP - 64) idx_compact(bs, bi, cnt, tau, lane);
; }
; __device__ __forceinline__ void indexer_unit(const bf16_t* IQ, const bf16_t* IK, const float* IW, unsigned short* SEL, LAS unsigned char* wlds, int t0, int lane) {
;     ...
;     idx_wait0(fa, fb);
; #pragma unroll
;     for (int q = 0; q < NQI; ++q) {
;         LAS float* bs = (LAS float*)(wlds + q * 4096); LAS unsigned* bi = (LAS unsigned*)(wlds + q * 4096 + 2048);
;         if (cnt[q] > 256) idx_compact(bs, bi, cnt[q], tau[q], lane);
;         __builtin_amdgcn_wave_barrier();
;         unsigned short* sel = SEL + (size_t)(t0 + q) * 256;
.Lix_eok0_3:
	s_add_i32 s4, s46, 0
	v_cmp_ge_i32_e32 vcc, s4, v116
	s_nop 1
	v_cndmask_b32_e32 v128, v208, v128, vcc
	s_add_i32 s4, s46, 1
	v_cmp_ge_i32_e32 vcc, s4, v116
	s_nop 1
	v_cndmask_b32_e32 v132, v208, v132, vcc
	s_add_i32 s4, s46, 2
	v_cmp_ge_i32_e32 vcc, s4, v116
	s_nop 1
	v_cndmask_b32_e32 v136, v208, v136, vcc
	s_add_i32 s4, s46, 3
	v_cmp_ge_i32_e32 vcc, s4, v116
	s_nop 1
	v_cndmask_b32_e32 v140, v208, v140, vcc
	v_cmp_lt_f32_e64 s[0:1], s58, v128
	s_cmp_eq_u64 s[0:1], 0
	s_cbranch_scc1 .Lix_skip12
	s_mov_b64 s[4:5], exec
	s_mov_b64 exec, s[0:1]
	v_mbcnt_lo_u32_b32 v190, s0, 0
	v_mbcnt_hi_u32_b32 v190, s1, v190
	v_add_u32_e32 v190, s52, v190
	v_lshl_add_u32 v190, v190, 2, s82
	ds_write2st64_b32 v190, v128, v116 offset0:0 offset1:8
	s_mov_b64 exec, s[4:5]
	s_bcnt1_i32_b64 s0, s[0:1]
	s_add_i32 s52, s52, s0
.Lix_skip12:
	v_cmp_lt_f32_e64 s[0:1], s59, v132
	s_cmp_eq_u64 s[0:1], 0
	s_cbranch_scc1 .Lix_skip13
	s_mov_b64 s[4:5], exec
	s_mov_b64 exec, s[0:1]
	v_mbcnt_lo_u32_b32 v190, s0, 0
	v_mbcnt_hi_u32_b32 v190, s1, v190
	v_add_u32_e32 v190, s53, v190
	v_lshl_add_u32 v190, v190, 2, s82
	ds_write2st64_b32 v190, v132, v116 offset0:16 offset1:24
	s_mov_b64 exec, s[4:5]
	s_bcnt1_i32_b64 s0, s[0:1]
	s_add_i32 s53, s53, s0
.Lix_skip13:
	v_cmp_lt_f32_e64 s[0:1], s60, v136
	s_cmp_eq_u64 s[0:1], 0
	s_cbranch_scc1 .Lix_skip14
	s_mov_b64 s[4:5], exec
	s_mov_b64 exec, s[0:1]
	v_mbcnt_lo_u32_b32 v190, s0, 0
	v_mbcnt_hi_u32_b32 v190, s1, v190
	v_add_u32_e32 v190, s54, v190
	v_lshl_add_u32 v190, v190, 2, s82
	ds_write2st64_b32 v190, v136, v116 offset0:32 offset1:40
	s_mov_b64 exec, s[4:5]
	s_bcnt1_i32_b64 s0, s[0:1]
	s_add_i32 s54, s54, s0
.Lix_skip14:
	v_cmp_lt_f32_e64 s[0:1], s61, v140
	s_cmp_eq_u64 s[0:1], 0
	s_cbranch_scc1 .Lix_skip15
	s_mov_b64 s[4:5], exec
	s_mov_b64 exec, s[0:1]
	v_mbcnt_lo_u32_b32 v190, s0, 0
	v_mbcnt_hi_u32_b32 v190, s1, v190
	v_add_u32_e32 v190, s55, v190
	v_lshl_add_u32 v190, v190, 2, s82
	ds_write2st64_b32 v190, v140, v116 offset0:48 offset1:56
	s_mov_b64 exec, s[4:5]
	s_bcnt1_i32_b64 s0, s[0:1]
	s_add_i32 s55, s55, s0
.Lix_skip15:
.Lix_done:
	s_cmpk_lt_i32 s52, 0x101
	s_cbranch_scc1 .Lix_fin0
	s_add_i32 s79, s82, 0
	s_mov_b32 s80, s52
	s_mov_b32 s56, s28
	s_movk_i32 s19, 256
	s_mov_b32 s78, 16
	s_branch .Lix_compact

; #define LAS __attribute__((address_space(3)))
; __device__ __forceinline__ void indexer_unit(const bf16_t* IQ, const bf16_t* IK, const float* IW, unsigned short* SEL, LAS unsigned char* wlds, int t0, int lane) {
;     ...
; #pragma unroll
;     for (int q = 0; q < NQI; ++q) {
;         LAS float* bs = (LAS float*)(wlds + q * 4096); LAS unsigned* bi = (LAS unsigned*)(wlds + q * 4096 + 2048);
;         if (cnt[q] > 256) idx_compact(bs, bi, cnt[q], tau[q], lane);
;         __builtin_amdgcn_wave_barrier();
;         unsigned short* sel = SEL + (size_t)(t0 + q) * 256;
; #pragma unroll
;         for (int j = 0; j < 4; ++j) { const int e = j * 64 + lane; if (e < cnt[q]) sel[e] = (unsigned short)bi[e]; }
;     }
.Lix_fin0:
	s_add_i32 s0, s46, 0
	s_lshl_b32 s0, s0, 9
	s_add_u32 s0, s44, s0
	s_addc_u32 s1, s45, 0
	ds_read2st64_b32 v[190:191], v187 offset0:8 offset1:9
	ds_read2st64_b32 v[192:193], v187 offset0:10 offset1:11
	s_mov_b64 s[4:5], exec
	s_waitcnt lgkmcnt(0)
	s_sub_i32 s19, s52, 0
	v_cmp_gt_i32_e32 vcc, s19, v182
	s_nop 1
	s_and_b64 exec, s[4:5], vcc
	global_store_short v189, v190, s[0:1]
	s_sub_i32 s19, s52, 64
	v_cmp_gt_i32_e32 vcc, s19, v182
	s_nop 1
	s_and_b64 exec, s[4:5], vcc
	global_store_short v189, v191, s[0:1] offset:128
	s_sub_i32 s19, s52, 128
	v_cmp_gt_i32_e32 vcc, s19, v182
	s_nop 1
	s_and_b64 exec, s[4:5], vcc
	global_store_short v189, v192, s[0:1] offset:256
	s_sub_i32 s19, s52, 192
	v_cmp_gt_i32_e32 vcc, s19, v182
	s_nop 1
	s_and_b64 exec, s[4:5], vcc
	global_store_short v189, v193, s[0:1] offset:384
	s_mov_b64 exec, s[4:5]
	s_cmpk_lt_i32 s53, 0x101
	s_cbranch_scc1 .Lix_fin1
	s_add_i32 s79, s82, 4096
	s_mov_b32 s80, s53
	s_mov_b32 s56, s29
	s_movk_i32 s19, 256
	s_mov_b32 s78, 17
	s_branch .Lix_compact

; #define LAS __attribute__((address_space(3)))
; __device__ __forceinline__ void indexer_unit(const bf16_t* IQ, const bf16_t* IK, const float* IW, unsigned short* SEL, LAS unsigned char* wlds, int t0, int lane) {
;     ...
; #pragma unroll
;     for (int q = 0; q < NQI; ++q) {
;         LAS float* bs = (LAS float*)(wlds + q * 4096); LAS unsigned* bi = (LAS unsigned*)(wlds + q * 4096 + 2048);
;         if (cnt[q] > 256) idx_compact(bs, bi, cnt[q], tau[q], lane);
;         __builtin_amdgcn_wave_barrier();
;         unsigned short* sel = SEL + (size_t)(t0 + q) * 256;
; #pragma unroll
;         for (int j = 0; j < 4; ++j) { const int e = j * 64 + lane; if (e < cnt[q]) sel[e] = (unsigned short)bi[e]; }
;     }
.Lix_fin1:
	s_add_i32 s0, s46, 1
	s_lshl_b32 s0, s0, 9
	s_add_u32 s0, s44, s0
	s_addc_u32 s1, s45, 0
	ds_read2st64_b32 v[190:191], v187 offset0:24 offset1:25
	ds_read2st64_b32 v[192:193], v187 offset0:26 offset1:27
	s_mov_b64 s[4:5], exec
	s_waitcnt lgkmcnt(0)
	s_sub_i32 s19, s53, 0
	v_cmp_gt_i32_e32 vcc, s19, v182
	s_nop 1
	s_and_b64 exec, s[4:5], vcc
	global_store_short v189, v190, s[0:1]
	s_sub_i32 s19, s53, 64
	v_cmp_gt_i32_e32 vcc, s19, v182
	s_nop 1
	s_and_b64 exec, s[4:5], vcc
	global_store_short v189, v191, s[0:1] offset:128
	s_sub_i32 s19, s53, 128
	v_cmp_gt_i32_e32 vcc, s19, v182
	s_nop 1
	s_and_b64 exec, s[4:5], vcc
	global_store_short v189, v192, s[0:1] offset:256
	s_sub_i32 s19, s53, 192
	v_cmp_gt_i32_e32 vcc, s19, v182
	s_nop 1
	s_and_b64 exec, s[4:5], vcc
	global_store_short v189, v193, s[0:1] offset:384
	s_mov_b64 exec, s[4:5]
	s_cmpk_lt_i32 s54, 0x101
	s_cbranch_scc1 .Lix_fin2
	s_add_i32 s79, s82, 8192
	s_mov_b32 s80, s54
	s_mov_b32 s56, s34
	s_movk_i32 s19, 256
	s_mov_b32 s78, 18
	s_branch .Lix_compact

; #define LAS __attribute__((address_space(3)))
; __device__ __forceinline__ void indexer_unit(const bf16_t* IQ, const bf16_t* IK, const float* IW, unsigned short* SEL, LAS unsigned char* wlds, int t0, int lane) {
;     ...
; #pragma unroll
;     for (int q = 0; q < NQI; ++q) {
;         LAS float* bs = (LAS float*)(wlds + q * 4096); LAS unsigned* bi = (LAS unsigned*)(wlds + q * 4096 + 2048);
;         if (cnt[q] > 256) idx_compact(bs, bi, cnt[q], tau[q], lane);
;         __builtin_amdgcn_wave_barrier();
;         unsigned short* sel = SEL + (size_t)(t0 + q) * 256;
; #pragma unroll
;         for (int j = 0; j < 4; ++j) { const int e = j * 64 + lane; if (e < cnt[q]) sel[e] = (unsigned short)bi[e]; }
;     }
.Lix_fin2:
	s_add_i32 s0, s46, 2
	s_lshl_b32 s0, s0, 9
	s_add_u32 s0, s44, s0
	s_addc_u32 s1, s45, 0
	ds_read2st64_b32 v[190:191], v187 offset0:40 offset1:41
	ds_read2st64_b32 v[192:193], v187 offset0:42 offset1:43
	s_mov_b64 s[4:5], exec
	s_waitcnt lgkmcnt(0)
	s_sub_i32 s19, s54, 0
	v_cmp_gt_i32_e32 vcc, s19, v182
	s_nop 1
	s_and_b64 exec, s[4:5], vcc
	global_store_short v189, v190, s[0:1]
	s_sub_i32 s19, s54, 64
	v_cmp_gt_i32_e32 vcc, s19, v182
	s_nop 1
	s_and_b64 exec, s[4:5], vcc
	global_store_short v189, v191, s[0:1] offset:128
	s_sub_i32 s19, s54, 128
	v_cmp_gt_i32_e32 vcc, s19, v182
	s_nop 1
	s_and_b64 exec, s[4:5], vcc
	global_store_short v189, v192, s[0:1] offset:256
	s_sub_i32 s19, s54, 192
	v_cmp_gt_i32_e32 vcc, s19, v182
	s_nop 1
	s_and_b64 exec, s[4:5], vcc
	global_store_short v189, v193, s[0:1] offset:384
	s_mov_b64 exec, s[4:5]
	s_cmpk_lt_i32 s55, 0x101
	s_cbranch_scc1 .Lix_fin3
	s_add_i32 s79, s82, 12288
	s_mov_b32 s80, s55
	s_mov_b32 s56, s35
	s_movk_i32 s19, 256
	s_mov_b32 s78, 19
	s_branch .Lix_compact

; __device__ __forceinline__ int lane_prefix(unsigned long long mask) { return __builtin_amdgcn_mbcnt_hi((unsigned)(mask >> 32), __builtin_amdgcn_mbcnt_lo((unsigned)mask, 0)); }
; __device__ __forceinline__ void idx_compact(LAS float* bs, LAS unsigned* bi, int& cnt, float& tau, int lane) {
;     ...
;     int base = 0, eqbase = 0;
;     __builtin_amdgcn_wave_barrier();
; #pragma unroll
;     for (int i = 0; i < ICAP / 64; ++i) {
;         const bool gt = u[i] > T, eq = u[i] == T;
;         const unsigned long long em = __ballot(eq); const int eqpos = eqbase + lane_prefix(em); eqbase += __popcll(em);
;         const bool keep = gt || (eq && eqpos < need_eq);
;         const unsigned long long km = __ballot(keep); const int pos = base + lane_prefix(km); base += __popcll(km);
;         if (keep) { bs[pos] = sort2f(u[i]); bi[pos] = id[i]; }
;     }
;     __builtin_amdgcn_wave_barrier();
;     cnt = 256; tau = sort2f(T);
; }
.Lix_cs_done:
	v_cmp_lt_u32_e64 s[64:65], s56, v194
	v_cmp_lt_u32_e64 s[30:31], s56, v195
	v_cmp_lt_u32_e64 s[36:37], s56, v196
	v_cmp_lt_u32_e64 s[62:63], s56, v197
	v_cmp_lt_u32_e64 s[68:69], s56, v198
	v_cmp_lt_u32_e64 s[70:71], s56, v199
	v_cmp_lt_u32_e64 s[72:73], s56, v200
	v_cmp_lt_u32_e64 s[74:75], s56, v201
	s_bcnt1_i32_b64 s0, s[64:65]
	s_bcnt1_i32_b64 s1, s[30:31]
	s_add_i32 s0, s0, s1
	s_bcnt1_i32_b64 s1, s[36:37]
	s_add_i32 s0, s0, s1
	s_bcnt1_i32_b64 s1, s[62:63]
	s_add_i32 s0, s0, s1
	s_bcnt1_i32_b64 s1, s[68:69]
	s_add_i32 s0, s0, s1
	s_bcnt1_i32_b64 s1, s[70:71]
	s_add_i32 s0, s0, s1
	s_bcnt1_i32_b64 s1, s[72:73]
	s_add_i32 s0, s0, s1
	s_bcnt1_i32_b64 s1, s[74:75]
	s_add_i32 s0, s0, s1
	s_cmp_le_u32 s100, s19
	s_cselect_b32 s80, s100, 0x100
	s_sub_i32 s19, s80, s0
	s_mov_b32 s98, 0
	s_mov_b32 s99, 0
	s_mov_b64 s[4:5], exec
	v_cmp_eq_u32_e64 s[0:1], s56, v194
	s_nop 1
	v_mbcnt_lo_u32_b32 v190, s0, 0
	v_mbcnt_hi_u32_b32 v190, s1, v190
	v_add_u32_e32 v190, s98, v190
	v_cmp_gt_i32_e32 vcc, s19, v190
	s_bcnt1_i32_b64 s83, s[0:1]
	s_add_i32 s98, s98, s83
	s_and_b64 s[0:1], s[0:1], vcc
	s_or_b64 s[0:1], s[0:1], s[64:65]
	v_mbcnt_lo_u32_b32 v191, s0, 0
	v_mbcnt_hi_u32_b32 v191, s1, v191
	v_add_u32_e32 v191, s99, v191
	v_lshl_add_u32 v191, v191, 2, s79
	s_mov_b64 exec, s[0:1]
	ds_write2st64_b32 v191, v240, v214 offset1:8
	s_mov_b64 exec, s[4:5]
	s_bcnt1_i32_b64 s83, s[0:1]
	s_add_i32 s99, s99, s83
	v_cmp_eq_u32_e64 s[0:1], s56, v195
	s_nop 1
	v_mbcnt_lo_u32_b32 v190, s0, 0
	v_mbcnt_hi_u32_b32 v190, s1, v190
	v_add_u32_e32 v190, s98, v190
	v_cmp_gt_i32_e32 vcc, s19, v190
	s_bcnt1_i32_b64 s83, s[0:1]
	s_add_i32 s98, s98, s83
	s_and_b64 s[0:1], s[0:1], vcc
	s_or_b64 s[0:1], s[0:1], s[30:31]
	v_mbcnt_lo_u32_b32 v191, s0, 0
	v_mbcnt_hi_u32_b32 v191, s1, v191
	v_add_u32_e32 v191, s99, v191
	v_lshl_add_u32 v191, v191, 2, s79
	s_mov_b64 exec, s[0:1]
	ds_write2st64_b32 v191, v241, v215 offset1:8
	s_mov_b64 exec, s[4:5]
	s_bcnt1_i32_b64 s83, s[0:1]
	s_add_i32 s99, s99, s83
	v_cmp_eq_u32_e64 s[0:1], s56, v196
	s_nop 1
	v_mbcnt_lo_u32_b32 v190, s0, 0
	v_mbcnt_hi_u32_b32 v190, s1, v190
	v_add_u32_e32 v190, s98, v190
	v_cmp_gt_i32_e32 vcc, s19, v190
	s_bcnt1_i32_b64 s83, s[0:1]
	s_add_i32 s98, s98, s83
	s_and_b64 s[0:1], s[0:1], vcc
	s_or_b64 s[0:1], s[0:1], s[36:37]
	v_mbcnt_lo_u32_b32 v191, s0, 0
	v_mbcnt_hi_u32_b32 v191, s1, v191
	v_add_u32_e32 v191, s99, v191
	v_lshl_add_u32 v191, v191, 2, s79
	s_mov_b64 exec, s[0:1]
	ds_write2st64_b32 v191, v242, v216 offset1:8
	s_mov_b64 exec, s[4:5]
	s_bcnt1_i32_b64 s83, s[0:1]
	s_add_i32 s99, s99, s83
	v_cmp_eq_u32_e64 s[0:1], s56, v197
	s_nop 1
	v_mbcnt_lo_u32_b32 v190, s0, 0
	v_mbcnt_hi_u32_b32 v190, s1, v190
	v_add_u32_e32 v190, s98, v190
	v_cmp_gt_i32_e32 vcc, s19, v190
	s_bcnt1_i32_b64 s83, s[0:1]
	s_add_i32 s98, s98, s83
	s_and_b64 s[0:1], s[0:1], vcc
	s_or_b64 s[0:1], s[0:1], s[62:63]
	v_mbcnt_lo_u32_b32 v191, s0, 0
	v_mbcnt_hi_u32_b32 v191, s1, v191
	v_add_u32_e32 v191, s99, v191
	v_lshl_add_u32 v191, v191, 2, s79
	s_mov_b64 exec, s[0:1]
	ds_write2st64_b32 v191, v243, v217 offset1:8
	s_mov_b64 exec, s[4:5]
	s_bcnt1_i32_b64 s83, s[0:1]
	s_add_i32 s99, s99, s83
	v_cmp_eq_u32_e64 s[0:1], s56, v198
	s_nop 1
	v_mbcnt_lo_u32_b32 v190, s0, 0
	v_mbcnt_hi_u32_b32 v190, s1, v190
	v_add_u32_e32 v190, s98, v190
	v_cmp_gt_i32_e32 vcc, s19, v190
	s_bcnt1_i32_b64 s83, s[0:1]
	s_add_i32 s98, s98, s83
	s_and_b64 s[0:1], s[0:1], vcc
	s_or_b64 s[0:1], s[0:1], s[68:69]
	v_mbcnt_lo_u32_b32 v191, s0, 0
	v_mbcnt_hi_u32_b32 v191, s1, v191
	v_add_u32_e32 v191, s99, v191
	v_lshl_add_u32 v191, v191, 2, s79
	s_mov_b64 exec, s[0:1]
	ds_write2st64_b32 v191, v244, v218 offset1:8
	s_mov_b64 exec, s[4:5]
	s_bcnt1_i32_b64 s83, s[0:1]
	s_add_i32 s99, s99, s83
	v_cmp_eq_u32_e64 s[0:1], s56, v199
	s_nop 1
	v_mbcnt_lo_u32_b32 v190, s0, 0
	v_mbcnt_hi_u32_b32 v190, s1, v190
	v_add_u32_e32 v190, s98, v190
	v_cmp_gt_i32_e32 vcc, s19, v190
	s_bcnt1_i32_b64 s83, s[0:1]
	s_add_i32 s98, s98, s83
	s_and_b64 s[0:1], s[0:1], vcc
	s_or_b64 s[0:1], s[0:1], s[70:71]
	v_mbcnt_lo_u32_b32 v191, s0, 0
	v_mbcnt_hi_u32_b32 v191, s1, v191
	v_add_u32_e32 v191, s99, v191
	v_lshl_add_u32 v191, v191, 2, s79
	s_mov_b64 exec, s[0:1]
	ds_write2st64_b32 v191, v245, v219 offset1:8
	s_mov_b64 exec, s[4:5]
	s_bcnt1_i32_b64 s83, s[0:1]
	s_add_i32 s99, s99, s83
	v_cmp_eq_u32_e64 s[0:1], s56, v200
	s_nop 1
	v_mbcnt_lo_u32_b32 v190, s0, 0
	v_mbcnt_hi_u32_b32 v190, s1, v190
	v_add_u32_e32 v190, s98, v190
	v_cmp_gt_i32_e32 vcc, s19, v190
	s_bcnt1_i32_b64 s83, s[0:1]
	s_add_i32 s98, s98, s83
	s_and_b64 s[0:1], s[0:1], vcc
	s_or_b64 s[0:1], s[0:1], s[72:73]
	v_mbcnt_lo_u32_b32 v191, s0, 0
	v_mbcnt_hi_u32_b32 v191, s1, v191
	v_add_u32_e32 v191, s99, v191
	v_lshl_add_u32 v191, v191, 2, s79
	s_mov_b64 exec, s[0:1]
	ds_write2st64_b32 v191, v246, v220 offset1:8
	s_mov_b64 exec, s[4:5]
	s_bcnt1_i32_b64 s83, s[0:1]
	s_add_i32 s99, s99, s83
	v_cmp_eq_u32_e64 s[0:1], s56, v201
	s_nop 1
	v_mbcnt_lo_u32_b32 v190, s0, 0
	v_mbcnt_hi_u32_b32 v190, s1, v190
	v_add_u32_e32 v190, s98, v190
	v_cmp_gt_i32_e32 vcc, s19, v190
	s_bcnt1_i32_b64 s83, s[0:1]
	s_add_i32 s98, s98, s83
	s_and_b64 s[0:1], s[0:1], vcc
	s_or_b64 s[0:1], s[0:1], s[74:75]
	v_mbcnt_lo_u32_b32 v191, s0, 0
	v_mbcnt_hi_u32_b32 v191, s1, v191
	v_add_u32_e32 v191, s99, v191
	v_lshl_add_u32 v191, v191, 2, s79
	s_mov_b64 exec, s[0:1]
	ds_write2st64_b32 v191, v247, v221 offset1:8
	s_mov_b64 exec, s[4:5]
	s_bcnt1_i32_b64 s83, s[0:1]
	s_add_i32 s99, s99, s83
	s_ashr_i32 s0, s56, 31
	s_not_b32 s0, s0
	s_or_b32 s0, s0, 0x80000000
	s_xor_b32 s81, s56, s0
	s_cmp_eq_u32 s78, 0
	s_cbranch_scc1 .Lix_ret0
	s_cmp_eq_u32 s78, 1
	s_cbranch_scc1 .Lix_ret1
	s_cmp_eq_u32 s78, 2
	s_cbranch_scc1 .Lix_ret2
	s_cmp_eq_u32 s78, 3
	s_cbranch_scc1 .Lix_ret3
	s_cmp_eq_u32 s78, 4
	s_cbranch_scc1 .Lix_ret4
	s_cmp_eq_u32 s78, 5
	s_cbranch_scc1 .Lix_ret5
	s_cmp_eq_u32 s78, 6
	s_cbranch_scc1 .Lix_ret6
	s_cmp_eq_u32 s78, 7
	s_cbranch_scc1 .Lix_ret7
	s_cmp_eq_u32 s78, 8
	s_cbranch_scc1 .Lix_ret8
	s_cmp_eq_u32 s78, 9
	s_cbranch_scc1 .Lix_ret9
	s_cmp_eq_u32 s78, 10
	s_cbranch_scc1 .Lix_ret10
	s_cmp_eq_u32 s78, 11
	s_cbranch_scc1 .Lix_ret11
	s_cmp_eq_u32 s78, 12
	s_cbranch_scc1 .Lix_ret12
	s_cmp_eq_u32 s78, 13
	s_cbranch_scc1 .Lix_ret13
	s_cmp_eq_u32 s78, 14
	s_cbranch_scc1 .Lix_ret14
	s_cmp_eq_u32 s78, 15
	s_cbranch_scc1 .Lix_ret15
	s_cmp_eq_u32 s78, 16
	s_cbranch_scc1 .Lix_ret16
	s_cmp_eq_u32 s78, 17
	s_cbranch_scc1 .Lix_ret17
	s_cmp_eq_u32 s78, 18
	s_cbranch_scc1 .Lix_ret18
	s_cmp_eq_u32 s78, 19
	s_cbranch_scc1 .Lix_ret19
	s_endpgm
